# same K-loop reordering applied to all eight GEMM instances
# baseline (speedup 1.0000x reference)
.LBB0_147:
	s_and_b32 s13, s12, 0x18000
	v_add_u32_e32 v222, s13, v180
	s_add_i32 s13, s12, 0xfffe8000
	s_and_b32 s13, s13, 0x18000
	v_or_b32_e32 v223, s13, v179
	v_add_u32_e32 v233, s13, v176
	s_waitcnt vmcnt(8) lgkmcnt(0)
	s_barrier
	v_mfma_f32_32x32x16_bf16 v[112:127], v[150:153], v[142:145], v[112:127]
	v_mfma_f32_32x32x16_bf16 v[96:111], v[150:153], v[130:133], v[96:111]
	v_add_u32_e32 v206, v223, v177
	v_add_u32_e32 v234, v233, v177
	ds_read_b128 v[202:205], v206 offset:16384
	ds_read_b128 v[206:209], v206 offset:18432
	ds_read_b128 v[210:213], v234
	ds_read_b128 v[214:217], v234 offset:2048
	ds_read_b128 v[224:227], v234 offset:4096
	ds_read_b128 v[234:237], v234 offset:6144
	v_mfma_f32_32x32x16_bf16 v[80:95], v[146:149], v[142:145], v[80:95]
	v_mfma_f32_32x32x16_bf16 v[64:79], v[146:149], v[130:133], v[64:79]
	v_readfirstlane_b32 s13, v222
	s_mov_b32 m0, s13
	s_nop 0
	global_load_lds_dwordx4 v[170:171], off
	v_mfma_f32_32x32x16_bf16 v[48:63], v[138:141], v[142:145], v[48:63]
	v_mfma_f32_32x32x16_bf16 v[32:47], v[138:141], v[130:133], v[32:47]
	s_add_i32 s14, s13, 0x2000
	v_lshl_add_u64 v[150:151], v[170:171], 0, s[34:35]
	s_mov_b32 m0, s14
	s_nop 0
	global_load_lds_dwordx4 v[150:151], off
	v_mfma_f32_32x32x16_bf16 v[16:31], v[134:137], v[142:145], v[16:31]
	v_mfma_f32_32x32x16_bf16 v[0:15], v[134:137], v[130:133], v[0:15]
	v_add_u32_e32 v130, v223, v178
	v_add_u32_e32 v134, v233, v178
	ds_read_b128 v[142:145], v130 offset:16384
	ds_read_b128 v[130:133], v130 offset:18432
	ds_read_b128 v[150:153], v134
	ds_read_b128 v[146:149], v134 offset:2048
	ds_read_b128 v[138:141], v134 offset:4096
	ds_read_b128 v[134:137], v134 offset:6144
	s_waitcnt lgkmcnt(9)
	v_mfma_f32_32x32x16_bf16 v[112:127], v[210:213], v[202:205], v[112:127]
	s_add_i32 s14, s13, 0x6000
	s_addk_i32 s13, 0x4000
	v_mfma_f32_32x32x16_bf16 v[96:111], v[210:213], v[206:209], v[96:111]
	s_mov_b32 m0, s13
	s_nop 0
	global_load_lds_dwordx4 v[172:173], off
	v_lshl_add_u64 v[222:223], v[172:173], 0, s[34:35]
	s_waitcnt lgkmcnt(8)
	v_mfma_f32_32x32x16_bf16 v[80:95], v[214:217], v[202:205], v[80:95]
	v_mfma_f32_32x32x16_bf16 v[64:79], v[214:217], v[206:209], v[64:79]
	s_waitcnt lgkmcnt(7)
	v_mfma_f32_32x32x16_bf16 v[48:63], v[224:227], v[202:205], v[48:63]
	v_mfma_f32_32x32x16_bf16 v[32:47], v[224:227], v[206:209], v[32:47]
	s_mov_b32 m0, s14
	s_nop 0
	global_load_lds_dwordx4 v[222:223], off
	s_waitcnt lgkmcnt(6)
	v_mfma_f32_32x32x16_bf16 v[16:31], v[234:237], v[202:205], v[16:31]
	s_add_i32 s12, s12, 0x8000
	v_lshl_add_u64 v[170:171], v[170:171], 0, 64
	v_lshl_add_u64 v[172:173], v[172:173], 0, 64
	s_cmp_eq_u32 s12, 0x100000
	v_mfma_f32_32x32x16_bf16 v[0:15], v[234:237], v[206:209], v[0:15]
	s_cbranch_scc0 .LBB0_147
	s_waitcnt vmcnt(8) lgkmcnt(0)
	s_barrier
	v_add_u32_e32 v202, v179, v177
	v_add_u32_e32 v222, v176, v177
	ds_read_b128 v[170:173], v202 offset:49152
	ds_read_b128 v[202:205], v202 offset:51200
	ds_read_b128 v[206:209], v222 offset:32768
	ds_read_b128 v[210:213], v222 offset:34816
	ds_read_b128 v[214:217], v222 offset:36864
	ds_read_b128 v[224:227], v222 offset:38912
	s_waitcnt lgkmcnt(9)
	v_mfma_f32_32x32x16_bf16 v[112:127], v[150:153], v[142:145], v[112:127]
	v_mfma_f32_32x32x16_bf16 v[96:111], v[150:153], v[130:133], v[96:111]
	s_waitcnt lgkmcnt(8)
	v_mfma_f32_32x32x16_bf16 v[80:95], v[146:149], v[142:145], v[80:95]
	v_mfma_f32_32x32x16_bf16 v[64:79], v[146:149], v[130:133], v[64:79]
	s_waitcnt lgkmcnt(7)
	v_mfma_f32_32x32x16_bf16 v[48:63], v[138:141], v[142:145], v[48:63]
	v_mfma_f32_32x32x16_bf16 v[32:47], v[138:141], v[130:133], v[32:47]
	s_waitcnt lgkmcnt(6)
	v_mfma_f32_32x32x16_bf16 v[16:31], v[134:137], v[142:145], v[16:31]
	v_mfma_f32_32x32x16_bf16 v[0:15], v[134:137], v[130:133], v[0:15]
	v_add_u32_e32 v134, v179, v178
	v_add_u32_e32 v150, v176, v178
	ds_read_b128 v[130:133], v134 offset:49152
	ds_read_b128 v[134:137], v134 offset:51200
	ds_read_b128 v[138:141], v150 offset:32768
	ds_read_b128 v[142:145], v150 offset:34816
	ds_read_b128 v[146:149], v150 offset:36864
	ds_read_b128 v[150:153], v150 offset:38912
	s_waitcnt lgkmcnt(9)
	v_mfma_f32_32x32x16_bf16 v[112:127], v[206:209], v[170:173], v[112:127]
	v_mfma_f32_32x32x16_bf16 v[96:111], v[206:209], v[202:205], v[96:111]
	s_waitcnt lgkmcnt(8)
	v_mfma_f32_32x32x16_bf16 v[80:95], v[210:213], v[170:173], v[80:95]
	v_mfma_f32_32x32x16_bf16 v[64:79], v[210:213], v[202:205], v[64:79]
	s_waitcnt lgkmcnt(7)
	v_mfma_f32_32x32x16_bf16 v[48:63], v[214:217], v[170:173], v[48:63]
	v_mfma_f32_32x32x16_bf16 v[32:47], v[214:217], v[202:205], v[32:47]
	s_waitcnt lgkmcnt(6)
	v_mfma_f32_32x32x16_bf16 v[0:15], v[224:227], v[202:205], v[0:15]
	s_waitcnt vmcnt(4) lgkmcnt(0)
	s_barrier
	v_add_u32_e32 v202, v199, v177
	v_add_u32_e32 v222, v200, v177
	v_mfma_f32_32x32x16_bf16 v[16:31], v[224:227], v[170:173], v[16:31]
	ds_read_b128 v[170:173], v202 offset:16384
	ds_read_b128 v[202:205], v202 offset:18432
	ds_read_b128 v[206:209], v222
	ds_read_b128 v[210:213], v222 offset:2048
	ds_read_b128 v[214:217], v222 offset:4096
	ds_read_b128 v[224:227], v222 offset:6144
	s_waitcnt lgkmcnt(9)
	v_mfma_f32_32x32x16_bf16 v[112:127], v[138:141], v[130:133], v[112:127]
	v_mfma_f32_32x32x16_bf16 v[96:111], v[138:141], v[134:137], v[96:111]
	s_waitcnt lgkmcnt(8)
	v_mfma_f32_32x32x16_bf16 v[80:95], v[142:145], v[130:133], v[80:95]
	v_mfma_f32_32x32x16_bf16 v[64:79], v[142:145], v[134:137], v[64:79]
	s_waitcnt lgkmcnt(7)
	v_mfma_f32_32x32x16_bf16 v[48:63], v[146:149], v[130:133], v[48:63]
	v_mfma_f32_32x32x16_bf16 v[32:47], v[146:149], v[134:137], v[32:47]
	s_waitcnt lgkmcnt(6)
	v_mfma_f32_32x32x16_bf16 v[16:31], v[150:153], v[130:133], v[16:31]
	v_mfma_f32_32x32x16_bf16 v[0:15], v[150:153], v[134:137], v[0:15]
	v_add_u32_e32 v134, v199, v178
	v_add_u32_e32 v150, v200, v178
	ds_read_b128 v[130:133], v134 offset:16384
	ds_read_b128 v[134:137], v134 offset:18432
	ds_read_b128 v[138:141], v150
	ds_read_b128 v[142:145], v150 offset:2048
	ds_read_b128 v[146:149], v150 offset:4096
	ds_read_b128 v[150:153], v150 offset:6144
	s_waitcnt lgkmcnt(9)
	v_mfma_f32_32x32x16_bf16 v[112:127], v[206:209], v[170:173], v[112:127]
	v_mfma_f32_32x32x16_bf16 v[96:111], v[206:209], v[202:205], v[96:111]
	s_waitcnt lgkmcnt(8)
	v_mfma_f32_32x32x16_bf16 v[80:95], v[210:213], v[170:173], v[80:95]
	v_mfma_f32_32x32x16_bf16 v[64:79], v[210:213], v[202:205], v[64:79]
	s_waitcnt lgkmcnt(7)
	v_mfma_f32_32x32x16_bf16 v[48:63], v[214:217], v[170:173], v[48:63]
	v_mfma_f32_32x32x16_bf16 v[32:47], v[214:217], v[202:205], v[32:47]
	s_waitcnt lgkmcnt(6)
	v_mfma_f32_32x32x16_bf16 v[0:15], v[224:227], v[202:205], v[0:15]
	s_waitcnt vmcnt(0) lgkmcnt(0)
	s_barrier
	v_add_u32_e32 v202, v197, v177
	v_add_u32_e32 v222, v198, v177
	v_mfma_f32_32x32x16_bf16 v[16:31], v[224:227], v[170:173], v[16:31]
	ds_read_b128 v[170:173], v202 offset:16384
	ds_read_b128 v[202:205], v202 offset:18432
	ds_read_b128 v[206:209], v222
	ds_read_b128 v[210:213], v222 offset:2048
	ds_read_b128 v[214:217], v222 offset:4096
	ds_read_b128 v[224:227], v222 offset:6144
	s_waitcnt lgkmcnt(9)
	v_mfma_f32_32x32x16_bf16 v[112:127], v[138:141], v[130:133], v[112:127]
	v_mfma_f32_32x32x16_bf16 v[96:111], v[138:141], v[134:137], v[96:111]
	s_waitcnt lgkmcnt(8)
	v_mfma_f32_32x32x16_bf16 v[80:95], v[142:145], v[130:133], v[80:95]
	v_mfma_f32_32x32x16_bf16 v[64:79], v[142:145], v[134:137], v[64:79]
	s_waitcnt lgkmcnt(7)
	v_mfma_f32_32x32x16_bf16 v[48:63], v[146:149], v[130:133], v[48:63]
	v_mfma_f32_32x32x16_bf16 v[32:47], v[146:149], v[134:137], v[32:47]
	s_waitcnt lgkmcnt(6)
	v_mfma_f32_32x32x16_bf16 v[16:31], v[150:153], v[130:133], v[16:31]
	v_mfma_f32_32x32x16_bf16 v[0:15], v[150:153], v[134:137], v[0:15]
	v_add_u32_e32 v134, v197, v178
	v_add_u32_e32 v150, v198, v178
	ds_read_b128 v[130:133], v134 offset:16384
	ds_read_b128 v[134:137], v134 offset:18432
	ds_read_b128 v[138:141], v150
	ds_read_b128 v[142:145], v150 offset:2048
	ds_read_b128 v[146:149], v150 offset:4096
	ds_read_b128 v[150:153], v150 offset:6144
	s_waitcnt lgkmcnt(9)
	v_mfma_f32_32x32x16_bf16 v[112:127], v[206:209], v[170:173], v[112:127]
	v_mfma_f32_32x32x16_bf16 v[96:111], v[206:209], v[202:205], v[96:111]
	s_waitcnt lgkmcnt(8)
	v_mfma_f32_32x32x16_bf16 v[80:95], v[210:213], v[170:173], v[80:95]
	v_mfma_f32_32x32x16_bf16 v[64:79], v[210:213], v[202:205], v[64:79]
	s_waitcnt lgkmcnt(7)
	v_mfma_f32_32x32x16_bf16 v[48:63], v[214:217], v[170:173], v[48:63]
	v_mfma_f32_32x32x16_bf16 v[32:47], v[214:217], v[202:205], v[32:47]
	s_waitcnt lgkmcnt(6)
	v_mfma_f32_32x32x16_bf16 v[16:31], v[224:227], v[170:173], v[16:31]
	v_mfma_f32_32x32x16_bf16 v[0:15], v[224:227], v[202:205], v[0:15]
	s_waitcnt lgkmcnt(3)
	v_mfma_f32_32x32x16_bf16 v[96:111], v[138:141], v[134:137], v[96:111]
	v_mfma_f32_32x32x16_bf16 v[112:127], v[138:141], v[130:133], v[112:127]
	s_nop 10
	v_cvt_pk_bf16_f32 v96, v96, s0
	v_cvt_pk_bf16_f32 v98, v98, s0
	s_waitcnt lgkmcnt(2)
	v_mfma_f32_32x32x16_bf16 v[80:95], v[142:145], v[130:133], v[80:95]
	v_cvt_pk_bf16_f32 v112, v112, s0
	s_waitcnt lgkmcnt(1)
	v_mfma_f32_32x32x16_bf16 v[48:63], v[146:149], v[130:133], v[48:63]
	s_nop 8
	v_cvt_pk_bf16_f32 v80, v80, s0
	s_waitcnt lgkmcnt(0)
	v_mfma_f32_32x32x16_bf16 v[16:31], v[150:153], v[130:133], v[16:31]
	v_or_b32_e32 v130, s11, v174
	v_ashrrev_i32_e32 v131, 31, v130
	v_lshl_add_u64 v[130:131], v[130:131], 1, v[158:159]
	v_cvt_pk_bf16_f32 v48, v48, s0
	v_mfma_f32_32x32x16_bf16 v[64:79], v[142:145], v[134:137], v[64:79]
	s_nop 6
	v_cvt_pk_bf16_f32 v16, v16, s0
	v_mfma_f32_32x32x16_bf16 v[32:47], v[146:149], v[134:137], v[32:47]
	s_nop 2
	v_cvt_pk_bf16_f32 v64, v64, s0
	v_cvt_pk_bf16_f32 v66, v66, s0
	v_mfma_f32_32x32x16_bf16 v[0:15], v[150:153], v[134:137], v[0:15]
	v_add_u32_e32 v134, s7, v128
	v_or_b32_e32 v132, v134, v181
	s_movk_i32 s7, 0x1800
	v_mad_i64_i32 v[132:133], s[12:13], v132, s7, v[130:131]
	global_store_short v[132:133], v96, off offset:64
	v_or_b32_e32 v96, v134, v182
	global_store_short v[132:133], v112, off
	v_mad_i64_i32 v[132:133], s[12:13], v96, s7, v[130:131]
	v_cvt_pk_bf16_f32 v96, v113, s0
	global_store_short v[132:133], v96, off
	v_cvt_pk_bf16_f32 v96, v97, s0
	global_store_short v[132:133], v96, off offset:64
	v_or_b32_e32 v96, v134, v183
	v_mad_i64_i32 v[96:97], s[12:13], v96, s7, v[130:131]
	v_cvt_pk_bf16_f32 v112, v114, s0
	global_store_short v[96:97], v112, off
	global_store_short v[96:97], v98, off offset:64
	v_or_b32_e32 v96, v134, v184
	v_mad_i64_i32 v[96:97], s[12:13], v96, s7, v[130:131]
	v_cvt_pk_bf16_f32 v98, v115, s0
	global_store_short v[96:97], v98, off
	v_cvt_pk_bf16_f32 v98, v99, s0
	global_store_short v[96:97], v98, off offset:64
	v_or_b32_e32 v96, v134, v185
	v_mad_i64_i32 v[96:97], s[12:13], v96, s7, v[130:131]
	v_cvt_pk_bf16_f32 v98, v116, s0
	global_store_short v[96:97], v98, off
	v_cvt_pk_bf16_f32 v98, v100, s0
	global_store_short v[96:97], v98, off offset:64
	v_or_b32_e32 v96, v134, v186
	v_mad_i64_i32 v[96:97], s[12:13], v96, s7, v[130:131]
	v_cvt_pk_bf16_f32 v98, v117, s0
	global_store_short v[96:97], v98, off
	v_cvt_pk_bf16_f32 v98, v101, s0
	global_store_short v[96:97], v98, off offset:64
	v_or_b32_e32 v96, v134, v187
	v_mad_i64_i32 v[96:97], s[12:13], v96, s7, v[130:131]
	v_cvt_pk_bf16_f32 v98, v118, s0
	global_store_short v[96:97], v98, off
	v_cvt_pk_bf16_f32 v98, v102, s0
	global_store_short v[96:97], v98, off offset:64
	v_or_b32_e32 v96, v134, v188
	v_mad_i64_i32 v[96:97], s[12:13], v96, s7, v[130:131]
	v_cvt_pk_bf16_f32 v98, v119, s0
	global_store_short v[96:97], v98, off
	v_cvt_pk_bf16_f32 v98, v103, s0
	global_store_short v[96:97], v98, off offset:64
	v_or_b32_e32 v96, v134, v189
	v_mad_i64_i32 v[96:97], s[12:13], v96, s7, v[130:131]
	v_cvt_pk_bf16_f32 v98, v120, s0
	global_store_short v[96:97], v98, off
	v_cvt_pk_bf16_f32 v98, v104, s0
	global_store_short v[96:97], v98, off offset:64
	v_or_b32_e32 v96, v134, v190
	v_mad_i64_i32 v[96:97], s[12:13], v96, s7, v[130:131]
	v_cvt_pk_bf16_f32 v98, v121, s0
	global_store_short v[96:97], v98, off
	v_cvt_pk_bf16_f32 v98, v105, s0
	global_store_short v[96:97], v98, off offset:64
	v_or_b32_e32 v96, v134, v191
	v_mad_i64_i32 v[96:97], s[12:13], v96, s7, v[130:131]
	v_cvt_pk_bf16_f32 v98, v122, s0
	global_store_short v[96:97], v98, off
	v_cvt_pk_bf16_f32 v98, v106, s0
	global_store_short v[96:97], v98, off offset:64
	v_or_b32_e32 v96, v134, v192
	v_mad_i64_i32 v[96:97], s[12:13], v96, s7, v[130:131]
	v_cvt_pk_bf16_f32 v98, v123, s0
	global_store_short v[96:97], v98, off
	v_cvt_pk_bf16_f32 v98, v107, s0
	global_store_short v[96:97], v98, off offset:64
	v_or_b32_e32 v96, v134, v193
	v_mad_i64_i32 v[96:97], s[12:13], v96, s7, v[130:131]
	v_cvt_pk_bf16_f32 v98, v124, s0
	global_store_short v[96:97], v98, off
	v_cvt_pk_bf16_f32 v98, v108, s0
	global_store_short v[96:97], v98, off offset:64
	v_or_b32_e32 v96, v134, v194
	v_mad_i64_i32 v[96:97], s[12:13], v96, s7, v[130:131]
	v_cvt_pk_bf16_f32 v98, v125, s0
	global_store_short v[96:97], v98, off
	v_cvt_pk_bf16_f32 v98, v109, s0
	global_store_short v[96:97], v98, off offset:64
	v_or_b32_e32 v96, v134, v195
	v_mad_i64_i32 v[96:97], s[12:13], v96, s7, v[130:131]
	v_cvt_pk_bf16_f32 v98, v126, s0
	global_store_short v[96:97], v98, off
	v_cvt_pk_bf16_f32 v98, v110, s0
	global_store_short v[96:97], v98, off offset:64
	v_or_b32_e32 v96, v134, v196
	v_mad_i64_i32 v[96:97], s[12:13], v96, s7, v[130:131]
	v_cvt_pk_bf16_f32 v98, v127, s0
	global_store_short v[96:97], v98, off
	v_cvt_pk_bf16_f32 v98, v111, s0
	global_store_short v[96:97], v98, off offset:64
	v_or_b32_e32 v98, 32, v134
	v_or_b32_e32 v96, v98, v181
	v_mad_i64_i32 v[96:97], s[12:13], v96, s7, v[130:131]
	global_store_short v[96:97], v64, off offset:64
	v_or_b32_e32 v64, v98, v182
	global_store_short v[96:97], v80, off
	v_mad_i64_i32 v[96:97], s[12:13], v64, s7, v[130:131]
	v_cvt_pk_bf16_f32 v64, v81, s0
	global_store_short v[96:97], v64, off
	v_cvt_pk_bf16_f32 v64, v65, s0
	global_store_short v[96:97], v64, off offset:64
	v_or_b32_e32 v64, v98, v183
	v_mad_i64_i32 v[64:65], s[12:13], v64, s7, v[130:131]
	v_cvt_pk_bf16_f32 v80, v82, s0
	global_store_short v[64:65], v80, off
	global_store_short v[64:65], v66, off offset:64
	v_or_b32_e32 v64, v98, v184
	v_mad_i64_i32 v[64:65], s[12:13], v64, s7, v[130:131]
	v_cvt_pk_bf16_f32 v66, v83, s0
	global_store_short v[64:65], v66, off
	v_cvt_pk_bf16_f32 v66, v67, s0
	global_store_short v[64:65], v66, off offset:64
	v_or_b32_e32 v64, v98, v185
	v_mad_i64_i32 v[64:65], s[12:13], v64, s7, v[130:131]
	v_cvt_pk_bf16_f32 v66, v84, s0
	global_store_short v[64:65], v66, off
	v_cvt_pk_bf16_f32 v66, v68, s0
	global_store_short v[64:65], v66, off offset:64
	v_or_b32_e32 v64, v98, v186
	v_mad_i64_i32 v[64:65], s[12:13], v64, s7, v[130:131]
	v_cvt_pk_bf16_f32 v66, v85, s0
	global_store_short v[64:65], v66, off
	v_cvt_pk_bf16_f32 v66, v69, s0
	global_store_short v[64:65], v66, off offset:64
	v_or_b32_e32 v64, v98, v187
	v_mad_i64_i32 v[64:65], s[12:13], v64, s7, v[130:131]
	v_cvt_pk_bf16_f32 v66, v86, s0
	global_store_short v[64:65], v66, off
	v_cvt_pk_bf16_f32 v66, v70, s0
	global_store_short v[64:65], v66, off offset:64
	v_or_b32_e32 v64, v98, v188
	v_mad_i64_i32 v[64:65], s[12:13], v64, s7, v[130:131]
	v_cvt_pk_bf16_f32 v66, v87, s0
	global_store_short v[64:65], v66, off
	v_cvt_pk_bf16_f32 v66, v71, s0
	global_store_short v[64:65], v66, off offset:64
	v_or_b32_e32 v64, v98, v189
	v_mad_i64_i32 v[64:65], s[12:13], v64, s7, v[130:131]
	v_cvt_pk_bf16_f32 v66, v88, s0
	global_store_short v[64:65], v66, off
	v_cvt_pk_bf16_f32 v66, v72, s0
	global_store_short v[64:65], v66, off offset:64
	v_or_b32_e32 v64, v98, v190
	v_mad_i64_i32 v[64:65], s[12:13], v64, s7, v[130:131]
	v_cvt_pk_bf16_f32 v66, v89, s0
	global_store_short v[64:65], v66, off
	v_cvt_pk_bf16_f32 v66, v73, s0
	global_store_short v[64:65], v66, off offset:64
	v_or_b32_e32 v64, v98, v191
	v_mad_i64_i32 v[64:65], s[12:13], v64, s7, v[130:131]
	v_cvt_pk_bf16_f32 v66, v90, s0
	global_store_short v[64:65], v66, off
	v_cvt_pk_bf16_f32 v66, v74, s0
	global_store_short v[64:65], v66, off offset:64
	v_or_b32_e32 v64, v98, v192
	v_mad_i64_i32 v[64:65], s[12:13], v64, s7, v[130:131]
	v_cvt_pk_bf16_f32 v66, v91, s0
	global_store_short v[64:65], v66, off
	v_cvt_pk_bf16_f32 v66, v75, s0
	global_store_short v[64:65], v66, off offset:64
	v_or_b32_e32 v64, v98, v193
	v_mad_i64_i32 v[64:65], s[12:13], v64, s7, v[130:131]
	v_cvt_pk_bf16_f32 v66, v92, s0
	global_store_short v[64:65], v66, off
	v_cvt_pk_bf16_f32 v66, v76, s0
	global_store_short v[64:65], v66, off offset:64
	v_or_b32_e32 v64, v98, v194
	v_mad_i64_i32 v[64:65], s[12:13], v64, s7, v[130:131]
	v_cvt_pk_bf16_f32 v66, v93, s0
	global_store_short v[64:65], v66, off
	v_cvt_pk_bf16_f32 v66, v77, s0
	global_store_short v[64:65], v66, off offset:64
	v_or_b32_e32 v64, v98, v195
	v_mad_i64_i32 v[64:65], s[12:13], v64, s7, v[130:131]
	v_cvt_pk_bf16_f32 v66, v94, s0
	global_store_short v[64:65], v66, off
	v_cvt_pk_bf16_f32 v66, v78, s0
	global_store_short v[64:65], v66, off offset:64
	v_or_b32_e32 v64, v98, v196
	v_mad_i64_i32 v[64:65], s[12:13], v64, s7, v[130:131]
	v_cvt_pk_bf16_f32 v66, v95, s0
	global_store_short v[64:65], v66, off
	v_cvt_pk_bf16_f32 v66, v79, s0
	global_store_short v[64:65], v66, off offset:64
	v_or_b32_e32 v66, 64, v134
	v_or_b32_e32 v64, v66, v181
	v_mad_i64_i32 v[64:65], s[12:13], v64, s7, v[130:131]
	v_cvt_pk_bf16_f32 v32, v32, s0
	global_store_short v[64:65], v32, off offset:64
	v_or_b32_e32 v32, v66, v182
	global_store_short v[64:65], v48, off
	v_mad_i64_i32 v[64:65], s[12:13], v32, s7, v[130:131]
	v_cvt_pk_bf16_f32 v32, v49, s0
	global_store_short v[64:65], v32, off
	v_cvt_pk_bf16_f32 v32, v33, s0
	global_store_short v[64:65], v32, off offset:64
	v_or_b32_e32 v32, v66, v183
	v_mad_i64_i32 v[32:33], s[12:13], v32, s7, v[130:131]
	v_cvt_pk_bf16_f32 v48, v50, s0
	v_cvt_pk_bf16_f32 v34, v34, s0
	global_store_short v[32:33], v48, off
	global_store_short v[32:33], v34, off offset:64
	v_or_b32_e32 v32, v66, v184
	v_mad_i64_i32 v[32:33], s[12:13], v32, s7, v[130:131]
	v_cvt_pk_bf16_f32 v34, v51, s0
	global_store_short v[32:33], v34, off
	v_cvt_pk_bf16_f32 v34, v35, s0
	global_store_short v[32:33], v34, off offset:64
	v_or_b32_e32 v32, v66, v185
	v_mad_i64_i32 v[32:33], s[12:13], v32, s7, v[130:131]
	v_cvt_pk_bf16_f32 v34, v52, s0
	global_store_short v[32:33], v34, off
	v_cvt_pk_bf16_f32 v34, v36, s0
	global_store_short v[32:33], v34, off offset:64
	v_or_b32_e32 v32, v66, v186
	v_mad_i64_i32 v[32:33], s[12:13], v32, s7, v[130:131]
	v_cvt_pk_bf16_f32 v34, v53, s0
	global_store_short v[32:33], v34, off
	v_cvt_pk_bf16_f32 v34, v37, s0
	global_store_short v[32:33], v34, off offset:64
	v_or_b32_e32 v32, v66, v187
	v_mad_i64_i32 v[32:33], s[12:13], v32, s7, v[130:131]
	v_cvt_pk_bf16_f32 v34, v54, s0
	global_store_short v[32:33], v34, off
	v_cvt_pk_bf16_f32 v34, v38, s0
	global_store_short v[32:33], v34, off offset:64
	v_or_b32_e32 v32, v66, v188
	v_mad_i64_i32 v[32:33], s[12:13], v32, s7, v[130:131]
	v_cvt_pk_bf16_f32 v34, v55, s0
	global_store_short v[32:33], v34, off
	v_cvt_pk_bf16_f32 v34, v39, s0
	global_store_short v[32:33], v34, off offset:64
	v_or_b32_e32 v32, v66, v189
	v_mad_i64_i32 v[32:33], s[12:13], v32, s7, v[130:131]
	v_cvt_pk_bf16_f32 v34, v56, s0
	global_store_short v[32:33], v34, off
	v_cvt_pk_bf16_f32 v34, v40, s0
	global_store_short v[32:33], v34, off offset:64
	v_or_b32_e32 v32, v66, v190
	v_mad_i64_i32 v[32:33], s[12:13], v32, s7, v[130:131]
	v_cvt_pk_bf16_f32 v34, v57, s0
	global_store_short v[32:33], v34, off
	v_cvt_pk_bf16_f32 v34, v41, s0
	global_store_short v[32:33], v34, off offset:64
	v_or_b32_e32 v32, v66, v191
	v_mad_i64_i32 v[32:33], s[12:13], v32, s7, v[130:131]
	v_cvt_pk_bf16_f32 v34, v58, s0
	global_store_short v[32:33], v34, off
	v_cvt_pk_bf16_f32 v34, v42, s0
	global_store_short v[32:33], v34, off offset:64
	v_or_b32_e32 v32, v66, v192
	v_mad_i64_i32 v[32:33], s[12:13], v32, s7, v[130:131]
	v_cvt_pk_bf16_f32 v34, v59, s0
	global_store_short v[32:33], v34, off
	v_cvt_pk_bf16_f32 v34, v43, s0
	global_store_short v[32:33], v34, off offset:64
	v_or_b32_e32 v32, v66, v193
	v_mad_i64_i32 v[32:33], s[12:13], v32, s7, v[130:131]
	v_cvt_pk_bf16_f32 v34, v60, s0
	global_store_short v[32:33], v34, off
	v_cvt_pk_bf16_f32 v34, v44, s0
	global_store_short v[32:33], v34, off offset:64
	v_or_b32_e32 v32, v66, v194
	v_mad_i64_i32 v[32:33], s[12:13], v32, s7, v[130:131]
	v_cvt_pk_bf16_f32 v34, v61, s0
	global_store_short v[32:33], v34, off
	v_cvt_pk_bf16_f32 v34, v45, s0
	global_store_short v[32:33], v34, off offset:64
	v_or_b32_e32 v32, v66, v195
	v_mad_i64_i32 v[32:33], s[12:13], v32, s7, v[130:131]
	v_cvt_pk_bf16_f32 v34, v62, s0
	global_store_short v[32:33], v34, off
	v_cvt_pk_bf16_f32 v34, v46, s0
	global_store_short v[32:33], v34, off offset:64
	v_or_b32_e32 v32, v66, v196
	v_mad_i64_i32 v[32:33], s[12:13], v32, s7, v[130:131]
	v_cvt_pk_bf16_f32 v34, v63, s0
	global_store_short v[32:33], v34, off
	v_cvt_pk_bf16_f32 v34, v47, s0
	global_store_short v[32:33], v34, off offset:64
	v_or_b32_e32 v34, 0x60, v134
	v_or_b32_e32 v32, v34, v181
	v_mad_i64_i32 v[32:33], s[12:13], v32, s7, v[130:131]
	v_cvt_pk_bf16_f32 v0, v0, s0
	global_store_short v[32:33], v0, off offset:64
	v_or_b32_e32 v0, v34, v182
	global_store_short v[32:33], v16, off
	v_mad_i64_i32 v[32:33], s[12:13], v0, s7, v[130:131]
	v_cvt_pk_bf16_f32 v0, v17, s0
	global_store_short v[32:33], v0, off
	v_cvt_pk_bf16_f32 v0, v1, s0
	global_store_short v[32:33], v0, off offset:64
	v_or_b32_e32 v0, v34, v183
	v_mad_i64_i32 v[0:1], s[12:13], v0, s7, v[130:131]
	v_cvt_pk_bf16_f32 v16, v18, s0
	v_cvt_pk_bf16_f32 v2, v2, s0
	global_store_short v[0:1], v16, off
	global_store_short v[0:1], v2, off offset:64
	v_or_b32_e32 v0, v34, v184
	v_mad_i64_i32 v[0:1], s[12:13], v0, s7, v[130:131]
	v_cvt_pk_bf16_f32 v2, v19, s0
	global_store_short v[0:1], v2, off
	v_cvt_pk_bf16_f32 v2, v3, s0
	global_store_short v[0:1], v2, off offset:64
	v_or_b32_e32 v0, v34, v185
	v_mad_i64_i32 v[0:1], s[12:13], v0, s7, v[130:131]
	v_cvt_pk_bf16_f32 v2, v20, s0
	global_store_short v[0:1], v2, off
	v_cvt_pk_bf16_f32 v2, v4, s0
	global_store_short v[0:1], v2, off offset:64
	v_or_b32_e32 v0, v34, v186
	v_mad_i64_i32 v[0:1], s[12:13], v0, s7, v[130:131]
	v_cvt_pk_bf16_f32 v2, v21, s0
	global_store_short v[0:1], v2, off
	v_cvt_pk_bf16_f32 v2, v5, s0
	global_store_short v[0:1], v2, off offset:64
	v_or_b32_e32 v0, v34, v187
	v_mad_i64_i32 v[0:1], s[12:13], v0, s7, v[130:131]
	v_cvt_pk_bf16_f32 v2, v22, s0
	global_store_short v[0:1], v2, off
	v_cvt_pk_bf16_f32 v2, v6, s0
	global_store_short v[0:1], v2, off offset:64
	v_or_b32_e32 v0, v34, v188
	v_mad_i64_i32 v[0:1], s[12:13], v0, s7, v[130:131]
	v_cvt_pk_bf16_f32 v2, v23, s0
	global_store_short v[0:1], v2, off
	v_cvt_pk_bf16_f32 v2, v7, s0
	global_store_short v[0:1], v2, off offset:64
	v_or_b32_e32 v0, v34, v189
	v_mad_i64_i32 v[0:1], s[12:13], v0, s7, v[130:131]
	v_cvt_pk_bf16_f32 v2, v24, s0
	global_store_short v[0:1], v2, off
	v_cvt_pk_bf16_f32 v2, v8, s0
	global_store_short v[0:1], v2, off offset:64
	v_or_b32_e32 v0, v34, v190
	v_mad_i64_i32 v[0:1], s[12:13], v0, s7, v[130:131]
	v_cvt_pk_bf16_f32 v2, v25, s0
	global_store_short v[0:1], v2, off
	v_cvt_pk_bf16_f32 v2, v9, s0
	global_store_short v[0:1], v2, off offset:64
	v_or_b32_e32 v0, v34, v191
	v_mad_i64_i32 v[0:1], s[12:13], v0, s7, v[130:131]
	v_cvt_pk_bf16_f32 v2, v26, s0
	global_store_short v[0:1], v2, off
	v_cvt_pk_bf16_f32 v2, v10, s0
	global_store_short v[0:1], v2, off offset:64
	v_or_b32_e32 v0, v34, v192
	v_mad_i64_i32 v[0:1], s[12:13], v0, s7, v[130:131]
	v_cvt_pk_bf16_f32 v2, v27, s0
	global_store_short v[0:1], v2, off
	v_cvt_pk_bf16_f32 v2, v11, s0
	global_store_short v[0:1], v2, off offset:64
	v_or_b32_e32 v0, v34, v193
	v_mad_i64_i32 v[0:1], s[12:13], v0, s7, v[130:131]
	v_cvt_pk_bf16_f32 v2, v28, s0
	global_store_short v[0:1], v2, off
	v_cvt_pk_bf16_f32 v2, v12, s0
	global_store_short v[0:1], v2, off offset:64
	v_or_b32_e32 v0, v34, v194
	v_mad_i64_i32 v[0:1], s[12:13], v0, s7, v[130:131]
	v_cvt_pk_bf16_f32 v2, v29, s0
	global_store_short v[0:1], v2, off
	v_cvt_pk_bf16_f32 v2, v13, s0
	global_store_short v[0:1], v2, off offset:64
	v_or_b32_e32 v0, v34, v195
	v_mad_i64_i32 v[0:1], s[12:13], v0, s7, v[130:131]
	v_cvt_pk_bf16_f32 v2, v30, s0
	global_store_short v[0:1], v2, off
	v_cvt_pk_bf16_f32 v2, v14, s0
	global_store_short v[0:1], v2, off offset:64
	v_or_b32_e32 v0, v34, v196
	v_mad_i64_i32 v[0:1], s[12:13], v0, s7, v[130:131]
	v_readlane_b32 s7, v252, 7
	s_add_i32 s10, s10, s7
	s_add_i32 s4, s4, s7
	v_readlane_b32 s7, v252, 8
	v_cvt_pk_bf16_f32 v2, v31, s0
	s_add_i32 s6, s6, s7
	global_store_short v[0:1], v2, off
	v_cvt_pk_bf16_f32 v2, v15, s0
	s_cmpk_gt_i32 s10, 0x5f
	global_store_short v[0:1], v2, off offset:64
	s_cbranch_scc0 .LBB0_146

.LBB0_263:
	s_and_b32 s11, s10, 0x18000
	v_add_u32_e32 v222, s11, v180
	s_add_i32 s11, s10, 0xfffe8000
	s_and_b32 s11, s11, 0x18000
	v_or_b32_e32 v223, s11, v179
	v_add_u32_e32 v233, s11, v176
	s_waitcnt vmcnt(8) lgkmcnt(0)
	s_barrier
	v_mfma_f32_32x32x16_bf16 v[112:127], v[150:153], v[142:145], v[112:127]
	v_mfma_f32_32x32x16_bf16 v[96:111], v[150:153], v[130:133], v[96:111]
	v_add_u32_e32 v206, v223, v177
	v_add_u32_e32 v234, v233, v177
	ds_read_b128 v[202:205], v206 offset:16384
	ds_read_b128 v[206:209], v206 offset:18432
	ds_read_b128 v[210:213], v234
	ds_read_b128 v[214:217], v234 offset:2048
	ds_read_b128 v[224:227], v234 offset:4096
	ds_read_b128 v[234:237], v234 offset:6144
	v_mfma_f32_32x32x16_bf16 v[80:95], v[146:149], v[142:145], v[80:95]
	v_mfma_f32_32x32x16_bf16 v[64:79], v[146:149], v[130:133], v[64:79]
	v_readfirstlane_b32 s11, v222
	s_mov_b32 m0, s11
	s_nop 0
	global_load_lds_dwordx4 v[170:171], off
	v_mfma_f32_32x32x16_bf16 v[48:63], v[138:141], v[142:145], v[48:63]
	v_mfma_f32_32x32x16_bf16 v[32:47], v[138:141], v[130:133], v[32:47]
	s_add_i32 s12, s11, 0x2000
	v_lshl_add_u64 v[150:151], v[170:171], 0, s[34:35]
	s_mov_b32 m0, s12
	s_nop 0
	global_load_lds_dwordx4 v[150:151], off
	v_mfma_f32_32x32x16_bf16 v[16:31], v[134:137], v[142:145], v[16:31]
	v_mfma_f32_32x32x16_bf16 v[0:15], v[134:137], v[130:133], v[0:15]
	v_add_u32_e32 v130, v223, v178
	v_add_u32_e32 v134, v233, v178
	ds_read_b128 v[142:145], v130 offset:16384
	ds_read_b128 v[130:133], v130 offset:18432
	ds_read_b128 v[150:153], v134
	ds_read_b128 v[146:149], v134 offset:2048
	ds_read_b128 v[138:141], v134 offset:4096
	ds_read_b128 v[134:137], v134 offset:6144
	s_waitcnt lgkmcnt(9)
	v_mfma_f32_32x32x16_bf16 v[112:127], v[210:213], v[202:205], v[112:127]
	s_add_i32 s12, s11, 0x6000
	s_addk_i32 s11, 0x4000
	v_mfma_f32_32x32x16_bf16 v[96:111], v[210:213], v[206:209], v[96:111]
	s_mov_b32 m0, s11
	s_nop 0
	global_load_lds_dwordx4 v[172:173], off
	v_lshl_add_u64 v[222:223], v[172:173], 0, s[34:35]
	s_waitcnt lgkmcnt(8)
	v_mfma_f32_32x32x16_bf16 v[80:95], v[214:217], v[202:205], v[80:95]
	v_mfma_f32_32x32x16_bf16 v[64:79], v[214:217], v[206:209], v[64:79]
	s_waitcnt lgkmcnt(7)
	v_mfma_f32_32x32x16_bf16 v[48:63], v[224:227], v[202:205], v[48:63]
	v_mfma_f32_32x32x16_bf16 v[32:47], v[224:227], v[206:209], v[32:47]
	s_mov_b32 m0, s12
	s_nop 0
	global_load_lds_dwordx4 v[222:223], off
	s_waitcnt lgkmcnt(6)
	v_mfma_f32_32x32x16_bf16 v[16:31], v[234:237], v[202:205], v[16:31]
	s_add_i32 s10, s10, 0x8000
	v_lshl_add_u64 v[170:171], v[170:171], 0, 64
	v_lshl_add_u64 v[172:173], v[172:173], 0, 64
	s_cmp_eq_u32 s10, 0x100000
	v_mfma_f32_32x32x16_bf16 v[0:15], v[234:237], v[206:209], v[0:15]
	s_cbranch_scc0 .LBB0_263
	s_waitcnt vmcnt(8) lgkmcnt(0)
	s_barrier
	v_add_u32_e32 v202, v179, v177
	v_add_u32_e32 v222, v176, v177
	ds_read_b128 v[170:173], v202 offset:49152
	ds_read_b128 v[202:205], v202 offset:51200
	ds_read_b128 v[206:209], v222 offset:32768
	ds_read_b128 v[210:213], v222 offset:34816
	ds_read_b128 v[214:217], v222 offset:36864
	ds_read_b128 v[224:227], v222 offset:38912
	s_waitcnt lgkmcnt(9)
	v_mfma_f32_32x32x16_bf16 v[112:127], v[150:153], v[142:145], v[112:127]
	v_mfma_f32_32x32x16_bf16 v[96:111], v[150:153], v[130:133], v[96:111]
	s_waitcnt lgkmcnt(8)
	v_mfma_f32_32x32x16_bf16 v[80:95], v[146:149], v[142:145], v[80:95]
	v_mfma_f32_32x32x16_bf16 v[64:79], v[146:149], v[130:133], v[64:79]
	s_waitcnt lgkmcnt(7)
	v_mfma_f32_32x32x16_bf16 v[48:63], v[138:141], v[142:145], v[48:63]
	v_mfma_f32_32x32x16_bf16 v[32:47], v[138:141], v[130:133], v[32:47]
	s_waitcnt lgkmcnt(6)
	v_mfma_f32_32x32x16_bf16 v[16:31], v[134:137], v[142:145], v[16:31]
	v_mfma_f32_32x32x16_bf16 v[0:15], v[134:137], v[130:133], v[0:15]
	v_add_u32_e32 v134, v179, v178
	v_add_u32_e32 v150, v176, v178
	ds_read_b128 v[130:133], v134 offset:49152
	ds_read_b128 v[134:137], v134 offset:51200
	ds_read_b128 v[138:141], v150 offset:32768
	ds_read_b128 v[142:145], v150 offset:34816
	ds_read_b128 v[146:149], v150 offset:36864
	ds_read_b128 v[150:153], v150 offset:38912
	s_waitcnt lgkmcnt(9)
	v_mfma_f32_32x32x16_bf16 v[112:127], v[206:209], v[170:173], v[112:127]
	v_mfma_f32_32x32x16_bf16 v[96:111], v[206:209], v[202:205], v[96:111]
	s_waitcnt lgkmcnt(8)
	v_mfma_f32_32x32x16_bf16 v[80:95], v[210:213], v[170:173], v[80:95]
	v_mfma_f32_32x32x16_bf16 v[64:79], v[210:213], v[202:205], v[64:79]
	s_waitcnt lgkmcnt(7)
	v_mfma_f32_32x32x16_bf16 v[48:63], v[214:217], v[170:173], v[48:63]
	v_mfma_f32_32x32x16_bf16 v[32:47], v[214:217], v[202:205], v[32:47]
	s_waitcnt lgkmcnt(6)
	v_mfma_f32_32x32x16_bf16 v[0:15], v[224:227], v[202:205], v[0:15]
	s_waitcnt vmcnt(4) lgkmcnt(0)
	s_barrier
	v_add_u32_e32 v202, v199, v177
	v_add_u32_e32 v222, v200, v177
	v_mfma_f32_32x32x16_bf16 v[16:31], v[224:227], v[170:173], v[16:31]
	ds_read_b128 v[170:173], v202 offset:16384
	ds_read_b128 v[202:205], v202 offset:18432
	ds_read_b128 v[206:209], v222
	ds_read_b128 v[210:213], v222 offset:2048
	ds_read_b128 v[214:217], v222 offset:4096
	ds_read_b128 v[224:227], v222 offset:6144
	s_waitcnt lgkmcnt(9)
	v_mfma_f32_32x32x16_bf16 v[112:127], v[138:141], v[130:133], v[112:127]
	v_mfma_f32_32x32x16_bf16 v[96:111], v[138:141], v[134:137], v[96:111]
	s_waitcnt lgkmcnt(8)
	v_mfma_f32_32x32x16_bf16 v[80:95], v[142:145], v[130:133], v[80:95]
	v_mfma_f32_32x32x16_bf16 v[64:79], v[142:145], v[134:137], v[64:79]
	s_waitcnt lgkmcnt(7)
	v_mfma_f32_32x32x16_bf16 v[48:63], v[146:149], v[130:133], v[48:63]
	v_mfma_f32_32x32x16_bf16 v[32:47], v[146:149], v[134:137], v[32:47]
	s_waitcnt lgkmcnt(6)
	v_mfma_f32_32x32x16_bf16 v[16:31], v[150:153], v[130:133], v[16:31]
	v_mfma_f32_32x32x16_bf16 v[0:15], v[150:153], v[134:137], v[0:15]
	v_add_u32_e32 v134, v199, v178
	v_add_u32_e32 v150, v200, v178
	ds_read_b128 v[130:133], v134 offset:16384
	ds_read_b128 v[134:137], v134 offset:18432
	ds_read_b128 v[138:141], v150
	ds_read_b128 v[142:145], v150 offset:2048
	ds_read_b128 v[146:149], v150 offset:4096
	ds_read_b128 v[150:153], v150 offset:6144
	s_waitcnt lgkmcnt(9)
	v_mfma_f32_32x32x16_bf16 v[112:127], v[206:209], v[170:173], v[112:127]
	v_mfma_f32_32x32x16_bf16 v[96:111], v[206:209], v[202:205], v[96:111]
	s_waitcnt lgkmcnt(8)
	v_mfma_f32_32x32x16_bf16 v[80:95], v[210:213], v[170:173], v[80:95]
	v_mfma_f32_32x32x16_bf16 v[64:79], v[210:213], v[202:205], v[64:79]
	s_waitcnt lgkmcnt(7)
	v_mfma_f32_32x32x16_bf16 v[48:63], v[214:217], v[170:173], v[48:63]
	v_mfma_f32_32x32x16_bf16 v[32:47], v[214:217], v[202:205], v[32:47]
	s_waitcnt lgkmcnt(6)
	v_mfma_f32_32x32x16_bf16 v[0:15], v[224:227], v[202:205], v[0:15]
	s_waitcnt vmcnt(0) lgkmcnt(0)
	s_barrier
	v_add_u32_e32 v202, v197, v177
	v_add_u32_e32 v222, v198, v177
	v_mfma_f32_32x32x16_bf16 v[16:31], v[224:227], v[170:173], v[16:31]
	ds_read_b128 v[170:173], v202 offset:16384
	ds_read_b128 v[202:205], v202 offset:18432
	ds_read_b128 v[206:209], v222
	ds_read_b128 v[210:213], v222 offset:2048
	ds_read_b128 v[214:217], v222 offset:4096
	ds_read_b128 v[224:227], v222 offset:6144
	s_waitcnt lgkmcnt(9)
	v_mfma_f32_32x32x16_bf16 v[112:127], v[138:141], v[130:133], v[112:127]
	v_mfma_f32_32x32x16_bf16 v[96:111], v[138:141], v[134:137], v[96:111]
	s_waitcnt lgkmcnt(8)
	v_mfma_f32_32x32x16_bf16 v[80:95], v[142:145], v[130:133], v[80:95]
	v_mfma_f32_32x32x16_bf16 v[64:79], v[142:145], v[134:137], v[64:79]
	s_waitcnt lgkmcnt(7)
	v_mfma_f32_32x32x16_bf16 v[48:63], v[146:149], v[130:133], v[48:63]
	v_mfma_f32_32x32x16_bf16 v[32:47], v[146:149], v[134:137], v[32:47]
	s_waitcnt lgkmcnt(6)
	v_mfma_f32_32x32x16_bf16 v[16:31], v[150:153], v[130:133], v[16:31]
	v_mfma_f32_32x32x16_bf16 v[0:15], v[150:153], v[134:137], v[0:15]
	v_add_u32_e32 v134, v197, v178
	v_add_u32_e32 v150, v198, v178
	ds_read_b128 v[130:133], v134 offset:16384
	ds_read_b128 v[134:137], v134 offset:18432
	ds_read_b128 v[138:141], v150
	ds_read_b128 v[142:145], v150 offset:2048
	ds_read_b128 v[146:149], v150 offset:4096
	ds_read_b128 v[150:153], v150 offset:6144
	s_waitcnt lgkmcnt(9)
	v_mfma_f32_32x32x16_bf16 v[112:127], v[206:209], v[170:173], v[112:127]
	v_mfma_f32_32x32x16_bf16 v[96:111], v[206:209], v[202:205], v[96:111]
	s_waitcnt lgkmcnt(8)
	v_mfma_f32_32x32x16_bf16 v[80:95], v[210:213], v[170:173], v[80:95]
	v_mfma_f32_32x32x16_bf16 v[64:79], v[210:213], v[202:205], v[64:79]
	s_waitcnt lgkmcnt(7)
	v_mfma_f32_32x32x16_bf16 v[48:63], v[214:217], v[170:173], v[48:63]
	v_mfma_f32_32x32x16_bf16 v[32:47], v[214:217], v[202:205], v[32:47]
	s_waitcnt lgkmcnt(6)
	v_mfma_f32_32x32x16_bf16 v[16:31], v[224:227], v[170:173], v[16:31]
	v_mfma_f32_32x32x16_bf16 v[0:15], v[224:227], v[202:205], v[0:15]
	s_waitcnt lgkmcnt(3)
	v_mfma_f32_32x32x16_bf16 v[112:127], v[138:141], v[130:133], v[112:127]
	v_mfma_f32_32x32x16_bf16 v[96:111], v[138:141], v[134:137], v[96:111]
	s_nop 10
	v_cvt_pk_bf16_f32 v112, v112, s0
	s_waitcnt lgkmcnt(2)
	v_mfma_f32_32x32x16_bf16 v[80:95], v[142:145], v[130:133], v[80:95]
	v_cvt_pk_bf16_f32 v96, v96, s0
	v_cvt_pk_bf16_f32 v98, v98, s0
	s_waitcnt lgkmcnt(1)
	v_mfma_f32_32x32x16_bf16 v[48:63], v[146:149], v[130:133], v[48:63]
	s_nop 7
	v_cvt_pk_bf16_f32 v80, v80, s0
	s_waitcnt lgkmcnt(0)
	v_mfma_f32_32x32x16_bf16 v[16:31], v[150:153], v[130:133], v[16:31]
	v_add_u32_e32 v132, s5, v128
	v_or_b32_e32 v130, s7, v174
	v_ashrrev_i32_e32 v131, 31, v130
	v_lshl_add_u64 v[130:131], v[130:131], 1, v[158:159]
	v_cvt_pk_bf16_f32 v48, v48, s0
	v_readlane_b32 s5, v252, 7
	s_add_i32 s6, s6, s5
	v_mfma_f32_32x32x16_bf16 v[64:79], v[142:145], v[134:137], v[64:79]
	s_nop 3
	v_cvt_pk_bf16_f32 v16, v16, s0
	s_add_i32 s2, s2, s5
	v_readlane_b32 s5, v252, 8
	s_add_i32 s4, s4, s5
	s_cmp_gt_i32 s6, 31
	s_nop 2
	v_cvt_pk_bf16_f32 v64, v64, s0
	v_mfma_f32_32x32x16_bf16 v[32:47], v[146:149], v[134:137], v[32:47]
	v_cvt_pk_bf16_f32 v66, v66, s0
	v_mfma_f32_32x32x16_bf16 v[0:15], v[150:153], v[134:137], v[0:15]
	v_or_b32_e32 v134, v132, v181
	v_ashrrev_i32_e32 v135, 31, v134
	v_lshlrev_b64 v[134:135], 11, v[134:135]
	v_lshl_add_u64 v[134:135], v[130:131], 0, v[134:135]
	global_store_short v[134:135], v112, off
	global_store_short v[134:135], v96, off offset:64
	v_or_b32_e32 v134, v132, v182
	v_ashrrev_i32_e32 v135, 31, v134
	v_lshlrev_b64 v[134:135], 11, v[134:135]
	v_lshl_add_u64 v[134:135], v[130:131], 0, v[134:135]
	v_cvt_pk_bf16_f32 v96, v113, s0
	global_store_short v[134:135], v96, off
	v_cvt_pk_bf16_f32 v96, v97, s0
	global_store_short v[134:135], v96, off offset:64
	v_or_b32_e32 v96, v132, v183
	v_ashrrev_i32_e32 v97, 31, v96
	v_lshlrev_b64 v[96:97], 11, v[96:97]
	v_lshl_add_u64 v[96:97], v[130:131], 0, v[96:97]
	v_cvt_pk_bf16_f32 v112, v114, s0
	global_store_short v[96:97], v112, off
	global_store_short v[96:97], v98, off offset:64
	v_or_b32_e32 v96, v132, v184
	v_ashrrev_i32_e32 v97, 31, v96
	v_lshlrev_b64 v[96:97], 11, v[96:97]
	v_lshl_add_u64 v[96:97], v[130:131], 0, v[96:97]
	v_cvt_pk_bf16_f32 v98, v115, s0
	global_store_short v[96:97], v98, off
	v_cvt_pk_bf16_f32 v98, v99, s0
	global_store_short v[96:97], v98, off offset:64
	v_or_b32_e32 v96, v132, v185
	v_ashrrev_i32_e32 v97, 31, v96
	v_lshlrev_b64 v[96:97], 11, v[96:97]
	v_lshl_add_u64 v[96:97], v[130:131], 0, v[96:97]
	v_cvt_pk_bf16_f32 v98, v116, s0
	global_store_short v[96:97], v98, off
	v_cvt_pk_bf16_f32 v98, v100, s0
	global_store_short v[96:97], v98, off offset:64
	v_or_b32_e32 v96, v132, v186
	v_ashrrev_i32_e32 v97, 31, v96
	v_lshlrev_b64 v[96:97], 11, v[96:97]
	v_lshl_add_u64 v[96:97], v[130:131], 0, v[96:97]
	v_cvt_pk_bf16_f32 v98, v117, s0
	global_store_short v[96:97], v98, off
	v_cvt_pk_bf16_f32 v98, v101, s0
	global_store_short v[96:97], v98, off offset:64
	v_or_b32_e32 v96, v132, v187
	v_ashrrev_i32_e32 v97, 31, v96
	v_lshlrev_b64 v[96:97], 11, v[96:97]
	v_lshl_add_u64 v[96:97], v[130:131], 0, v[96:97]
	v_cvt_pk_bf16_f32 v98, v118, s0
	global_store_short v[96:97], v98, off
	v_cvt_pk_bf16_f32 v98, v102, s0
	global_store_short v[96:97], v98, off offset:64
	v_or_b32_e32 v96, v132, v188
	v_ashrrev_i32_e32 v97, 31, v96
	v_lshlrev_b64 v[96:97], 11, v[96:97]
	v_lshl_add_u64 v[96:97], v[130:131], 0, v[96:97]
	v_cvt_pk_bf16_f32 v98, v119, s0
	global_store_short v[96:97], v98, off
	v_cvt_pk_bf16_f32 v98, v103, s0
	global_store_short v[96:97], v98, off offset:64
	v_or_b32_e32 v96, v132, v189
	v_ashrrev_i32_e32 v97, 31, v96
	v_lshlrev_b64 v[96:97], 11, v[96:97]
	v_lshl_add_u64 v[96:97], v[130:131], 0, v[96:97]
	v_cvt_pk_bf16_f32 v98, v120, s0
	global_store_short v[96:97], v98, off
	v_cvt_pk_bf16_f32 v98, v104, s0
	global_store_short v[96:97], v98, off offset:64
	v_or_b32_e32 v96, v132, v190
	v_ashrrev_i32_e32 v97, 31, v96
	v_lshlrev_b64 v[96:97], 11, v[96:97]
	v_lshl_add_u64 v[96:97], v[130:131], 0, v[96:97]
	v_cvt_pk_bf16_f32 v98, v121, s0
	global_store_short v[96:97], v98, off
	v_cvt_pk_bf16_f32 v98, v105, s0
	global_store_short v[96:97], v98, off offset:64
	v_or_b32_e32 v96, v132, v191
	v_ashrrev_i32_e32 v97, 31, v96
	v_lshlrev_b64 v[96:97], 11, v[96:97]
	v_lshl_add_u64 v[96:97], v[130:131], 0, v[96:97]
	v_cvt_pk_bf16_f32 v98, v122, s0
	global_store_short v[96:97], v98, off
	v_cvt_pk_bf16_f32 v98, v106, s0
	global_store_short v[96:97], v98, off offset:64
	v_or_b32_e32 v96, v132, v192
	v_ashrrev_i32_e32 v97, 31, v96
	v_lshlrev_b64 v[96:97], 11, v[96:97]
	v_lshl_add_u64 v[96:97], v[130:131], 0, v[96:97]
	v_cvt_pk_bf16_f32 v98, v123, s0
	global_store_short v[96:97], v98, off
	v_cvt_pk_bf16_f32 v98, v107, s0
	global_store_short v[96:97], v98, off offset:64
	v_or_b32_e32 v96, v132, v193
	v_ashrrev_i32_e32 v97, 31, v96
	v_lshlrev_b64 v[96:97], 11, v[96:97]
	v_lshl_add_u64 v[96:97], v[130:131], 0, v[96:97]
	v_cvt_pk_bf16_f32 v98, v124, s0
	global_store_short v[96:97], v98, off
	v_cvt_pk_bf16_f32 v98, v108, s0
	global_store_short v[96:97], v98, off offset:64
	v_or_b32_e32 v96, v132, v194
	v_ashrrev_i32_e32 v97, 31, v96
	v_lshlrev_b64 v[96:97], 11, v[96:97]
	v_lshl_add_u64 v[96:97], v[130:131], 0, v[96:97]
	v_cvt_pk_bf16_f32 v98, v125, s0
	global_store_short v[96:97], v98, off
	v_cvt_pk_bf16_f32 v98, v109, s0
	global_store_short v[96:97], v98, off offset:64
	v_or_b32_e32 v96, v132, v195
	v_ashrrev_i32_e32 v97, 31, v96
	v_lshlrev_b64 v[96:97], 11, v[96:97]
	v_lshl_add_u64 v[96:97], v[130:131], 0, v[96:97]
	v_cvt_pk_bf16_f32 v98, v126, s0
	global_store_short v[96:97], v98, off
	v_cvt_pk_bf16_f32 v98, v110, s0
	global_store_short v[96:97], v98, off offset:64
	v_or_b32_e32 v96, v132, v196
	v_ashrrev_i32_e32 v97, 31, v96
	v_lshlrev_b64 v[96:97], 11, v[96:97]
	v_lshl_add_u64 v[96:97], v[130:131], 0, v[96:97]
	v_cvt_pk_bf16_f32 v98, v127, s0
	global_store_short v[96:97], v98, off
	v_cvt_pk_bf16_f32 v98, v111, s0
	global_store_short v[96:97], v98, off offset:64
	v_or_b32_e32 v98, 32, v132
	v_or_b32_e32 v96, v98, v181
	v_ashrrev_i32_e32 v97, 31, v96
	v_lshlrev_b64 v[96:97], 11, v[96:97]
	v_lshl_add_u64 v[96:97], v[130:131], 0, v[96:97]
	global_store_short v[96:97], v80, off
	global_store_short v[96:97], v64, off offset:64
	v_or_b32_e32 v96, v98, v182
	v_ashrrev_i32_e32 v97, 31, v96
	v_lshlrev_b64 v[96:97], 11, v[96:97]
	v_lshl_add_u64 v[96:97], v[130:131], 0, v[96:97]
	v_cvt_pk_bf16_f32 v64, v81, s0
	global_store_short v[96:97], v64, off
	v_cvt_pk_bf16_f32 v64, v65, s0
	global_store_short v[96:97], v64, off offset:64
	v_or_b32_e32 v64, v98, v183
	v_ashrrev_i32_e32 v65, 31, v64
	v_lshlrev_b64 v[64:65], 11, v[64:65]
	v_lshl_add_u64 v[64:65], v[130:131], 0, v[64:65]
	v_cvt_pk_bf16_f32 v80, v82, s0
	global_store_short v[64:65], v80, off
	global_store_short v[64:65], v66, off offset:64
	v_or_b32_e32 v64, v98, v184
	v_ashrrev_i32_e32 v65, 31, v64
	v_lshlrev_b64 v[64:65], 11, v[64:65]
	v_lshl_add_u64 v[64:65], v[130:131], 0, v[64:65]
	v_cvt_pk_bf16_f32 v66, v83, s0
	global_store_short v[64:65], v66, off
	v_cvt_pk_bf16_f32 v66, v67, s0
	global_store_short v[64:65], v66, off offset:64
	v_or_b32_e32 v64, v98, v185
	v_ashrrev_i32_e32 v65, 31, v64
	v_lshlrev_b64 v[64:65], 11, v[64:65]
	v_lshl_add_u64 v[64:65], v[130:131], 0, v[64:65]
	v_cvt_pk_bf16_f32 v66, v84, s0
	global_store_short v[64:65], v66, off
	v_cvt_pk_bf16_f32 v66, v68, s0
	global_store_short v[64:65], v66, off offset:64
	v_or_b32_e32 v64, v98, v186
	v_ashrrev_i32_e32 v65, 31, v64
	v_lshlrev_b64 v[64:65], 11, v[64:65]
	v_lshl_add_u64 v[64:65], v[130:131], 0, v[64:65]
	v_cvt_pk_bf16_f32 v66, v85, s0
	global_store_short v[64:65], v66, off
	v_cvt_pk_bf16_f32 v66, v69, s0
	global_store_short v[64:65], v66, off offset:64
	v_or_b32_e32 v64, v98, v187
	v_ashrrev_i32_e32 v65, 31, v64
	v_lshlrev_b64 v[64:65], 11, v[64:65]
	v_lshl_add_u64 v[64:65], v[130:131], 0, v[64:65]
	v_cvt_pk_bf16_f32 v66, v86, s0
	global_store_short v[64:65], v66, off
	v_cvt_pk_bf16_f32 v66, v70, s0
	global_store_short v[64:65], v66, off offset:64
	v_or_b32_e32 v64, v98, v188
	v_ashrrev_i32_e32 v65, 31, v64
	v_lshlrev_b64 v[64:65], 11, v[64:65]
	v_lshl_add_u64 v[64:65], v[130:131], 0, v[64:65]
	v_cvt_pk_bf16_f32 v66, v87, s0
	global_store_short v[64:65], v66, off
	v_cvt_pk_bf16_f32 v66, v71, s0
	global_store_short v[64:65], v66, off offset:64
	v_or_b32_e32 v64, v98, v189
	v_ashrrev_i32_e32 v65, 31, v64
	v_lshlrev_b64 v[64:65], 11, v[64:65]
	v_lshl_add_u64 v[64:65], v[130:131], 0, v[64:65]
	v_cvt_pk_bf16_f32 v66, v88, s0
	global_store_short v[64:65], v66, off
	v_cvt_pk_bf16_f32 v66, v72, s0
	global_store_short v[64:65], v66, off offset:64
	v_or_b32_e32 v64, v98, v190
	v_ashrrev_i32_e32 v65, 31, v64
	v_lshlrev_b64 v[64:65], 11, v[64:65]
	v_lshl_add_u64 v[64:65], v[130:131], 0, v[64:65]
	v_cvt_pk_bf16_f32 v66, v89, s0
	global_store_short v[64:65], v66, off
	v_cvt_pk_bf16_f32 v66, v73, s0
	global_store_short v[64:65], v66, off offset:64
	v_or_b32_e32 v64, v98, v191
	v_ashrrev_i32_e32 v65, 31, v64
	v_lshlrev_b64 v[64:65], 11, v[64:65]
	v_lshl_add_u64 v[64:65], v[130:131], 0, v[64:65]
	v_cvt_pk_bf16_f32 v66, v90, s0
	global_store_short v[64:65], v66, off
	v_cvt_pk_bf16_f32 v66, v74, s0
	global_store_short v[64:65], v66, off offset:64
	v_or_b32_e32 v64, v98, v192
	v_ashrrev_i32_e32 v65, 31, v64
	v_lshlrev_b64 v[64:65], 11, v[64:65]
	v_lshl_add_u64 v[64:65], v[130:131], 0, v[64:65]
	v_cvt_pk_bf16_f32 v66, v91, s0
	global_store_short v[64:65], v66, off
	v_cvt_pk_bf16_f32 v66, v75, s0
	global_store_short v[64:65], v66, off offset:64
	v_or_b32_e32 v64, v98, v193
	v_ashrrev_i32_e32 v65, 31, v64
	v_lshlrev_b64 v[64:65], 11, v[64:65]
	v_lshl_add_u64 v[64:65], v[130:131], 0, v[64:65]
	v_cvt_pk_bf16_f32 v66, v92, s0
	global_store_short v[64:65], v66, off
	v_cvt_pk_bf16_f32 v66, v76, s0
	global_store_short v[64:65], v66, off offset:64
	v_or_b32_e32 v64, v98, v194
	v_ashrrev_i32_e32 v65, 31, v64
	v_lshlrev_b64 v[64:65], 11, v[64:65]
	v_lshl_add_u64 v[64:65], v[130:131], 0, v[64:65]
	v_cvt_pk_bf16_f32 v66, v93, s0
	global_store_short v[64:65], v66, off
	v_cvt_pk_bf16_f32 v66, v77, s0
	global_store_short v[64:65], v66, off offset:64
	v_or_b32_e32 v64, v98, v195
	v_ashrrev_i32_e32 v65, 31, v64
	v_lshlrev_b64 v[64:65], 11, v[64:65]
	v_lshl_add_u64 v[64:65], v[130:131], 0, v[64:65]
	v_cvt_pk_bf16_f32 v66, v94, s0
	global_store_short v[64:65], v66, off
	v_cvt_pk_bf16_f32 v66, v78, s0
	global_store_short v[64:65], v66, off offset:64
	v_or_b32_e32 v64, v98, v196
	v_ashrrev_i32_e32 v65, 31, v64
	v_lshlrev_b64 v[64:65], 11, v[64:65]
	v_lshl_add_u64 v[64:65], v[130:131], 0, v[64:65]
	v_cvt_pk_bf16_f32 v66, v95, s0
	global_store_short v[64:65], v66, off
	v_cvt_pk_bf16_f32 v66, v79, s0
	global_store_short v[64:65], v66, off offset:64
	v_or_b32_e32 v66, 64, v132
	v_or_b32_e32 v64, v66, v181
	v_ashrrev_i32_e32 v65, 31, v64
	v_lshlrev_b64 v[64:65], 11, v[64:65]
	v_lshl_add_u64 v[64:65], v[130:131], 0, v[64:65]
	v_cvt_pk_bf16_f32 v32, v32, s0
	global_store_short v[64:65], v48, off
	global_store_short v[64:65], v32, off offset:64
	v_or_b32_e32 v64, v66, v182
	v_ashrrev_i32_e32 v65, 31, v64
	v_lshlrev_b64 v[64:65], 11, v[64:65]
	v_lshl_add_u64 v[64:65], v[130:131], 0, v[64:65]
	v_cvt_pk_bf16_f32 v32, v49, s0
	global_store_short v[64:65], v32, off
	v_cvt_pk_bf16_f32 v32, v33, s0
	global_store_short v[64:65], v32, off offset:64
	v_or_b32_e32 v32, v66, v183
	v_ashrrev_i32_e32 v33, 31, v32
	v_lshlrev_b64 v[32:33], 11, v[32:33]
	v_lshl_add_u64 v[32:33], v[130:131], 0, v[32:33]
	v_cvt_pk_bf16_f32 v48, v50, s0
	v_cvt_pk_bf16_f32 v34, v34, s0
	global_store_short v[32:33], v48, off
	global_store_short v[32:33], v34, off offset:64
	v_or_b32_e32 v32, v66, v184
	v_ashrrev_i32_e32 v33, 31, v32
	v_lshlrev_b64 v[32:33], 11, v[32:33]
	v_lshl_add_u64 v[32:33], v[130:131], 0, v[32:33]
	v_cvt_pk_bf16_f32 v34, v51, s0
	global_store_short v[32:33], v34, off
	v_cvt_pk_bf16_f32 v34, v35, s0
	global_store_short v[32:33], v34, off offset:64
	v_or_b32_e32 v32, v66, v185
	v_ashrrev_i32_e32 v33, 31, v32
	v_lshlrev_b64 v[32:33], 11, v[32:33]
	v_lshl_add_u64 v[32:33], v[130:131], 0, v[32:33]
	v_cvt_pk_bf16_f32 v34, v52, s0
	global_store_short v[32:33], v34, off
	v_cvt_pk_bf16_f32 v34, v36, s0
	global_store_short v[32:33], v34, off offset:64
	v_or_b32_e32 v32, v66, v186
	v_ashrrev_i32_e32 v33, 31, v32
	v_lshlrev_b64 v[32:33], 11, v[32:33]
	v_lshl_add_u64 v[32:33], v[130:131], 0, v[32:33]
	v_cvt_pk_bf16_f32 v34, v53, s0
	global_store_short v[32:33], v34, off
	v_cvt_pk_bf16_f32 v34, v37, s0
	global_store_short v[32:33], v34, off offset:64
	v_or_b32_e32 v32, v66, v187
	v_ashrrev_i32_e32 v33, 31, v32
	v_lshlrev_b64 v[32:33], 11, v[32:33]
	v_lshl_add_u64 v[32:33], v[130:131], 0, v[32:33]
	v_cvt_pk_bf16_f32 v34, v54, s0
	global_store_short v[32:33], v34, off
	v_cvt_pk_bf16_f32 v34, v38, s0
	global_store_short v[32:33], v34, off offset:64
	v_or_b32_e32 v32, v66, v188
	v_ashrrev_i32_e32 v33, 31, v32
	v_lshlrev_b64 v[32:33], 11, v[32:33]
	v_lshl_add_u64 v[32:33], v[130:131], 0, v[32:33]
	v_cvt_pk_bf16_f32 v34, v55, s0
	global_store_short v[32:33], v34, off
	v_cvt_pk_bf16_f32 v34, v39, s0
	global_store_short v[32:33], v34, off offset:64
	v_or_b32_e32 v32, v66, v189
	v_ashrrev_i32_e32 v33, 31, v32
	v_lshlrev_b64 v[32:33], 11, v[32:33]
	v_lshl_add_u64 v[32:33], v[130:131], 0, v[32:33]
	v_cvt_pk_bf16_f32 v34, v56, s0
	global_store_short v[32:33], v34, off
	v_cvt_pk_bf16_f32 v34, v40, s0
	global_store_short v[32:33], v34, off offset:64
	v_or_b32_e32 v32, v66, v190
	v_ashrrev_i32_e32 v33, 31, v32
	v_lshlrev_b64 v[32:33], 11, v[32:33]
	v_lshl_add_u64 v[32:33], v[130:131], 0, v[32:33]
	v_cvt_pk_bf16_f32 v34, v57, s0
	global_store_short v[32:33], v34, off
	v_cvt_pk_bf16_f32 v34, v41, s0
	global_store_short v[32:33], v34, off offset:64
	v_or_b32_e32 v32, v66, v191
	v_ashrrev_i32_e32 v33, 31, v32
	v_lshlrev_b64 v[32:33], 11, v[32:33]
	v_lshl_add_u64 v[32:33], v[130:131], 0, v[32:33]
	v_cvt_pk_bf16_f32 v34, v58, s0
	global_store_short v[32:33], v34, off
	v_cvt_pk_bf16_f32 v34, v42, s0
	global_store_short v[32:33], v34, off offset:64
	v_or_b32_e32 v32, v66, v192
	v_ashrrev_i32_e32 v33, 31, v32
	v_lshlrev_b64 v[32:33], 11, v[32:33]
	v_lshl_add_u64 v[32:33], v[130:131], 0, v[32:33]
	v_cvt_pk_bf16_f32 v34, v59, s0
	global_store_short v[32:33], v34, off
	v_cvt_pk_bf16_f32 v34, v43, s0
	global_store_short v[32:33], v34, off offset:64
	v_or_b32_e32 v32, v66, v193
	v_ashrrev_i32_e32 v33, 31, v32
	v_lshlrev_b64 v[32:33], 11, v[32:33]
	v_lshl_add_u64 v[32:33], v[130:131], 0, v[32:33]
	v_cvt_pk_bf16_f32 v34, v60, s0
	global_store_short v[32:33], v34, off
	v_cvt_pk_bf16_f32 v34, v44, s0
	global_store_short v[32:33], v34, off offset:64
	v_or_b32_e32 v32, v66, v194
	v_ashrrev_i32_e32 v33, 31, v32
	v_lshlrev_b64 v[32:33], 11, v[32:33]
	v_lshl_add_u64 v[32:33], v[130:131], 0, v[32:33]
	v_cvt_pk_bf16_f32 v34, v61, s0
	global_store_short v[32:33], v34, off
	v_cvt_pk_bf16_f32 v34, v45, s0
	global_store_short v[32:33], v34, off offset:64
	v_or_b32_e32 v32, v66, v195
	v_ashrrev_i32_e32 v33, 31, v32
	v_lshlrev_b64 v[32:33], 11, v[32:33]
	v_lshl_add_u64 v[32:33], v[130:131], 0, v[32:33]
	v_cvt_pk_bf16_f32 v34, v62, s0
	global_store_short v[32:33], v34, off
	v_cvt_pk_bf16_f32 v34, v46, s0
	global_store_short v[32:33], v34, off offset:64
	v_or_b32_e32 v32, v66, v196
	v_ashrrev_i32_e32 v33, 31, v32
	v_lshlrev_b64 v[32:33], 11, v[32:33]
	v_lshl_add_u64 v[32:33], v[130:131], 0, v[32:33]
	v_cvt_pk_bf16_f32 v34, v63, s0
	global_store_short v[32:33], v34, off
	v_cvt_pk_bf16_f32 v34, v47, s0
	global_store_short v[32:33], v34, off offset:64
	v_or_b32_e32 v34, 0x60, v132
	v_or_b32_e32 v32, v34, v181
	v_ashrrev_i32_e32 v33, 31, v32
	v_lshlrev_b64 v[32:33], 11, v[32:33]
	v_lshl_add_u64 v[32:33], v[130:131], 0, v[32:33]
	v_cvt_pk_bf16_f32 v0, v0, s0
	global_store_short v[32:33], v16, off
	global_store_short v[32:33], v0, off offset:64
	v_or_b32_e32 v32, v34, v182
	v_ashrrev_i32_e32 v33, 31, v32
	v_lshlrev_b64 v[32:33], 11, v[32:33]
	v_lshl_add_u64 v[32:33], v[130:131], 0, v[32:33]
	v_cvt_pk_bf16_f32 v0, v17, s0
	global_store_short v[32:33], v0, off
	v_cvt_pk_bf16_f32 v0, v1, s0
	global_store_short v[32:33], v0, off offset:64
	v_or_b32_e32 v0, v34, v183
	v_ashrrev_i32_e32 v1, 31, v0
	v_lshlrev_b64 v[0:1], 11, v[0:1]
	v_lshl_add_u64 v[0:1], v[130:131], 0, v[0:1]
	v_cvt_pk_bf16_f32 v16, v18, s0
	v_cvt_pk_bf16_f32 v2, v2, s0
	global_store_short v[0:1], v16, off
	global_store_short v[0:1], v2, off offset:64
	v_or_b32_e32 v0, v34, v184
	v_ashrrev_i32_e32 v1, 31, v0
	v_lshlrev_b64 v[0:1], 11, v[0:1]
	v_lshl_add_u64 v[0:1], v[130:131], 0, v[0:1]
	v_cvt_pk_bf16_f32 v2, v19, s0
	global_store_short v[0:1], v2, off
	v_cvt_pk_bf16_f32 v2, v3, s0
	global_store_short v[0:1], v2, off offset:64
	v_or_b32_e32 v0, v34, v185
	v_ashrrev_i32_e32 v1, 31, v0
	v_lshlrev_b64 v[0:1], 11, v[0:1]
	v_lshl_add_u64 v[0:1], v[130:131], 0, v[0:1]
	v_cvt_pk_bf16_f32 v2, v20, s0
	global_store_short v[0:1], v2, off
	v_cvt_pk_bf16_f32 v2, v4, s0
	global_store_short v[0:1], v2, off offset:64
	v_or_b32_e32 v0, v34, v186
	v_ashrrev_i32_e32 v1, 31, v0
	v_lshlrev_b64 v[0:1], 11, v[0:1]
	v_lshl_add_u64 v[0:1], v[130:131], 0, v[0:1]
	v_cvt_pk_bf16_f32 v2, v21, s0
	global_store_short v[0:1], v2, off
	v_cvt_pk_bf16_f32 v2, v5, s0
	global_store_short v[0:1], v2, off offset:64
	v_or_b32_e32 v0, v34, v187
	v_ashrrev_i32_e32 v1, 31, v0
	v_lshlrev_b64 v[0:1], 11, v[0:1]
	v_lshl_add_u64 v[0:1], v[130:131], 0, v[0:1]
	v_cvt_pk_bf16_f32 v2, v22, s0
	global_store_short v[0:1], v2, off
	v_cvt_pk_bf16_f32 v2, v6, s0
	global_store_short v[0:1], v2, off offset:64
	v_or_b32_e32 v0, v34, v188
	v_ashrrev_i32_e32 v1, 31, v0
	v_lshlrev_b64 v[0:1], 11, v[0:1]
	v_lshl_add_u64 v[0:1], v[130:131], 0, v[0:1]
	v_cvt_pk_bf16_f32 v2, v23, s0
	global_store_short v[0:1], v2, off
	v_cvt_pk_bf16_f32 v2, v7, s0
	global_store_short v[0:1], v2, off offset:64
	v_or_b32_e32 v0, v34, v189
	v_ashrrev_i32_e32 v1, 31, v0
	v_lshlrev_b64 v[0:1], 11, v[0:1]
	v_lshl_add_u64 v[0:1], v[130:131], 0, v[0:1]
	v_cvt_pk_bf16_f32 v2, v24, s0
	global_store_short v[0:1], v2, off
	v_cvt_pk_bf16_f32 v2, v8, s0
	global_store_short v[0:1], v2, off offset:64
	v_or_b32_e32 v0, v34, v190
	v_ashrrev_i32_e32 v1, 31, v0
	v_lshlrev_b64 v[0:1], 11, v[0:1]
	v_lshl_add_u64 v[0:1], v[130:131], 0, v[0:1]
	v_cvt_pk_bf16_f32 v2, v25, s0
	global_store_short v[0:1], v2, off
	v_cvt_pk_bf16_f32 v2, v9, s0
	global_store_short v[0:1], v2, off offset:64
	v_or_b32_e32 v0, v34, v191
	v_ashrrev_i32_e32 v1, 31, v0
	v_lshlrev_b64 v[0:1], 11, v[0:1]
	v_lshl_add_u64 v[0:1], v[130:131], 0, v[0:1]
	v_cvt_pk_bf16_f32 v2, v26, s0
	global_store_short v[0:1], v2, off
	v_cvt_pk_bf16_f32 v2, v10, s0
	global_store_short v[0:1], v2, off offset:64
	v_or_b32_e32 v0, v34, v192
	v_ashrrev_i32_e32 v1, 31, v0
	v_lshlrev_b64 v[0:1], 11, v[0:1]
	v_lshl_add_u64 v[0:1], v[130:131], 0, v[0:1]
	v_cvt_pk_bf16_f32 v2, v27, s0
	global_store_short v[0:1], v2, off
	v_cvt_pk_bf16_f32 v2, v11, s0
	global_store_short v[0:1], v2, off offset:64
	v_or_b32_e32 v0, v34, v193
	v_ashrrev_i32_e32 v1, 31, v0
	v_lshlrev_b64 v[0:1], 11, v[0:1]
	v_lshl_add_u64 v[0:1], v[130:131], 0, v[0:1]
	v_cvt_pk_bf16_f32 v2, v28, s0
	global_store_short v[0:1], v2, off
	v_cvt_pk_bf16_f32 v2, v12, s0
	global_store_short v[0:1], v2, off offset:64
	v_or_b32_e32 v0, v34, v194
	v_ashrrev_i32_e32 v1, 31, v0
	v_lshlrev_b64 v[0:1], 11, v[0:1]
	v_lshl_add_u64 v[0:1], v[130:131], 0, v[0:1]
	v_cvt_pk_bf16_f32 v2, v29, s0
	global_store_short v[0:1], v2, off
	v_cvt_pk_bf16_f32 v2, v13, s0
	global_store_short v[0:1], v2, off offset:64
	v_or_b32_e32 v0, v34, v195
	v_ashrrev_i32_e32 v1, 31, v0
	v_lshlrev_b64 v[0:1], 11, v[0:1]
	v_lshl_add_u64 v[0:1], v[130:131], 0, v[0:1]
	v_cvt_pk_bf16_f32 v2, v30, s0
	global_store_short v[0:1], v2, off
	v_cvt_pk_bf16_f32 v2, v14, s0
	global_store_short v[0:1], v2, off offset:64
	v_or_b32_e32 v0, v34, v196
	v_ashrrev_i32_e32 v1, 31, v0
	v_lshlrev_b64 v[0:1], 11, v[0:1]
	v_lshl_add_u64 v[0:1], v[130:131], 0, v[0:1]
	v_cvt_pk_bf16_f32 v2, v31, s0
	global_store_short v[0:1], v2, off
	v_cvt_pk_bf16_f32 v2, v15, s0
	global_store_short v[0:1], v2, off offset:64
	s_cbranch_scc0 .LBB0_262

.LBB0_330:
	s_and_b32 s3, s2, 0x18000
	v_add_u32_e32 v128, s3, v182
	s_add_i32 s3, s2, 0xfffe8000
	s_and_b32 s3, s3, 0x18000
	v_or_b32_e32 v214, s3, v181
	v_add_u32_e32 v215, s3, v178
	s_waitcnt vmcnt(8) lgkmcnt(0)
	s_barrier
	v_mfma_f32_32x32x16_bf16 v[112:127], v[150:153], v[142:145], v[112:127]
	v_mfma_f32_32x32x16_bf16 v[96:111], v[150:153], v[130:133], v[96:111]
	v_add_u32_e32 v194, v214, v179
	v_add_u32_e32 v210, v215, v179
	ds_read_b128 v[190:193], v194 offset:16384
	ds_read_b128 v[194:197], v194 offset:18432
	ds_read_b128 v[198:201], v210
	ds_read_b128 v[202:205], v210 offset:2048
	ds_read_b128 v[206:209], v210 offset:4096
	ds_read_b128 v[210:213], v210 offset:6144
	v_mfma_f32_32x32x16_bf16 v[80:95], v[146:149], v[142:145], v[80:95]
	v_mfma_f32_32x32x16_bf16 v[64:79], v[146:149], v[130:133], v[64:79]
	v_readfirstlane_b32 s3, v128
	s_mov_b32 m0, s3
	s_nop 0
	global_load_lds_dwordx4 v[172:173], off
	v_mfma_f32_32x32x16_bf16 v[48:63], v[138:141], v[142:145], v[48:63]
	v_mfma_f32_32x32x16_bf16 v[32:47], v[138:141], v[130:133], v[32:47]
	s_add_i32 s24, s3, 0x2000
	v_lshl_add_u64 v[150:151], v[172:173], 0, s[26:27]
	s_mov_b32 m0, s24
	s_nop 0
	global_load_lds_dwordx4 v[150:151], off
	v_mfma_f32_32x32x16_bf16 v[16:31], v[134:137], v[142:145], v[16:31]
	v_mfma_f32_32x32x16_bf16 v[0:15], v[134:137], v[130:133], v[0:15]
	v_add_u32_e32 v128, v214, v180
	ds_read_b128 v[142:145], v128 offset:16384
	ds_read_b128 v[130:133], v128 offset:18432
	v_add_u32_e32 v128, v215, v180
	ds_read_b128 v[150:153], v128
	ds_read_b128 v[146:149], v128 offset:2048
	ds_read_b128 v[138:141], v128 offset:4096
	ds_read_b128 v[134:137], v128 offset:6144
	s_waitcnt lgkmcnt(9)
	v_mfma_f32_32x32x16_bf16 v[112:127], v[198:201], v[190:193], v[112:127]
	s_add_i32 s24, s3, 0x6000
	s_addk_i32 s3, 0x4000
	v_mfma_f32_32x32x16_bf16 v[96:111], v[198:201], v[194:197], v[96:111]
	s_mov_b32 m0, s3
	s_nop 0
	global_load_lds_dwordx4 v[174:175], off
	v_lshl_add_u64 v[214:215], v[174:175], 0, s[26:27]
	s_waitcnt lgkmcnt(8)
	v_mfma_f32_32x32x16_bf16 v[80:95], v[202:205], v[190:193], v[80:95]
	v_mfma_f32_32x32x16_bf16 v[64:79], v[202:205], v[194:197], v[64:79]
	s_waitcnt lgkmcnt(7)
	v_mfma_f32_32x32x16_bf16 v[48:63], v[206:209], v[190:193], v[48:63]
	v_mfma_f32_32x32x16_bf16 v[32:47], v[206:209], v[194:197], v[32:47]
	s_mov_b32 m0, s24
	s_nop 0
	global_load_lds_dwordx4 v[214:215], off
	s_waitcnt lgkmcnt(6)
	v_mfma_f32_32x32x16_bf16 v[16:31], v[210:213], v[190:193], v[16:31]
	s_add_i32 s2, s2, 0x8000
	v_lshl_add_u64 v[172:173], v[172:173], 0, 64
	v_lshl_add_u64 v[174:175], v[174:175], 0, 64
	s_cmp_eq_u32 s2, 0x100000
	v_mfma_f32_32x32x16_bf16 v[0:15], v[210:213], v[194:197], v[0:15]
	s_cbranch_scc0 .LBB0_330
	s_waitcnt vmcnt(8) lgkmcnt(0)
	s_barrier
	v_add_u32_e32 v128, v181, v179
	ds_read_b128 v[172:175], v128 offset:49152
	ds_read_b128 v[190:193], v128 offset:51200
	v_add_u32_e32 v128, v178, v179
	ds_read_b128 v[194:197], v128 offset:32768
	ds_read_b128 v[198:201], v128 offset:34816
	ds_read_b128 v[202:205], v128 offset:36864
	ds_read_b128 v[206:209], v128 offset:38912
	s_waitcnt lgkmcnt(9)
	v_mfma_f32_32x32x16_bf16 v[112:127], v[150:153], v[142:145], v[112:127]
	v_mfma_f32_32x32x16_bf16 v[96:111], v[150:153], v[130:133], v[96:111]
	s_waitcnt lgkmcnt(8)
	v_mfma_f32_32x32x16_bf16 v[80:95], v[146:149], v[142:145], v[80:95]
	v_mfma_f32_32x32x16_bf16 v[64:79], v[146:149], v[130:133], v[64:79]
	s_waitcnt lgkmcnt(7)
	v_mfma_f32_32x32x16_bf16 v[48:63], v[138:141], v[142:145], v[48:63]
	v_mfma_f32_32x32x16_bf16 v[32:47], v[138:141], v[130:133], v[32:47]
	s_waitcnt lgkmcnt(6)
	v_mfma_f32_32x32x16_bf16 v[16:31], v[134:137], v[142:145], v[16:31]
	v_mfma_f32_32x32x16_bf16 v[0:15], v[134:137], v[130:133], v[0:15]
	v_add_u32_e32 v128, v181, v180
	ds_read_b128 v[130:133], v128 offset:49152
	ds_read_b128 v[134:137], v128 offset:51200
	v_add_u32_e32 v128, v178, v180
	ds_read_b128 v[138:141], v128 offset:32768
	ds_read_b128 v[142:145], v128 offset:34816
	ds_read_b128 v[146:149], v128 offset:36864
	ds_read_b128 v[150:153], v128 offset:38912
	s_waitcnt lgkmcnt(9)
	v_mfma_f32_32x32x16_bf16 v[112:127], v[194:197], v[172:175], v[112:127]
	v_mfma_f32_32x32x16_bf16 v[96:111], v[194:197], v[190:193], v[96:111]
	s_waitcnt lgkmcnt(8)
	v_mfma_f32_32x32x16_bf16 v[80:95], v[198:201], v[172:175], v[80:95]
	v_mfma_f32_32x32x16_bf16 v[64:79], v[198:201], v[190:193], v[64:79]
	s_waitcnt lgkmcnt(7)
	v_mfma_f32_32x32x16_bf16 v[48:63], v[202:205], v[172:175], v[48:63]
	v_mfma_f32_32x32x16_bf16 v[32:47], v[202:205], v[190:193], v[32:47]
	s_waitcnt vmcnt(4) lgkmcnt(0)
	s_barrier
	v_add_u32_e32 v128, v187, v179
	s_waitcnt lgkmcnt(6)
	v_mfma_f32_32x32x16_bf16 v[16:31], v[206:209], v[172:175], v[16:31]
	v_mfma_f32_32x32x16_bf16 v[0:15], v[206:209], v[190:193], v[0:15]
	ds_read_b128 v[172:175], v128 offset:16384
	ds_read_b128 v[190:193], v128 offset:18432
	v_add_u32_e32 v128, v188, v179
	ds_read_b128 v[194:197], v128
	ds_read_b128 v[198:201], v128 offset:2048
	ds_read_b128 v[202:205], v128 offset:4096
	ds_read_b128 v[206:209], v128 offset:6144
	s_waitcnt lgkmcnt(9)
	v_mfma_f32_32x32x16_bf16 v[112:127], v[138:141], v[130:133], v[112:127]
	v_mfma_f32_32x32x16_bf16 v[96:111], v[138:141], v[134:137], v[96:111]
	s_waitcnt lgkmcnt(8)
	v_mfma_f32_32x32x16_bf16 v[80:95], v[142:145], v[130:133], v[80:95]
	v_mfma_f32_32x32x16_bf16 v[64:79], v[142:145], v[134:137], v[64:79]
	s_waitcnt lgkmcnt(7)
	v_mfma_f32_32x32x16_bf16 v[48:63], v[146:149], v[130:133], v[48:63]
	v_mfma_f32_32x32x16_bf16 v[32:47], v[146:149], v[134:137], v[32:47]
	s_waitcnt lgkmcnt(6)
	v_mfma_f32_32x32x16_bf16 v[16:31], v[150:153], v[130:133], v[16:31]
	v_mfma_f32_32x32x16_bf16 v[0:15], v[150:153], v[134:137], v[0:15]
	v_add_u32_e32 v128, v187, v180
	ds_read_b128 v[130:133], v128 offset:16384
	ds_read_b128 v[134:137], v128 offset:18432
	v_add_u32_e32 v128, v188, v180
	ds_read_b128 v[138:141], v128
	ds_read_b128 v[142:145], v128 offset:2048
	ds_read_b128 v[146:149], v128 offset:4096
	ds_read_b128 v[150:153], v128 offset:6144
	s_waitcnt lgkmcnt(9)
	v_mfma_f32_32x32x16_bf16 v[112:127], v[194:197], v[172:175], v[112:127]
	v_mfma_f32_32x32x16_bf16 v[96:111], v[194:197], v[190:193], v[96:111]
	s_waitcnt lgkmcnt(8)
	v_mfma_f32_32x32x16_bf16 v[80:95], v[198:201], v[172:175], v[80:95]
	v_mfma_f32_32x32x16_bf16 v[64:79], v[198:201], v[190:193], v[64:79]
	s_waitcnt lgkmcnt(7)
	v_mfma_f32_32x32x16_bf16 v[48:63], v[202:205], v[172:175], v[48:63]
	v_mfma_f32_32x32x16_bf16 v[32:47], v[202:205], v[190:193], v[32:47]
	s_waitcnt vmcnt(0) lgkmcnt(0)
	s_barrier
	v_add_u32_e32 v128, v185, v179
	s_waitcnt lgkmcnt(6)
	v_mfma_f32_32x32x16_bf16 v[16:31], v[206:209], v[172:175], v[16:31]
	v_mfma_f32_32x32x16_bf16 v[0:15], v[206:209], v[190:193], v[0:15]
	ds_read_b128 v[172:175], v128 offset:16384
	ds_read_b128 v[190:193], v128 offset:18432
	v_add_u32_e32 v128, v186, v179
	ds_read_b128 v[194:197], v128
	ds_read_b128 v[198:201], v128 offset:2048
	ds_read_b128 v[202:205], v128 offset:4096
	ds_read_b128 v[206:209], v128 offset:6144
	s_waitcnt lgkmcnt(9)
	v_mfma_f32_32x32x16_bf16 v[112:127], v[138:141], v[130:133], v[112:127]
	v_mfma_f32_32x32x16_bf16 v[96:111], v[138:141], v[134:137], v[96:111]
	s_waitcnt lgkmcnt(8)
	v_mfma_f32_32x32x16_bf16 v[80:95], v[142:145], v[130:133], v[80:95]
	v_mfma_f32_32x32x16_bf16 v[64:79], v[142:145], v[134:137], v[64:79]
	s_waitcnt lgkmcnt(7)
	v_mfma_f32_32x32x16_bf16 v[48:63], v[146:149], v[130:133], v[48:63]
	v_mfma_f32_32x32x16_bf16 v[32:47], v[146:149], v[134:137], v[32:47]
	s_waitcnt lgkmcnt(6)
	v_mfma_f32_32x32x16_bf16 v[16:31], v[150:153], v[130:133], v[16:31]
	v_mfma_f32_32x32x16_bf16 v[0:15], v[150:153], v[134:137], v[0:15]
	v_add_u32_e32 v128, v185, v180
	ds_read_b128 v[130:133], v128 offset:16384
	ds_read_b128 v[138:141], v128 offset:18432
	v_add_u32_e32 v128, v186, v180
	ds_read_b128 v[134:137], v128
	ds_read_b128 v[142:145], v128 offset:2048
	ds_read_b128 v[146:149], v128 offset:4096
	ds_read_b128 v[210:213], v128 offset:6144
	s_waitcnt lgkmcnt(9)
	v_mfma_f32_32x32x16_bf16 v[112:127], v[194:197], v[172:175], v[112:127]
	v_mfma_f32_32x32x16_bf16 v[96:111], v[194:197], v[190:193], v[96:111]
	s_waitcnt lgkmcnt(8)
	v_mfma_f32_32x32x16_bf16 v[80:95], v[198:201], v[172:175], v[80:95]
	v_mfma_f32_32x32x16_bf16 v[64:79], v[198:201], v[190:193], v[64:79]
	s_waitcnt lgkmcnt(7)
	v_mfma_f32_32x32x16_bf16 v[48:63], v[202:205], v[172:175], v[48:63]
	v_mfma_f32_32x32x16_bf16 v[32:47], v[202:205], v[190:193], v[32:47]
	s_waitcnt lgkmcnt(6)
	v_mfma_f32_32x32x16_bf16 v[16:31], v[206:209], v[172:175], v[16:31]
	v_add_u32_e32 v150, s0, v157
	s_movk_i32 s2, 0x2000
	s_movk_i32 s0, 0x1fff
	v_cmp_gt_i32_e32 vcc, s2, v150
	s_movk_i32 s2, 0x7ff
	v_mfma_f32_32x32x16_bf16 v[0:15], v[206:209], v[190:193], v[0:15]
	s_waitcnt lgkmcnt(3)
	v_mfma_f32_32x32x16_bf16 v[112:127], v[134:137], v[130:133], v[112:127]
	v_mfma_f32_32x32x16_bf16 v[96:111], v[134:137], v[138:141], v[96:111]
	v_or_b32_e32 v136, s1, v176
	v_cmp_lt_i32_e64 s[0:1], s0, v150
	v_cmp_lt_i32_e64 s[2:3], s2, v136
	s_waitcnt lgkmcnt(2)
	v_mfma_f32_32x32x16_bf16 v[80:95], v[142:145], v[130:133], v[80:95]
	v_mfma_f32_32x32x16_bf16 v[64:79], v[142:145], v[138:141], v[64:79]
	s_waitcnt lgkmcnt(1)
	v_mfma_f32_32x32x16_bf16 v[48:63], v[146:149], v[130:133], v[48:63]
	v_mfma_f32_32x32x16_bf16 v[32:47], v[146:149], v[138:141], v[32:47]
	s_waitcnt lgkmcnt(0)
	v_mfma_f32_32x32x16_bf16 v[16:31], v[210:213], v[130:133], v[16:31]
	v_or_b32_e32 v130, v150, v183
	v_mfma_f32_32x32x16_bf16 v[0:15], v[210:213], v[138:141], v[0:15]
	s_and_saveexec_b64 s[24:25], s[2:3]
	s_xor_b64 s[2:3], exec, s[24:25]
	s_cbranch_execz .LBB0_461
	v_ashrrev_i32_e32 v134, 8, v150
	v_ashrrev_i32_e32 v135, 31, v134
	s_and_saveexec_b64 s[24:25], vcc
	s_xor_b64 s[24:25], exec, s[24:25]
	v_lshlrev_b64 v[140:141], 18, v[134:135]
	v_and_b32_e32 v128, 0x84, v130
	s_or_saveexec_b64 s[24:25], s[24:25]
	v_mov_b64_e32 v[138:139], 0x100
	s_xor_b64 exec, exec, s[24:25]
	v_add_u32_e32 v128, 0xffffe000, v150
	v_lshrrev_b32_e32 v128, 11, v128
	s_mov_b32 s26, 0x240000
	v_mad_u64_u32 v[140:141], s[26:27], v128, s26, v[166:167]
	v_and_b32_e32 v128, 0x784, v130
	v_add_u32_e32 v128, 0x100, v128
	v_mov_b64_e32 v[138:139], 0x900
	s_or_b64 exec, exec, s[24:25]
	v_add_u32_e32 v132, v136, v184
	v_or_b32_e32 v142, 1, v130
	v_or_b32_e32 v144, 2, v130
	v_or_b32_e32 v146, 3, v130
	v_lshl_add_u64 v[140:141], v[140:141], 1, s[6:7]
	v_mad_u64_u32 v[152:153], s[24:25], v138, v132, 0
	v_ashrrev_i32_e32 v131, 31, v130
	v_ashrrev_i32_e32 v143, 31, v142
	v_ashrrev_i32_e32 v145, 31, v144
	v_ashrrev_i32_e32 v147, 31, v146
	v_lshl_add_u64 v[152:153], v[152:153], 1, v[140:141]
	v_lshlrev_b64 v[136:137], 12, v[130:131]
	v_lshlrev_b64 v[142:143], 12, v[142:143]
	v_lshlrev_b64 v[144:145], 12, v[144:145]
	v_lshlrev_b64 v[146:147], 12, v[146:147]
	v_cvt_pk_bf16_f32 v148, v112, v113
	v_cvt_pk_bf16_f32 v149, v114, v115
	v_mov_b32_e32 v133, v129
	v_lshl_add_u64 v[152:153], v[128:129], 1, v[152:153]
	global_store_dwordx2 v[152:153], v[148:149], off
	v_lshl_add_u64 v[148:149], s[18:19], 0, v[136:137]
	v_lshlrev_b64 v[136:137], 2, v[132:133]
	v_lshl_add_u64 v[152:153], s[18:19], 0, v[142:143]
	v_lshl_add_u64 v[172:173], s[18:19], 0, v[144:145]
	v_lshl_add_u64 v[174:175], s[18:19], 0, v[146:147]
	v_lshl_add_u64 v[142:143], v[148:149], 0, v[136:137]
	v_lshl_add_u64 v[144:145], v[152:153], 0, v[136:137]
	v_lshl_add_u64 v[146:147], v[172:173], 0, v[136:137]
	v_lshl_add_u64 v[148:149], v[174:175], 0, v[136:137]
	s_and_saveexec_b64 s[24:25], vcc
	s_cbranch_execz .LBB0_338
	global_store_dword v[142:143], v112, off nt
	global_store_dword v[144:145], v113, off nt
	global_store_dword v[146:147], v114, off nt
	global_store_dword v[148:149], v115, off nt

.LBB0_1102:
	s_and_b32 s7, s6, 0x18000
	v_add_u32_e32 v222, s7, v180
	s_add_i32 s7, s6, 0xfffe8000
	s_and_b32 s7, s7, 0x18000
	v_or_b32_e32 v223, s7, v179
	v_add_u32_e32 v233, s7, v176
	s_waitcnt vmcnt(8) lgkmcnt(0)
	s_barrier
	v_mfma_f32_32x32x16_bf16 v[112:127], v[150:153], v[142:145], v[112:127]
	v_mfma_f32_32x32x16_bf16 v[96:111], v[150:153], v[130:133], v[96:111]
	v_add_u32_e32 v206, v223, v177
	v_add_u32_e32 v234, v233, v177
	ds_read_b128 v[202:205], v206 offset:16384
	ds_read_b128 v[206:209], v206 offset:18432
	ds_read_b128 v[210:213], v234
	ds_read_b128 v[214:217], v234 offset:2048
	ds_read_b128 v[224:227], v234 offset:4096
	ds_read_b128 v[234:237], v234 offset:6144
	v_mfma_f32_32x32x16_bf16 v[80:95], v[146:149], v[142:145], v[80:95]
	v_mfma_f32_32x32x16_bf16 v[64:79], v[146:149], v[130:133], v[64:79]
	v_readfirstlane_b32 s7, v222
	s_mov_b32 m0, s7
	s_nop 0
	global_load_lds_dwordx4 v[170:171], off
	v_mfma_f32_32x32x16_bf16 v[48:63], v[138:141], v[142:145], v[48:63]
	v_mfma_f32_32x32x16_bf16 v[32:47], v[138:141], v[130:133], v[32:47]
	s_add_i32 s10, s7, 0x2000
	v_lshl_add_u64 v[150:151], v[170:171], 0, s[34:35]
	s_mov_b32 m0, s10
	s_nop 0
	global_load_lds_dwordx4 v[150:151], off
	v_mfma_f32_32x32x16_bf16 v[16:31], v[134:137], v[142:145], v[16:31]
	v_mfma_f32_32x32x16_bf16 v[0:15], v[134:137], v[130:133], v[0:15]
	v_add_u32_e32 v130, v223, v178
	v_add_u32_e32 v134, v233, v178
	ds_read_b128 v[142:145], v130 offset:16384
	ds_read_b128 v[130:133], v130 offset:18432
	ds_read_b128 v[150:153], v134
	ds_read_b128 v[146:149], v134 offset:2048
	ds_read_b128 v[138:141], v134 offset:4096
	ds_read_b128 v[134:137], v134 offset:6144
	s_waitcnt lgkmcnt(9)
	v_mfma_f32_32x32x16_bf16 v[112:127], v[210:213], v[202:205], v[112:127]
	s_add_i32 s10, s7, 0x6000
	s_addk_i32 s7, 0x4000
	v_mfma_f32_32x32x16_bf16 v[96:111], v[210:213], v[206:209], v[96:111]
	s_mov_b32 m0, s7
	s_nop 0
	global_load_lds_dwordx4 v[172:173], off
	v_lshl_add_u64 v[222:223], v[172:173], 0, s[34:35]
	s_waitcnt lgkmcnt(8)
	v_mfma_f32_32x32x16_bf16 v[80:95], v[214:217], v[202:205], v[80:95]
	v_mfma_f32_32x32x16_bf16 v[64:79], v[214:217], v[206:209], v[64:79]
	s_waitcnt lgkmcnt(7)
	v_mfma_f32_32x32x16_bf16 v[48:63], v[224:227], v[202:205], v[48:63]
	v_mfma_f32_32x32x16_bf16 v[32:47], v[224:227], v[206:209], v[32:47]
	s_mov_b32 m0, s10
	s_nop 0
	global_load_lds_dwordx4 v[222:223], off
	s_waitcnt lgkmcnt(6)
	v_mfma_f32_32x32x16_bf16 v[16:31], v[234:237], v[202:205], v[16:31]
	s_add_i32 s6, s6, 0x8000
	v_lshl_add_u64 v[170:171], v[170:171], 0, 64
	v_lshl_add_u64 v[172:173], v[172:173], 0, 64
	s_cmp_eq_u32 s6, 0x100000
	v_mfma_f32_32x32x16_bf16 v[0:15], v[234:237], v[206:209], v[0:15]
	s_cbranch_scc0 .LBB0_1102
	s_waitcnt vmcnt(8) lgkmcnt(0)
	s_barrier
	v_add_u32_e32 v202, v179, v177
	v_add_u32_e32 v222, v176, v177
	ds_read_b128 v[170:173], v202 offset:49152
	ds_read_b128 v[202:205], v202 offset:51200
	ds_read_b128 v[206:209], v222 offset:32768
	ds_read_b128 v[210:213], v222 offset:34816
	ds_read_b128 v[214:217], v222 offset:36864
	ds_read_b128 v[224:227], v222 offset:38912
	s_waitcnt lgkmcnt(9)
	v_mfma_f32_32x32x16_bf16 v[112:127], v[150:153], v[142:145], v[112:127]
	v_mfma_f32_32x32x16_bf16 v[96:111], v[150:153], v[130:133], v[96:111]
	s_waitcnt lgkmcnt(8)
	v_mfma_f32_32x32x16_bf16 v[80:95], v[146:149], v[142:145], v[80:95]
	v_mfma_f32_32x32x16_bf16 v[64:79], v[146:149], v[130:133], v[64:79]
	s_waitcnt lgkmcnt(7)
	v_mfma_f32_32x32x16_bf16 v[48:63], v[138:141], v[142:145], v[48:63]
	v_mfma_f32_32x32x16_bf16 v[32:47], v[138:141], v[130:133], v[32:47]
	s_waitcnt lgkmcnt(6)
	v_mfma_f32_32x32x16_bf16 v[16:31], v[134:137], v[142:145], v[16:31]
	v_mfma_f32_32x32x16_bf16 v[0:15], v[134:137], v[130:133], v[0:15]
	v_add_u32_e32 v134, v179, v178
	v_add_u32_e32 v150, v176, v178
	ds_read_b128 v[130:133], v134 offset:49152
	ds_read_b128 v[134:137], v134 offset:51200
	ds_read_b128 v[138:141], v150 offset:32768
	ds_read_b128 v[142:145], v150 offset:34816
	ds_read_b128 v[146:149], v150 offset:36864
	ds_read_b128 v[150:153], v150 offset:38912
	s_waitcnt lgkmcnt(9)
	v_mfma_f32_32x32x16_bf16 v[112:127], v[206:209], v[170:173], v[112:127]
	v_mfma_f32_32x32x16_bf16 v[96:111], v[206:209], v[202:205], v[96:111]
	s_waitcnt lgkmcnt(8)
	v_mfma_f32_32x32x16_bf16 v[80:95], v[210:213], v[170:173], v[80:95]
	v_mfma_f32_32x32x16_bf16 v[64:79], v[210:213], v[202:205], v[64:79]
	s_waitcnt lgkmcnt(7)
	v_mfma_f32_32x32x16_bf16 v[48:63], v[214:217], v[170:173], v[48:63]
	v_mfma_f32_32x32x16_bf16 v[32:47], v[214:217], v[202:205], v[32:47]
	s_waitcnt lgkmcnt(6)
	v_mfma_f32_32x32x16_bf16 v[0:15], v[224:227], v[202:205], v[0:15]
	s_waitcnt vmcnt(4) lgkmcnt(0)
	s_barrier
	v_add_u32_e32 v202, v199, v177
	v_add_u32_e32 v222, v200, v177
	v_mfma_f32_32x32x16_bf16 v[16:31], v[224:227], v[170:173], v[16:31]
	ds_read_b128 v[170:173], v202 offset:16384
	ds_read_b128 v[202:205], v202 offset:18432
	ds_read_b128 v[206:209], v222
	ds_read_b128 v[210:213], v222 offset:2048
	ds_read_b128 v[214:217], v222 offset:4096
	ds_read_b128 v[224:227], v222 offset:6144
	s_waitcnt lgkmcnt(9)
	v_mfma_f32_32x32x16_bf16 v[112:127], v[138:141], v[130:133], v[112:127]
	v_mfma_f32_32x32x16_bf16 v[96:111], v[138:141], v[134:137], v[96:111]
	s_waitcnt lgkmcnt(8)
	v_mfma_f32_32x32x16_bf16 v[80:95], v[142:145], v[130:133], v[80:95]
	v_mfma_f32_32x32x16_bf16 v[64:79], v[142:145], v[134:137], v[64:79]
	s_waitcnt lgkmcnt(7)
	v_mfma_f32_32x32x16_bf16 v[48:63], v[146:149], v[130:133], v[48:63]
	v_mfma_f32_32x32x16_bf16 v[32:47], v[146:149], v[134:137], v[32:47]
	s_waitcnt lgkmcnt(6)
	v_mfma_f32_32x32x16_bf16 v[16:31], v[150:153], v[130:133], v[16:31]
	v_mfma_f32_32x32x16_bf16 v[0:15], v[150:153], v[134:137], v[0:15]
	v_add_u32_e32 v134, v199, v178
	v_add_u32_e32 v150, v200, v178
	ds_read_b128 v[130:133], v134 offset:16384
	ds_read_b128 v[134:137], v134 offset:18432
	ds_read_b128 v[138:141], v150
	ds_read_b128 v[142:145], v150 offset:2048
	ds_read_b128 v[146:149], v150 offset:4096
	ds_read_b128 v[150:153], v150 offset:6144
	s_waitcnt lgkmcnt(9)
	v_mfma_f32_32x32x16_bf16 v[112:127], v[206:209], v[170:173], v[112:127]
	v_mfma_f32_32x32x16_bf16 v[96:111], v[206:209], v[202:205], v[96:111]
	s_waitcnt lgkmcnt(8)
	v_mfma_f32_32x32x16_bf16 v[80:95], v[210:213], v[170:173], v[80:95]
	v_mfma_f32_32x32x16_bf16 v[64:79], v[210:213], v[202:205], v[64:79]
	s_waitcnt lgkmcnt(7)
	v_mfma_f32_32x32x16_bf16 v[48:63], v[214:217], v[170:173], v[48:63]
	v_mfma_f32_32x32x16_bf16 v[32:47], v[214:217], v[202:205], v[32:47]
	s_waitcnt lgkmcnt(6)
	v_mfma_f32_32x32x16_bf16 v[0:15], v[224:227], v[202:205], v[0:15]
	s_waitcnt vmcnt(0) lgkmcnt(0)
	s_barrier
	v_add_u32_e32 v202, v197, v177
	v_add_u32_e32 v222, v198, v177
	v_mfma_f32_32x32x16_bf16 v[16:31], v[224:227], v[170:173], v[16:31]
	ds_read_b128 v[170:173], v202 offset:16384
	ds_read_b128 v[202:205], v202 offset:18432
	ds_read_b128 v[206:209], v222
	ds_read_b128 v[210:213], v222 offset:2048
	ds_read_b128 v[214:217], v222 offset:4096
	ds_read_b128 v[224:227], v222 offset:6144
	s_waitcnt lgkmcnt(9)
	v_mfma_f32_32x32x16_bf16 v[112:127], v[138:141], v[130:133], v[112:127]
	v_mfma_f32_32x32x16_bf16 v[96:111], v[138:141], v[134:137], v[96:111]
	s_waitcnt lgkmcnt(8)
	v_mfma_f32_32x32x16_bf16 v[80:95], v[142:145], v[130:133], v[80:95]
	v_mfma_f32_32x32x16_bf16 v[64:79], v[142:145], v[134:137], v[64:79]
	s_waitcnt lgkmcnt(7)
	v_mfma_f32_32x32x16_bf16 v[48:63], v[146:149], v[130:133], v[48:63]
	v_mfma_f32_32x32x16_bf16 v[32:47], v[146:149], v[134:137], v[32:47]
	s_waitcnt lgkmcnt(6)
	v_mfma_f32_32x32x16_bf16 v[16:31], v[150:153], v[130:133], v[16:31]
	v_mfma_f32_32x32x16_bf16 v[0:15], v[150:153], v[134:137], v[0:15]
	v_add_u32_e32 v134, v197, v178
	v_add_u32_e32 v150, v198, v178
	ds_read_b128 v[130:133], v134 offset:16384
	ds_read_b128 v[134:137], v134 offset:18432
	ds_read_b128 v[138:141], v150
	ds_read_b128 v[142:145], v150 offset:2048
	ds_read_b128 v[146:149], v150 offset:4096
	ds_read_b128 v[150:153], v150 offset:6144
	s_waitcnt lgkmcnt(9)
	v_mfma_f32_32x32x16_bf16 v[112:127], v[206:209], v[170:173], v[112:127]
	v_mfma_f32_32x32x16_bf16 v[96:111], v[206:209], v[202:205], v[96:111]
	s_waitcnt lgkmcnt(8)
	v_mfma_f32_32x32x16_bf16 v[80:95], v[210:213], v[170:173], v[80:95]
	v_mfma_f32_32x32x16_bf16 v[64:79], v[210:213], v[202:205], v[64:79]
	s_waitcnt lgkmcnt(7)
	v_mfma_f32_32x32x16_bf16 v[48:63], v[214:217], v[170:173], v[48:63]
	v_mfma_f32_32x32x16_bf16 v[32:47], v[214:217], v[202:205], v[32:47]
	s_waitcnt lgkmcnt(6)
	v_mfma_f32_32x32x16_bf16 v[16:31], v[224:227], v[170:173], v[16:31]
	v_mfma_f32_32x32x16_bf16 v[0:15], v[224:227], v[202:205], v[0:15]
	s_waitcnt lgkmcnt(3)
	v_mfma_f32_32x32x16_bf16 v[112:127], v[138:141], v[130:133], v[112:127]
	v_mfma_f32_32x32x16_bf16 v[96:111], v[138:141], v[134:137], v[96:111]
	s_nop 10
	v_cvt_pk_bf16_f32 v112, v112, s0
	s_waitcnt lgkmcnt(2)
	v_mfma_f32_32x32x16_bf16 v[80:95], v[142:145], v[130:133], v[80:95]
	v_cvt_pk_bf16_f32 v96, v96, s0
	v_cvt_pk_bf16_f32 v98, v98, s0
	s_waitcnt lgkmcnt(1)
	v_mfma_f32_32x32x16_bf16 v[48:63], v[146:149], v[130:133], v[48:63]
	s_nop 7
	v_cvt_pk_bf16_f32 v80, v80, s0
	s_waitcnt lgkmcnt(0)
	v_mfma_f32_32x32x16_bf16 v[16:31], v[150:153], v[130:133], v[16:31]
	v_add_u32_e32 v132, s3, v128
	v_or_b32_e32 v130, s5, v174
	v_ashrrev_i32_e32 v131, 31, v130
	v_lshl_add_u64 v[130:131], v[130:131], 1, v[158:159]
	v_cvt_pk_bf16_f32 v48, v48, s0
	v_readlane_b32 s3, v252, 7
	s_add_i32 s4, s4, s3
	v_mfma_f32_32x32x16_bf16 v[64:79], v[142:145], v[134:137], v[64:79]
	s_nop 3
	v_cvt_pk_bf16_f32 v16, v16, s0
	v_mfma_f32_32x32x16_bf16 v[32:47], v[146:149], v[134:137], v[32:47]
	s_nop 5
	v_cvt_pk_bf16_f32 v64, v64, s0
	v_cvt_pk_bf16_f32 v66, v66, s0
	v_mfma_f32_32x32x16_bf16 v[0:15], v[150:153], v[134:137], v[0:15]
	v_or_b32_e32 v134, v132, v181
	v_ashrrev_i32_e32 v135, 31, v134
	v_lshlrev_b64 v[134:135], 11, v[134:135]
	v_lshl_add_u64 v[134:135], v[130:131], 0, v[134:135]
	global_store_short v[134:135], v112, off
	global_store_short v[134:135], v96, off offset:64
	v_or_b32_e32 v134, v132, v182
	v_ashrrev_i32_e32 v135, 31, v134
	v_lshlrev_b64 v[134:135], 11, v[134:135]
	v_lshl_add_u64 v[134:135], v[130:131], 0, v[134:135]
	v_cvt_pk_bf16_f32 v96, v113, s0
	global_store_short v[134:135], v96, off
	v_cvt_pk_bf16_f32 v96, v97, s0
	global_store_short v[134:135], v96, off offset:64
	v_or_b32_e32 v96, v132, v183
	v_ashrrev_i32_e32 v97, 31, v96
	v_lshlrev_b64 v[96:97], 11, v[96:97]
	v_lshl_add_u64 v[96:97], v[130:131], 0, v[96:97]
	v_cvt_pk_bf16_f32 v112, v114, s0
	global_store_short v[96:97], v112, off
	global_store_short v[96:97], v98, off offset:64
	v_or_b32_e32 v96, v132, v184
	v_ashrrev_i32_e32 v97, 31, v96
	v_lshlrev_b64 v[96:97], 11, v[96:97]
	v_lshl_add_u64 v[96:97], v[130:131], 0, v[96:97]
	v_cvt_pk_bf16_f32 v98, v115, s0
	global_store_short v[96:97], v98, off
	v_cvt_pk_bf16_f32 v98, v99, s0
	global_store_short v[96:97], v98, off offset:64
	v_or_b32_e32 v96, v132, v185
	v_ashrrev_i32_e32 v97, 31, v96
	v_lshlrev_b64 v[96:97], 11, v[96:97]
	v_lshl_add_u64 v[96:97], v[130:131], 0, v[96:97]
	v_cvt_pk_bf16_f32 v98, v116, s0
	global_store_short v[96:97], v98, off
	v_cvt_pk_bf16_f32 v98, v100, s0
	global_store_short v[96:97], v98, off offset:64
	v_or_b32_e32 v96, v132, v186
	v_ashrrev_i32_e32 v97, 31, v96
	v_lshlrev_b64 v[96:97], 11, v[96:97]
	v_lshl_add_u64 v[96:97], v[130:131], 0, v[96:97]
	v_cvt_pk_bf16_f32 v98, v117, s0
	global_store_short v[96:97], v98, off
	v_cvt_pk_bf16_f32 v98, v101, s0
	global_store_short v[96:97], v98, off offset:64
	v_or_b32_e32 v96, v132, v187
	v_ashrrev_i32_e32 v97, 31, v96
	v_lshlrev_b64 v[96:97], 11, v[96:97]
	v_lshl_add_u64 v[96:97], v[130:131], 0, v[96:97]
	v_cvt_pk_bf16_f32 v98, v118, s0
	global_store_short v[96:97], v98, off
	v_cvt_pk_bf16_f32 v98, v102, s0
	global_store_short v[96:97], v98, off offset:64
	v_or_b32_e32 v96, v132, v188
	v_ashrrev_i32_e32 v97, 31, v96
	v_lshlrev_b64 v[96:97], 11, v[96:97]
	v_lshl_add_u64 v[96:97], v[130:131], 0, v[96:97]
	v_cvt_pk_bf16_f32 v98, v119, s0
	global_store_short v[96:97], v98, off
	v_cvt_pk_bf16_f32 v98, v103, s0
	global_store_short v[96:97], v98, off offset:64
	v_or_b32_e32 v96, v132, v189
	v_ashrrev_i32_e32 v97, 31, v96
	v_lshlrev_b64 v[96:97], 11, v[96:97]
	v_lshl_add_u64 v[96:97], v[130:131], 0, v[96:97]
	v_cvt_pk_bf16_f32 v98, v120, s0
	global_store_short v[96:97], v98, off
	v_cvt_pk_bf16_f32 v98, v104, s0
	global_store_short v[96:97], v98, off offset:64
	v_or_b32_e32 v96, v132, v190
	v_ashrrev_i32_e32 v97, 31, v96
	v_lshlrev_b64 v[96:97], 11, v[96:97]
	v_lshl_add_u64 v[96:97], v[130:131], 0, v[96:97]
	v_cvt_pk_bf16_f32 v98, v121, s0
	global_store_short v[96:97], v98, off
	v_cvt_pk_bf16_f32 v98, v105, s0
	global_store_short v[96:97], v98, off offset:64
	v_or_b32_e32 v96, v132, v191
	v_ashrrev_i32_e32 v97, 31, v96
	v_lshlrev_b64 v[96:97], 11, v[96:97]
	v_lshl_add_u64 v[96:97], v[130:131], 0, v[96:97]
	v_cvt_pk_bf16_f32 v98, v122, s0
	global_store_short v[96:97], v98, off
	v_cvt_pk_bf16_f32 v98, v106, s0
	global_store_short v[96:97], v98, off offset:64
	v_or_b32_e32 v96, v132, v192
	v_ashrrev_i32_e32 v97, 31, v96
	v_lshlrev_b64 v[96:97], 11, v[96:97]
	v_lshl_add_u64 v[96:97], v[130:131], 0, v[96:97]
	v_cvt_pk_bf16_f32 v98, v123, s0
	global_store_short v[96:97], v98, off
	v_cvt_pk_bf16_f32 v98, v107, s0
	global_store_short v[96:97], v98, off offset:64
	v_or_b32_e32 v96, v132, v193
	v_ashrrev_i32_e32 v97, 31, v96
	v_lshlrev_b64 v[96:97], 11, v[96:97]
	v_lshl_add_u64 v[96:97], v[130:131], 0, v[96:97]
	v_cvt_pk_bf16_f32 v98, v124, s0
	global_store_short v[96:97], v98, off
	v_cvt_pk_bf16_f32 v98, v108, s0
	global_store_short v[96:97], v98, off offset:64
	v_or_b32_e32 v96, v132, v194
	v_ashrrev_i32_e32 v97, 31, v96
	v_lshlrev_b64 v[96:97], 11, v[96:97]
	v_lshl_add_u64 v[96:97], v[130:131], 0, v[96:97]
	v_cvt_pk_bf16_f32 v98, v125, s0
	global_store_short v[96:97], v98, off
	v_cvt_pk_bf16_f32 v98, v109, s0
	global_store_short v[96:97], v98, off offset:64
	v_or_b32_e32 v96, v132, v195
	v_ashrrev_i32_e32 v97, 31, v96
	v_lshlrev_b64 v[96:97], 11, v[96:97]
	v_lshl_add_u64 v[96:97], v[130:131], 0, v[96:97]
	v_cvt_pk_bf16_f32 v98, v126, s0
	global_store_short v[96:97], v98, off
	v_cvt_pk_bf16_f32 v98, v110, s0
	global_store_short v[96:97], v98, off offset:64
	v_or_b32_e32 v96, v132, v196
	v_ashrrev_i32_e32 v97, 31, v96
	v_lshlrev_b64 v[96:97], 11, v[96:97]
	v_lshl_add_u64 v[96:97], v[130:131], 0, v[96:97]
	v_cvt_pk_bf16_f32 v98, v127, s0
	global_store_short v[96:97], v98, off
	v_cvt_pk_bf16_f32 v98, v111, s0
	global_store_short v[96:97], v98, off offset:64
	v_or_b32_e32 v98, 32, v132
	v_or_b32_e32 v96, v98, v181
	v_ashrrev_i32_e32 v97, 31, v96
	v_lshlrev_b64 v[96:97], 11, v[96:97]
	v_lshl_add_u64 v[96:97], v[130:131], 0, v[96:97]
	global_store_short v[96:97], v80, off
	global_store_short v[96:97], v64, off offset:64
	v_or_b32_e32 v96, v98, v182
	v_ashrrev_i32_e32 v97, 31, v96
	v_lshlrev_b64 v[96:97], 11, v[96:97]
	v_lshl_add_u64 v[96:97], v[130:131], 0, v[96:97]
	v_cvt_pk_bf16_f32 v64, v81, s0
	global_store_short v[96:97], v64, off
	v_cvt_pk_bf16_f32 v64, v65, s0
	global_store_short v[96:97], v64, off offset:64
	v_or_b32_e32 v64, v98, v183
	v_ashrrev_i32_e32 v65, 31, v64
	v_lshlrev_b64 v[64:65], 11, v[64:65]
	v_lshl_add_u64 v[64:65], v[130:131], 0, v[64:65]
	v_cvt_pk_bf16_f32 v80, v82, s0
	global_store_short v[64:65], v80, off
	global_store_short v[64:65], v66, off offset:64
	v_or_b32_e32 v64, v98, v184
	v_ashrrev_i32_e32 v65, 31, v64
	v_lshlrev_b64 v[64:65], 11, v[64:65]
	v_lshl_add_u64 v[64:65], v[130:131], 0, v[64:65]
	v_cvt_pk_bf16_f32 v66, v83, s0
	global_store_short v[64:65], v66, off
	v_cvt_pk_bf16_f32 v66, v67, s0
	global_store_short v[64:65], v66, off offset:64
	v_or_b32_e32 v64, v98, v185
	v_ashrrev_i32_e32 v65, 31, v64
	v_lshlrev_b64 v[64:65], 11, v[64:65]
	v_lshl_add_u64 v[64:65], v[130:131], 0, v[64:65]
	v_cvt_pk_bf16_f32 v66, v84, s0
	global_store_short v[64:65], v66, off
	v_cvt_pk_bf16_f32 v66, v68, s0
	global_store_short v[64:65], v66, off offset:64
	v_or_b32_e32 v64, v98, v186
	v_ashrrev_i32_e32 v65, 31, v64
	v_lshlrev_b64 v[64:65], 11, v[64:65]
	v_lshl_add_u64 v[64:65], v[130:131], 0, v[64:65]
	v_cvt_pk_bf16_f32 v66, v85, s0
	global_store_short v[64:65], v66, off
	v_cvt_pk_bf16_f32 v66, v69, s0
	global_store_short v[64:65], v66, off offset:64
	v_or_b32_e32 v64, v98, v187
	v_ashrrev_i32_e32 v65, 31, v64
	v_lshlrev_b64 v[64:65], 11, v[64:65]
	v_lshl_add_u64 v[64:65], v[130:131], 0, v[64:65]
	v_cvt_pk_bf16_f32 v66, v86, s0
	global_store_short v[64:65], v66, off
	v_cvt_pk_bf16_f32 v66, v70, s0
	global_store_short v[64:65], v66, off offset:64
	v_or_b32_e32 v64, v98, v188
	v_ashrrev_i32_e32 v65, 31, v64
	v_lshlrev_b64 v[64:65], 11, v[64:65]
	v_lshl_add_u64 v[64:65], v[130:131], 0, v[64:65]
	v_cvt_pk_bf16_f32 v66, v87, s0
	global_store_short v[64:65], v66, off
	v_cvt_pk_bf16_f32 v66, v71, s0
	global_store_short v[64:65], v66, off offset:64
	v_or_b32_e32 v64, v98, v189
	v_ashrrev_i32_e32 v65, 31, v64
	v_lshlrev_b64 v[64:65], 11, v[64:65]
	v_lshl_add_u64 v[64:65], v[130:131], 0, v[64:65]
	v_cvt_pk_bf16_f32 v66, v88, s0
	global_store_short v[64:65], v66, off
	v_cvt_pk_bf16_f32 v66, v72, s0
	global_store_short v[64:65], v66, off offset:64
	v_or_b32_e32 v64, v98, v190
	v_ashrrev_i32_e32 v65, 31, v64
	v_lshlrev_b64 v[64:65], 11, v[64:65]
	v_lshl_add_u64 v[64:65], v[130:131], 0, v[64:65]
	v_cvt_pk_bf16_f32 v66, v89, s0
	global_store_short v[64:65], v66, off
	v_cvt_pk_bf16_f32 v66, v73, s0
	global_store_short v[64:65], v66, off offset:64
	v_or_b32_e32 v64, v98, v191
	v_ashrrev_i32_e32 v65, 31, v64
	v_lshlrev_b64 v[64:65], 11, v[64:65]
	v_lshl_add_u64 v[64:65], v[130:131], 0, v[64:65]
	v_cvt_pk_bf16_f32 v66, v90, s0
	global_store_short v[64:65], v66, off
	v_cvt_pk_bf16_f32 v66, v74, s0
	global_store_short v[64:65], v66, off offset:64
	v_or_b32_e32 v64, v98, v192
	v_ashrrev_i32_e32 v65, 31, v64
	v_lshlrev_b64 v[64:65], 11, v[64:65]
	v_lshl_add_u64 v[64:65], v[130:131], 0, v[64:65]
	v_cvt_pk_bf16_f32 v66, v91, s0
	global_store_short v[64:65], v66, off
	v_cvt_pk_bf16_f32 v66, v75, s0
	global_store_short v[64:65], v66, off offset:64
	v_or_b32_e32 v64, v98, v193
	v_ashrrev_i32_e32 v65, 31, v64
	v_lshlrev_b64 v[64:65], 11, v[64:65]
	v_lshl_add_u64 v[64:65], v[130:131], 0, v[64:65]
	v_cvt_pk_bf16_f32 v66, v92, s0
	global_store_short v[64:65], v66, off
	v_cvt_pk_bf16_f32 v66, v76, s0
	global_store_short v[64:65], v66, off offset:64
	v_or_b32_e32 v64, v98, v194
	v_ashrrev_i32_e32 v65, 31, v64
	v_lshlrev_b64 v[64:65], 11, v[64:65]
	v_lshl_add_u64 v[64:65], v[130:131], 0, v[64:65]
	v_cvt_pk_bf16_f32 v66, v93, s0
	global_store_short v[64:65], v66, off
	v_cvt_pk_bf16_f32 v66, v77, s0
	global_store_short v[64:65], v66, off offset:64
	v_or_b32_e32 v64, v98, v195
	v_ashrrev_i32_e32 v65, 31, v64
	v_lshlrev_b64 v[64:65], 11, v[64:65]
	v_lshl_add_u64 v[64:65], v[130:131], 0, v[64:65]
	v_cvt_pk_bf16_f32 v66, v94, s0
	global_store_short v[64:65], v66, off
	v_cvt_pk_bf16_f32 v66, v78, s0
	global_store_short v[64:65], v66, off offset:64
	v_or_b32_e32 v64, v98, v196
	v_ashrrev_i32_e32 v65, 31, v64
	v_lshlrev_b64 v[64:65], 11, v[64:65]
	v_lshl_add_u64 v[64:65], v[130:131], 0, v[64:65]
	v_cvt_pk_bf16_f32 v66, v95, s0
	global_store_short v[64:65], v66, off
	v_cvt_pk_bf16_f32 v66, v79, s0
	global_store_short v[64:65], v66, off offset:64
	v_or_b32_e32 v66, 64, v132
	v_or_b32_e32 v64, v66, v181
	v_ashrrev_i32_e32 v65, 31, v64
	v_lshlrev_b64 v[64:65], 11, v[64:65]
	v_lshl_add_u64 v[64:65], v[130:131], 0, v[64:65]
	v_cvt_pk_bf16_f32 v32, v32, s0
	global_store_short v[64:65], v48, off
	global_store_short v[64:65], v32, off offset:64
	v_or_b32_e32 v64, v66, v182
	v_ashrrev_i32_e32 v65, 31, v64
	v_lshlrev_b64 v[64:65], 11, v[64:65]
	v_lshl_add_u64 v[64:65], v[130:131], 0, v[64:65]
	v_cvt_pk_bf16_f32 v32, v49, s0
	global_store_short v[64:65], v32, off
	v_cvt_pk_bf16_f32 v32, v33, s0
	global_store_short v[64:65], v32, off offset:64
	v_or_b32_e32 v32, v66, v183
	v_ashrrev_i32_e32 v33, 31, v32
	v_lshlrev_b64 v[32:33], 11, v[32:33]
	v_lshl_add_u64 v[32:33], v[130:131], 0, v[32:33]
	v_cvt_pk_bf16_f32 v48, v50, s0
	v_cvt_pk_bf16_f32 v34, v34, s0
	global_store_short v[32:33], v48, off
	global_store_short v[32:33], v34, off offset:64
	v_or_b32_e32 v32, v66, v184
	v_ashrrev_i32_e32 v33, 31, v32
	v_lshlrev_b64 v[32:33], 11, v[32:33]
	v_lshl_add_u64 v[32:33], v[130:131], 0, v[32:33]
	v_cvt_pk_bf16_f32 v34, v51, s0
	global_store_short v[32:33], v34, off
	v_cvt_pk_bf16_f32 v34, v35, s0
	global_store_short v[32:33], v34, off offset:64
	v_or_b32_e32 v32, v66, v185
	v_ashrrev_i32_e32 v33, 31, v32
	v_lshlrev_b64 v[32:33], 11, v[32:33]
	v_lshl_add_u64 v[32:33], v[130:131], 0, v[32:33]
	v_cvt_pk_bf16_f32 v34, v52, s0
	global_store_short v[32:33], v34, off
	v_cvt_pk_bf16_f32 v34, v36, s0
	global_store_short v[32:33], v34, off offset:64
	v_or_b32_e32 v32, v66, v186
	v_ashrrev_i32_e32 v33, 31, v32
	v_lshlrev_b64 v[32:33], 11, v[32:33]
	v_lshl_add_u64 v[32:33], v[130:131], 0, v[32:33]
	v_cvt_pk_bf16_f32 v34, v53, s0
	global_store_short v[32:33], v34, off
	v_cvt_pk_bf16_f32 v34, v37, s0
	global_store_short v[32:33], v34, off offset:64
	v_or_b32_e32 v32, v66, v187
	v_ashrrev_i32_e32 v33, 31, v32
	v_lshlrev_b64 v[32:33], 11, v[32:33]
	v_lshl_add_u64 v[32:33], v[130:131], 0, v[32:33]
	v_cvt_pk_bf16_f32 v34, v54, s0
	global_store_short v[32:33], v34, off
	v_cvt_pk_bf16_f32 v34, v38, s0
	global_store_short v[32:33], v34, off offset:64
	v_or_b32_e32 v32, v66, v188
	v_ashrrev_i32_e32 v33, 31, v32
	v_lshlrev_b64 v[32:33], 11, v[32:33]
	v_lshl_add_u64 v[32:33], v[130:131], 0, v[32:33]
	v_cvt_pk_bf16_f32 v34, v55, s0
	global_store_short v[32:33], v34, off
	v_cvt_pk_bf16_f32 v34, v39, s0
	global_store_short v[32:33], v34, off offset:64
	v_or_b32_e32 v32, v66, v189
	v_ashrrev_i32_e32 v33, 31, v32
	v_lshlrev_b64 v[32:33], 11, v[32:33]
	v_lshl_add_u64 v[32:33], v[130:131], 0, v[32:33]
	v_cvt_pk_bf16_f32 v34, v56, s0
	global_store_short v[32:33], v34, off
	v_cvt_pk_bf16_f32 v34, v40, s0
	global_store_short v[32:33], v34, off offset:64
	v_or_b32_e32 v32, v66, v190
	v_ashrrev_i32_e32 v33, 31, v32
	v_lshlrev_b64 v[32:33], 11, v[32:33]
	v_lshl_add_u64 v[32:33], v[130:131], 0, v[32:33]
	v_cvt_pk_bf16_f32 v34, v57, s0
	global_store_short v[32:33], v34, off
	v_cvt_pk_bf16_f32 v34, v41, s0
	global_store_short v[32:33], v34, off offset:64
	v_or_b32_e32 v32, v66, v191
	v_ashrrev_i32_e32 v33, 31, v32
	v_lshlrev_b64 v[32:33], 11, v[32:33]
	v_lshl_add_u64 v[32:33], v[130:131], 0, v[32:33]
	v_cvt_pk_bf16_f32 v34, v58, s0
	global_store_short v[32:33], v34, off
	v_cvt_pk_bf16_f32 v34, v42, s0
	global_store_short v[32:33], v34, off offset:64
	v_or_b32_e32 v32, v66, v192
	v_ashrrev_i32_e32 v33, 31, v32
	v_lshlrev_b64 v[32:33], 11, v[32:33]
	v_lshl_add_u64 v[32:33], v[130:131], 0, v[32:33]
	v_cvt_pk_bf16_f32 v34, v59, s0
	global_store_short v[32:33], v34, off
	v_cvt_pk_bf16_f32 v34, v43, s0
	global_store_short v[32:33], v34, off offset:64
	v_or_b32_e32 v32, v66, v193
	v_ashrrev_i32_e32 v33, 31, v32
	v_lshlrev_b64 v[32:33], 11, v[32:33]
	v_lshl_add_u64 v[32:33], v[130:131], 0, v[32:33]
	v_cvt_pk_bf16_f32 v34, v60, s0
	global_store_short v[32:33], v34, off
	v_cvt_pk_bf16_f32 v34, v44, s0
	global_store_short v[32:33], v34, off offset:64
	v_or_b32_e32 v32, v66, v194
	v_ashrrev_i32_e32 v33, 31, v32
	v_lshlrev_b64 v[32:33], 11, v[32:33]
	v_lshl_add_u64 v[32:33], v[130:131], 0, v[32:33]
	v_cvt_pk_bf16_f32 v34, v61, s0
	global_store_short v[32:33], v34, off
	v_cvt_pk_bf16_f32 v34, v45, s0
	global_store_short v[32:33], v34, off offset:64
	v_or_b32_e32 v32, v66, v195
	v_ashrrev_i32_e32 v33, 31, v32
	v_lshlrev_b64 v[32:33], 11, v[32:33]
	v_lshl_add_u64 v[32:33], v[130:131], 0, v[32:33]
	v_cvt_pk_bf16_f32 v34, v62, s0
	global_store_short v[32:33], v34, off
	v_cvt_pk_bf16_f32 v34, v46, s0
	global_store_short v[32:33], v34, off offset:64
	v_or_b32_e32 v32, v66, v196
	v_ashrrev_i32_e32 v33, 31, v32
	v_lshlrev_b64 v[32:33], 11, v[32:33]
	v_lshl_add_u64 v[32:33], v[130:131], 0, v[32:33]
	v_cvt_pk_bf16_f32 v34, v63, s0
	global_store_short v[32:33], v34, off
	v_cvt_pk_bf16_f32 v34, v47, s0
	global_store_short v[32:33], v34, off offset:64
	v_or_b32_e32 v34, 0x60, v132
	v_or_b32_e32 v32, v34, v181
	v_ashrrev_i32_e32 v33, 31, v32
	v_lshlrev_b64 v[32:33], 11, v[32:33]
	v_lshl_add_u64 v[32:33], v[130:131], 0, v[32:33]
	v_cvt_pk_bf16_f32 v0, v0, s0
	global_store_short v[32:33], v16, off
	global_store_short v[32:33], v0, off offset:64
	v_or_b32_e32 v32, v34, v182
	v_ashrrev_i32_e32 v33, 31, v32
	v_lshlrev_b64 v[32:33], 11, v[32:33]
	v_lshl_add_u64 v[32:33], v[130:131], 0, v[32:33]
	v_cvt_pk_bf16_f32 v0, v17, s0
	global_store_short v[32:33], v0, off
	v_cvt_pk_bf16_f32 v0, v1, s0
	global_store_short v[32:33], v0, off offset:64
	v_or_b32_e32 v0, v34, v183
	v_ashrrev_i32_e32 v1, 31, v0
	v_lshlrev_b64 v[0:1], 11, v[0:1]
	v_lshl_add_u64 v[0:1], v[130:131], 0, v[0:1]
	v_cvt_pk_bf16_f32 v16, v18, s0
	v_cvt_pk_bf16_f32 v2, v2, s0
	global_store_short v[0:1], v16, off
	global_store_short v[0:1], v2, off offset:64
	v_or_b32_e32 v0, v34, v184
	v_ashrrev_i32_e32 v1, 31, v0
	v_lshlrev_b64 v[0:1], 11, v[0:1]
	v_lshl_add_u64 v[0:1], v[130:131], 0, v[0:1]
	v_cvt_pk_bf16_f32 v2, v19, s0
	global_store_short v[0:1], v2, off
	v_cvt_pk_bf16_f32 v2, v3, s0
	global_store_short v[0:1], v2, off offset:64
	v_or_b32_e32 v0, v34, v185
	v_ashrrev_i32_e32 v1, 31, v0
	v_lshlrev_b64 v[0:1], 11, v[0:1]
	v_lshl_add_u64 v[0:1], v[130:131], 0, v[0:1]
	v_cvt_pk_bf16_f32 v2, v20, s0
	global_store_short v[0:1], v2, off
	v_cvt_pk_bf16_f32 v2, v4, s0
	global_store_short v[0:1], v2, off offset:64
	v_or_b32_e32 v0, v34, v186
	v_ashrrev_i32_e32 v1, 31, v0
	v_lshlrev_b64 v[0:1], 11, v[0:1]
	v_lshl_add_u64 v[0:1], v[130:131], 0, v[0:1]
	v_cvt_pk_bf16_f32 v2, v21, s0
	global_store_short v[0:1], v2, off
	v_cvt_pk_bf16_f32 v2, v5, s0
	global_store_short v[0:1], v2, off offset:64
	v_or_b32_e32 v0, v34, v187
	v_ashrrev_i32_e32 v1, 31, v0
	v_lshlrev_b64 v[0:1], 11, v[0:1]
	v_lshl_add_u64 v[0:1], v[130:131], 0, v[0:1]
	v_cvt_pk_bf16_f32 v2, v22, s0
	global_store_short v[0:1], v2, off
	v_cvt_pk_bf16_f32 v2, v6, s0
	global_store_short v[0:1], v2, off offset:64
	v_or_b32_e32 v0, v34, v188
	v_ashrrev_i32_e32 v1, 31, v0
	v_lshlrev_b64 v[0:1], 11, v[0:1]
	v_lshl_add_u64 v[0:1], v[130:131], 0, v[0:1]
	v_cvt_pk_bf16_f32 v2, v23, s0
	global_store_short v[0:1], v2, off
	v_cvt_pk_bf16_f32 v2, v7, s0
	global_store_short v[0:1], v2, off offset:64
	v_or_b32_e32 v0, v34, v189
	v_ashrrev_i32_e32 v1, 31, v0
	v_lshlrev_b64 v[0:1], 11, v[0:1]
	v_lshl_add_u64 v[0:1], v[130:131], 0, v[0:1]
	v_cvt_pk_bf16_f32 v2, v24, s0
	global_store_short v[0:1], v2, off
	v_cvt_pk_bf16_f32 v2, v8, s0
	global_store_short v[0:1], v2, off offset:64
	v_or_b32_e32 v0, v34, v190
	v_ashrrev_i32_e32 v1, 31, v0
	v_lshlrev_b64 v[0:1], 11, v[0:1]
	v_lshl_add_u64 v[0:1], v[130:131], 0, v[0:1]
	v_cvt_pk_bf16_f32 v2, v25, s0
	global_store_short v[0:1], v2, off
	v_cvt_pk_bf16_f32 v2, v9, s0
	global_store_short v[0:1], v2, off offset:64
	v_or_b32_e32 v0, v34, v191
	v_ashrrev_i32_e32 v1, 31, v0
	v_lshlrev_b64 v[0:1], 11, v[0:1]
	v_lshl_add_u64 v[0:1], v[130:131], 0, v[0:1]
	v_cvt_pk_bf16_f32 v2, v26, s0
	global_store_short v[0:1], v2, off
	v_cvt_pk_bf16_f32 v2, v10, s0
	global_store_short v[0:1], v2, off offset:64
	v_or_b32_e32 v0, v34, v192
	v_ashrrev_i32_e32 v1, 31, v0
	v_lshlrev_b64 v[0:1], 11, v[0:1]
	v_lshl_add_u64 v[0:1], v[130:131], 0, v[0:1]
	v_cvt_pk_bf16_f32 v2, v27, s0
	global_store_short v[0:1], v2, off
	v_cvt_pk_bf16_f32 v2, v11, s0
	global_store_short v[0:1], v2, off offset:64
	v_or_b32_e32 v0, v34, v193
	v_ashrrev_i32_e32 v1, 31, v0
	v_lshlrev_b64 v[0:1], 11, v[0:1]
	v_lshl_add_u64 v[0:1], v[130:131], 0, v[0:1]
	v_cvt_pk_bf16_f32 v2, v28, s0
	global_store_short v[0:1], v2, off
	v_cvt_pk_bf16_f32 v2, v12, s0
	global_store_short v[0:1], v2, off offset:64
	v_or_b32_e32 v0, v34, v194
	v_ashrrev_i32_e32 v1, 31, v0
	v_lshlrev_b64 v[0:1], 11, v[0:1]
	v_lshl_add_u64 v[0:1], v[130:131], 0, v[0:1]
	v_cvt_pk_bf16_f32 v2, v29, s0
	global_store_short v[0:1], v2, off
	v_cvt_pk_bf16_f32 v2, v13, s0
	global_store_short v[0:1], v2, off offset:64
	v_or_b32_e32 v0, v34, v195
	v_ashrrev_i32_e32 v1, 31, v0
	v_lshlrev_b64 v[0:1], 11, v[0:1]
	v_lshl_add_u64 v[0:1], v[130:131], 0, v[0:1]
	v_cvt_pk_bf16_f32 v2, v30, s0
	global_store_short v[0:1], v2, off
	v_cvt_pk_bf16_f32 v2, v14, s0
	global_store_short v[0:1], v2, off offset:64
	v_or_b32_e32 v0, v34, v196
	v_ashrrev_i32_e32 v1, 31, v0
	v_lshlrev_b64 v[0:1], 11, v[0:1]
	v_lshl_add_u64 v[0:1], v[130:131], 0, v[0:1]
	v_cvt_pk_bf16_f32 v2, v31, s0
	global_store_short v[0:1], v2, off
	v_cvt_pk_bf16_f32 v2, v15, s0
	s_add_i32 s0, s0, s3
	v_readlane_b32 s3, v252, 8
	s_add_i32 s2, s2, s3
	s_cmp_gt_i32 s4, 31
	global_store_short v[0:1], v2, off offset:64
	s_cbranch_scc0 .LBB0_1101

.LBB0_2226:
	s_and_b32 s9, s8, 0x18000
	v_add_u32_e32 v222, s9, v180
	s_add_i32 s9, s8, 0xfffe8000
	s_and_b32 s9, s9, 0x18000
	v_or_b32_e32 v223, s9, v179
	v_add_u32_e32 v233, s9, v176
	s_waitcnt vmcnt(8) lgkmcnt(0)
	s_barrier
	v_mfma_f32_32x32x16_bf16 v[112:127], v[150:153], v[142:145], v[112:127]
	v_mfma_f32_32x32x16_bf16 v[96:111], v[150:153], v[130:133], v[96:111]
	v_add_u32_e32 v206, v223, v177
	v_add_u32_e32 v234, v233, v177
	ds_read_b128 v[202:205], v206 offset:16384
	ds_read_b128 v[206:209], v206 offset:18432
	ds_read_b128 v[210:213], v234
	ds_read_b128 v[214:217], v234 offset:2048
	ds_read_b128 v[224:227], v234 offset:4096
	ds_read_b128 v[234:237], v234 offset:6144
	v_mfma_f32_32x32x16_bf16 v[80:95], v[146:149], v[142:145], v[80:95]
	v_mfma_f32_32x32x16_bf16 v[64:79], v[146:149], v[130:133], v[64:79]
	v_readfirstlane_b32 s9, v222
	s_mov_b32 m0, s9
	s_nop 0
	global_load_lds_dwordx4 v[170:171], off
	v_mfma_f32_32x32x16_bf16 v[48:63], v[138:141], v[142:145], v[48:63]
	v_mfma_f32_32x32x16_bf16 v[32:47], v[138:141], v[130:133], v[32:47]
	s_add_i32 s10, s9, 0x2000
	v_lshl_add_u64 v[150:151], v[170:171], 0, s[12:13]
	s_mov_b32 m0, s10
	s_nop 0
	global_load_lds_dwordx4 v[150:151], off
	v_mfma_f32_32x32x16_bf16 v[16:31], v[134:137], v[142:145], v[16:31]
	v_mfma_f32_32x32x16_bf16 v[0:15], v[134:137], v[130:133], v[0:15]
	v_add_u32_e32 v130, v223, v178
	v_add_u32_e32 v134, v233, v178
	ds_read_b128 v[142:145], v130 offset:16384
	ds_read_b128 v[130:133], v130 offset:18432
	ds_read_b128 v[150:153], v134
	ds_read_b128 v[146:149], v134 offset:2048
	ds_read_b128 v[138:141], v134 offset:4096
	ds_read_b128 v[134:137], v134 offset:6144
	s_waitcnt lgkmcnt(9)
	v_mfma_f32_32x32x16_bf16 v[112:127], v[210:213], v[202:205], v[112:127]
	s_add_i32 s10, s9, 0x6000
	s_addk_i32 s9, 0x4000
	v_mfma_f32_32x32x16_bf16 v[96:111], v[210:213], v[206:209], v[96:111]
	s_mov_b32 m0, s9
	s_nop 0
	global_load_lds_dwordx4 v[172:173], off
	v_lshl_add_u64 v[222:223], v[172:173], 0, s[12:13]
	s_waitcnt lgkmcnt(8)
	v_mfma_f32_32x32x16_bf16 v[80:95], v[214:217], v[202:205], v[80:95]
	v_mfma_f32_32x32x16_bf16 v[64:79], v[214:217], v[206:209], v[64:79]
	s_waitcnt lgkmcnt(7)
	v_mfma_f32_32x32x16_bf16 v[48:63], v[224:227], v[202:205], v[48:63]
	v_mfma_f32_32x32x16_bf16 v[32:47], v[224:227], v[206:209], v[32:47]
	s_mov_b32 m0, s10
	s_nop 0
	global_load_lds_dwordx4 v[222:223], off
	s_waitcnt lgkmcnt(6)
	v_mfma_f32_32x32x16_bf16 v[16:31], v[234:237], v[202:205], v[16:31]
	s_add_i32 s8, s8, 0x8000
	v_lshl_add_u64 v[170:171], v[170:171], 0, 64
	v_lshl_add_u64 v[172:173], v[172:173], 0, 64
	s_cmp_eq_u32 s8, 0x200000
	v_mfma_f32_32x32x16_bf16 v[0:15], v[234:237], v[206:209], v[0:15]
	s_cbranch_scc0 .LBB0_2226
	s_waitcnt vmcnt(8) lgkmcnt(0)
	s_barrier
	v_add_u32_e32 v202, v179, v177
	v_add_u32_e32 v222, v176, v177
	ds_read_b128 v[170:173], v202 offset:49152
	ds_read_b128 v[202:205], v202 offset:51200
	ds_read_b128 v[206:209], v222 offset:32768
	ds_read_b128 v[210:213], v222 offset:34816
	ds_read_b128 v[214:217], v222 offset:36864
	ds_read_b128 v[224:227], v222 offset:38912
	s_waitcnt lgkmcnt(9)
	v_mfma_f32_32x32x16_bf16 v[112:127], v[150:153], v[142:145], v[112:127]
	v_mfma_f32_32x32x16_bf16 v[96:111], v[150:153], v[130:133], v[96:111]
	s_waitcnt lgkmcnt(8)
	v_mfma_f32_32x32x16_bf16 v[80:95], v[146:149], v[142:145], v[80:95]
	v_mfma_f32_32x32x16_bf16 v[64:79], v[146:149], v[130:133], v[64:79]
	s_waitcnt lgkmcnt(7)
	v_mfma_f32_32x32x16_bf16 v[48:63], v[138:141], v[142:145], v[48:63]
	v_mfma_f32_32x32x16_bf16 v[32:47], v[138:141], v[130:133], v[32:47]
	s_waitcnt lgkmcnt(6)
	v_mfma_f32_32x32x16_bf16 v[16:31], v[134:137], v[142:145], v[16:31]
	v_mfma_f32_32x32x16_bf16 v[0:15], v[134:137], v[130:133], v[0:15]
	v_add_u32_e32 v134, v179, v178
	v_add_u32_e32 v150, v176, v178
	ds_read_b128 v[130:133], v134 offset:49152
	ds_read_b128 v[134:137], v134 offset:51200
	ds_read_b128 v[138:141], v150 offset:32768
	ds_read_b128 v[142:145], v150 offset:34816
	ds_read_b128 v[146:149], v150 offset:36864
	ds_read_b128 v[150:153], v150 offset:38912
	s_waitcnt lgkmcnt(9)
	v_mfma_f32_32x32x16_bf16 v[112:127], v[206:209], v[170:173], v[112:127]
	v_mfma_f32_32x32x16_bf16 v[96:111], v[206:209], v[202:205], v[96:111]
	s_waitcnt lgkmcnt(8)
	v_mfma_f32_32x32x16_bf16 v[80:95], v[210:213], v[170:173], v[80:95]
	v_mfma_f32_32x32x16_bf16 v[64:79], v[210:213], v[202:205], v[64:79]
	s_waitcnt lgkmcnt(7)
	v_mfma_f32_32x32x16_bf16 v[48:63], v[214:217], v[170:173], v[48:63]
	v_mfma_f32_32x32x16_bf16 v[32:47], v[214:217], v[202:205], v[32:47]
	s_waitcnt lgkmcnt(6)
	v_mfma_f32_32x32x16_bf16 v[0:15], v[224:227], v[202:205], v[0:15]
	s_waitcnt vmcnt(4) lgkmcnt(0)
	s_barrier
	v_add_u32_e32 v202, v199, v177
	v_add_u32_e32 v222, v200, v177
	v_mfma_f32_32x32x16_bf16 v[16:31], v[224:227], v[170:173], v[16:31]
	ds_read_b128 v[170:173], v202 offset:16384
	ds_read_b128 v[202:205], v202 offset:18432
	ds_read_b128 v[206:209], v222
	ds_read_b128 v[210:213], v222 offset:2048
	ds_read_b128 v[214:217], v222 offset:4096
	ds_read_b128 v[224:227], v222 offset:6144
	s_waitcnt lgkmcnt(9)
	v_mfma_f32_32x32x16_bf16 v[112:127], v[138:141], v[130:133], v[112:127]
	v_mfma_f32_32x32x16_bf16 v[96:111], v[138:141], v[134:137], v[96:111]
	s_waitcnt lgkmcnt(8)
	v_mfma_f32_32x32x16_bf16 v[80:95], v[142:145], v[130:133], v[80:95]
	v_mfma_f32_32x32x16_bf16 v[64:79], v[142:145], v[134:137], v[64:79]
	s_waitcnt lgkmcnt(7)
	v_mfma_f32_32x32x16_bf16 v[48:63], v[146:149], v[130:133], v[48:63]
	v_mfma_f32_32x32x16_bf16 v[32:47], v[146:149], v[134:137], v[32:47]
	s_waitcnt lgkmcnt(6)
	v_mfma_f32_32x32x16_bf16 v[16:31], v[150:153], v[130:133], v[16:31]
	v_mfma_f32_32x32x16_bf16 v[0:15], v[150:153], v[134:137], v[0:15]
	v_add_u32_e32 v134, v199, v178
	v_add_u32_e32 v150, v200, v178
	ds_read_b128 v[130:133], v134 offset:16384
	ds_read_b128 v[134:137], v134 offset:18432
	ds_read_b128 v[138:141], v150
	ds_read_b128 v[142:145], v150 offset:2048
	ds_read_b128 v[146:149], v150 offset:4096
	ds_read_b128 v[150:153], v150 offset:6144
	s_waitcnt lgkmcnt(9)
	v_mfma_f32_32x32x16_bf16 v[112:127], v[206:209], v[170:173], v[112:127]
	v_mfma_f32_32x32x16_bf16 v[96:111], v[206:209], v[202:205], v[96:111]
	s_waitcnt lgkmcnt(8)
	v_mfma_f32_32x32x16_bf16 v[80:95], v[210:213], v[170:173], v[80:95]
	v_mfma_f32_32x32x16_bf16 v[64:79], v[210:213], v[202:205], v[64:79]
	s_waitcnt lgkmcnt(7)
	v_mfma_f32_32x32x16_bf16 v[48:63], v[214:217], v[170:173], v[48:63]
	v_mfma_f32_32x32x16_bf16 v[32:47], v[214:217], v[202:205], v[32:47]
	s_waitcnt lgkmcnt(6)
	v_mfma_f32_32x32x16_bf16 v[0:15], v[224:227], v[202:205], v[0:15]
	s_waitcnt vmcnt(0) lgkmcnt(0)
	s_barrier
	v_add_u32_e32 v202, v197, v177
	v_add_u32_e32 v222, v198, v177
	v_mfma_f32_32x32x16_bf16 v[16:31], v[224:227], v[170:173], v[16:31]
	ds_read_b128 v[170:173], v202 offset:16384
	ds_read_b128 v[202:205], v202 offset:18432
	ds_read_b128 v[206:209], v222
	ds_read_b128 v[210:213], v222 offset:2048
	ds_read_b128 v[214:217], v222 offset:4096
	ds_read_b128 v[224:227], v222 offset:6144
	s_waitcnt lgkmcnt(9)
	v_mfma_f32_32x32x16_bf16 v[112:127], v[138:141], v[130:133], v[112:127]
	v_mfma_f32_32x32x16_bf16 v[96:111], v[138:141], v[134:137], v[96:111]
	s_waitcnt lgkmcnt(8)
	v_mfma_f32_32x32x16_bf16 v[80:95], v[142:145], v[130:133], v[80:95]
	v_mfma_f32_32x32x16_bf16 v[64:79], v[142:145], v[134:137], v[64:79]
	s_waitcnt lgkmcnt(7)
	v_mfma_f32_32x32x16_bf16 v[48:63], v[146:149], v[130:133], v[48:63]
	v_mfma_f32_32x32x16_bf16 v[32:47], v[146:149], v[134:137], v[32:47]
	s_waitcnt lgkmcnt(6)
	v_mfma_f32_32x32x16_bf16 v[16:31], v[150:153], v[130:133], v[16:31]
	v_mfma_f32_32x32x16_bf16 v[0:15], v[150:153], v[134:137], v[0:15]
	v_add_u32_e32 v134, v197, v178
	v_add_u32_e32 v150, v198, v178
	ds_read_b128 v[130:133], v134 offset:16384
	ds_read_b128 v[134:137], v134 offset:18432
	ds_read_b128 v[138:141], v150
	ds_read_b128 v[142:145], v150 offset:2048
	ds_read_b128 v[146:149], v150 offset:4096
	ds_read_b128 v[150:153], v150 offset:6144
	s_waitcnt lgkmcnt(9)
	v_mfma_f32_32x32x16_bf16 v[112:127], v[206:209], v[170:173], v[112:127]
	v_mfma_f32_32x32x16_bf16 v[96:111], v[206:209], v[202:205], v[96:111]
	s_waitcnt lgkmcnt(8)
	v_mfma_f32_32x32x16_bf16 v[80:95], v[210:213], v[170:173], v[80:95]
	v_mfma_f32_32x32x16_bf16 v[64:79], v[210:213], v[202:205], v[64:79]
	s_waitcnt lgkmcnt(7)
	v_mfma_f32_32x32x16_bf16 v[48:63], v[214:217], v[170:173], v[48:63]
	v_mfma_f32_32x32x16_bf16 v[32:47], v[214:217], v[202:205], v[32:47]
	s_waitcnt lgkmcnt(6)
	v_mfma_f32_32x32x16_bf16 v[16:31], v[224:227], v[170:173], v[16:31]
	v_mfma_f32_32x32x16_bf16 v[0:15], v[224:227], v[202:205], v[0:15]
	s_waitcnt lgkmcnt(3)
	v_mfma_f32_32x32x16_bf16 v[112:127], v[138:141], v[130:133], v[112:127]
	s_waitcnt lgkmcnt(2)
	v_mfma_f32_32x32x16_bf16 v[80:95], v[142:145], v[130:133], v[80:95]
	s_waitcnt lgkmcnt(1)
	v_mfma_f32_32x32x16_bf16 v[48:63], v[146:149], v[130:133], v[48:63]
	s_waitcnt lgkmcnt(0)
	v_mfma_f32_32x32x16_bf16 v[16:31], v[150:153], v[130:133], v[16:31]
	v_add_u32_e32 v132, s6, v174
	v_or_b32_e32 v130, s7, v128
	v_ashrrev_i32_e32 v131, 31, v130
	v_lshl_add_u64 v[130:131], v[130:131], 1, v[158:159]
	v_readlane_b32 s6, v252, 7
	s_add_i32 s4, s4, s6
	s_add_i32 s2, s2, s6
	v_mfma_f32_32x32x16_bf16 v[96:111], v[138:141], v[134:137], v[96:111]
	v_or_b32_e32 v138, v132, v181
	v_ashrrev_i32_e32 v139, 31, v138
	v_readlane_b32 s6, v252, 8
	s_add_i32 s5, s5, s6
	s_cmp_gt_i32 s4, 31
	v_mfma_f32_32x32x16_bf16 v[64:79], v[142:145], v[134:137], v[64:79]
	v_mfma_f32_32x32x16_bf16 v[32:47], v[146:149], v[134:137], v[32:47]
	v_mfma_f32_32x32x16_bf16 v[0:15], v[150:153], v[134:137], v[0:15]
	v_and_b32_e32 v134, 0xff, v138
	v_lshl_add_u32 v134, v134, 2, v250
	ds_read_b96 v[134:136], v134
	v_lshlrev_b64 v[138:139], 11, v[138:139]
	v_lshl_add_u64 v[138:139], v[130:131], 0, v[138:139]
	s_waitcnt lgkmcnt(0)
	v_mul_f32_e32 v112, v112, v134
	v_mul_f32_e32 v96, v96, v134
	v_cvt_pk_bf16_f32 v112, v112, s0
	v_cvt_pk_bf16_f32 v96, v96, s0
	global_store_short v[138:139], v112, off
	global_store_short v[138:139], v96, off offset:64
	v_or_b32_e32 v138, v132, v182
	v_ashrrev_i32_e32 v139, 31, v138
	v_lshlrev_b64 v[138:139], 11, v[138:139]
	v_mul_f32_e32 v96, v113, v135
	v_lshl_add_u64 v[138:139], v[130:131], 0, v[138:139]
	v_cvt_pk_bf16_f32 v96, v96, s0
	global_store_short v[138:139], v96, off
	v_mul_f32_e32 v96, v97, v135
	v_cvt_pk_bf16_f32 v96, v96, s0
	global_store_short v[138:139], v96, off offset:64
	v_or_b32_e32 v96, v132, v183
	v_ashrrev_i32_e32 v97, 31, v96
	v_lshlrev_b64 v[96:97], 11, v[96:97]
	v_mul_f32_e32 v112, v114, v136
	v_mul_f32_e32 v98, v98, v136
	v_lshl_add_u64 v[96:97], v[130:131], 0, v[96:97]
	v_cvt_pk_bf16_f32 v112, v112, s0
	v_cvt_pk_bf16_f32 v98, v98, s0
	global_store_short v[96:97], v112, off
	global_store_short v[96:97], v98, off offset:64
	v_or_b32_e32 v96, v132, v184
	v_ashrrev_i32_e32 v97, 31, v96
	v_and_b32_e32 v112, 0xff, v96
	v_lshl_add_u32 v112, v112, 2, v250
	ds_read_b32 v98, v112
	v_lshlrev_b64 v[96:97], 11, v[96:97]
	v_lshl_add_u64 v[96:97], v[130:131], 0, v[96:97]
	s_waitcnt lgkmcnt(0)
	v_mul_f32_e32 v112, v115, v98
	v_cvt_pk_bf16_f32 v112, v112, s0
	global_store_short v[96:97], v112, off
	v_mul_f32_e32 v98, v99, v98
	v_or_b32_e32 v112, v132, v185
	v_cvt_pk_bf16_f32 v98, v98, s0
	v_ashrrev_i32_e32 v113, 31, v112
	global_store_short v[96:97], v98, off offset:64
	v_and_b32_e32 v96, 0xff, v112
	v_lshl_add_u32 v96, v96, 2, v250
	ds_read_b96 v[96:98], v96
	v_lshlrev_b64 v[112:113], 11, v[112:113]
	v_lshl_add_u64 v[112:113], v[130:131], 0, v[112:113]
	s_waitcnt lgkmcnt(0)
	v_mul_f32_e32 v99, v116, v96
	v_mul_f32_e32 v96, v100, v96
	v_cvt_pk_bf16_f32 v99, v99, s0
	v_cvt_pk_bf16_f32 v96, v96, s0
	global_store_short v[112:113], v99, off
	global_store_short v[112:113], v96, off offset:64
	v_or_b32_e32 v112, v132, v186
	v_ashrrev_i32_e32 v113, 31, v112
	v_lshlrev_b64 v[112:113], 11, v[112:113]
	v_mul_f32_e32 v96, v117, v97
	v_lshl_add_u64 v[112:113], v[130:131], 0, v[112:113]
	v_cvt_pk_bf16_f32 v96, v96, s0
	global_store_short v[112:113], v96, off
	v_mul_f32_e32 v96, v101, v97
	v_cvt_pk_bf16_f32 v96, v96, s0
	global_store_short v[112:113], v96, off offset:64
	v_or_b32_e32 v96, v132, v187
	v_ashrrev_i32_e32 v97, 31, v96
	v_lshlrev_b64 v[96:97], 11, v[96:97]
	v_mul_f32_e32 v99, v118, v98
	v_mul_f32_e32 v98, v102, v98
	v_lshl_add_u64 v[96:97], v[130:131], 0, v[96:97]
	v_cvt_pk_bf16_f32 v99, v99, s0
	v_cvt_pk_bf16_f32 v98, v98, s0
	global_store_short v[96:97], v99, off
	global_store_short v[96:97], v98, off offset:64
	v_or_b32_e32 v96, v132, v188
	v_ashrrev_i32_e32 v97, 31, v96
	v_and_b32_e32 v98, 0xff, v96
	v_lshl_add_u32 v98, v98, 2, v250
	ds_read_b32 v98, v98
	v_lshlrev_b64 v[96:97], 11, v[96:97]
	v_or_b32_e32 v100, v132, v189
	v_lshl_add_u64 v[96:97], v[130:131], 0, v[96:97]
	v_ashrrev_i32_e32 v101, 31, v100
	s_waitcnt lgkmcnt(0)
	v_mul_f32_e32 v99, v119, v98
	v_mul_f32_e32 v98, v103, v98
	v_cvt_pk_bf16_f32 v99, v99, s0
	v_cvt_pk_bf16_f32 v98, v98, s0
	global_store_short v[96:97], v99, off
	global_store_short v[96:97], v98, off offset:64
	v_and_b32_e32 v96, 0xff, v100
	v_lshl_add_u32 v96, v96, 2, v250
	ds_read_b96 v[96:98], v96
	v_lshlrev_b64 v[100:101], 11, v[100:101]
	v_lshl_add_u64 v[100:101], v[130:131], 0, v[100:101]
	s_waitcnt lgkmcnt(0)
	v_mul_f32_e32 v99, v120, v96
	v_mul_f32_e32 v96, v104, v96
	v_cvt_pk_bf16_f32 v99, v99, s0
	v_cvt_pk_bf16_f32 v96, v96, s0
	global_store_short v[100:101], v99, off
	global_store_short v[100:101], v96, off offset:64
	v_or_b32_e32 v100, v132, v190
	v_ashrrev_i32_e32 v101, 31, v100
	v_lshlrev_b64 v[100:101], 11, v[100:101]
	v_mul_f32_e32 v96, v121, v97
	v_lshl_add_u64 v[100:101], v[130:131], 0, v[100:101]
	v_cvt_pk_bf16_f32 v96, v96, s0
	global_store_short v[100:101], v96, off
	v_mul_f32_e32 v96, v105, v97
	v_cvt_pk_bf16_f32 v96, v96, s0
	global_store_short v[100:101], v96, off offset:64
	v_or_b32_e32 v96, v132, v191
	v_ashrrev_i32_e32 v97, 31, v96
	v_lshlrev_b64 v[96:97], 11, v[96:97]
	v_mul_f32_e32 v99, v122, v98
	v_mul_f32_e32 v98, v106, v98
	v_lshl_add_u64 v[96:97], v[130:131], 0, v[96:97]
	v_cvt_pk_bf16_f32 v99, v99, s0
	v_cvt_pk_bf16_f32 v98, v98, s0
	global_store_short v[96:97], v99, off
	global_store_short v[96:97], v98, off offset:64
	v_or_b32_e32 v96, v132, v192
	v_ashrrev_i32_e32 v97, 31, v96
	v_and_b32_e32 v98, 0xff, v96
	v_lshl_add_u32 v98, v98, 2, v250
	ds_read_b32 v98, v98
	v_lshlrev_b64 v[96:97], 11, v[96:97]
	v_or_b32_e32 v100, v132, v193
	v_lshl_add_u64 v[96:97], v[130:131], 0, v[96:97]
	v_ashrrev_i32_e32 v101, 31, v100
	s_waitcnt lgkmcnt(0)
	v_mul_f32_e32 v99, v123, v98
	v_mul_f32_e32 v98, v107, v98
	v_cvt_pk_bf16_f32 v99, v99, s0
	v_cvt_pk_bf16_f32 v98, v98, s0
	global_store_short v[96:97], v99, off
	global_store_short v[96:97], v98, off offset:64
	v_and_b32_e32 v96, 0xff, v100
	v_lshl_add_u32 v96, v96, 2, v250
	ds_read_b96 v[96:98], v96
	v_lshlrev_b64 v[100:101], 11, v[100:101]
	v_lshl_add_u64 v[100:101], v[130:131], 0, v[100:101]
	s_waitcnt lgkmcnt(0)
	v_mul_f32_e32 v99, v124, v96
	v_mul_f32_e32 v96, v108, v96
	v_cvt_pk_bf16_f32 v99, v99, s0
	v_cvt_pk_bf16_f32 v96, v96, s0
	global_store_short v[100:101], v99, off
	global_store_short v[100:101], v96, off offset:64
	v_or_b32_e32 v100, v132, v194
	v_ashrrev_i32_e32 v101, 31, v100
	v_lshlrev_b64 v[100:101], 11, v[100:101]
	v_mul_f32_e32 v96, v125, v97
	v_lshl_add_u64 v[100:101], v[130:131], 0, v[100:101]
	v_cvt_pk_bf16_f32 v96, v96, s0
	global_store_short v[100:101], v96, off
	v_mul_f32_e32 v96, v109, v97
	v_cvt_pk_bf16_f32 v96, v96, s0
	global_store_short v[100:101], v96, off offset:64
	v_or_b32_e32 v96, v132, v195
	v_ashrrev_i32_e32 v97, 31, v96
	v_lshlrev_b64 v[96:97], 11, v[96:97]
	v_mul_f32_e32 v99, v126, v98
	v_mul_f32_e32 v98, v110, v98
	v_lshl_add_u64 v[96:97], v[130:131], 0, v[96:97]
	v_cvt_pk_bf16_f32 v99, v99, s0
	v_cvt_pk_bf16_f32 v98, v98, s0
	global_store_short v[96:97], v99, off
	global_store_short v[96:97], v98, off offset:64
	v_or_b32_e32 v96, v132, v196
	v_ashrrev_i32_e32 v97, 31, v96
	v_and_b32_e32 v98, 0xff, v96
	v_lshl_add_u32 v98, v98, 2, v250
	ds_read_b32 v98, v98
	v_lshlrev_b64 v[96:97], 11, v[96:97]
	v_lshl_add_u64 v[96:97], v[130:131], 0, v[96:97]
	s_waitcnt lgkmcnt(0)
	v_mul_f32_e32 v99, v127, v98
	v_mul_f32_e32 v98, v111, v98
	v_cvt_pk_bf16_f32 v99, v99, s0
	v_cvt_pk_bf16_f32 v98, v98, s0
	global_store_short v[96:97], v99, off
	global_store_short v[96:97], v98, off offset:64
	v_or_b32_e32 v96, 32, v132
	v_or_b32_e32 v102, v96, v181
	v_ashrrev_i32_e32 v103, 31, v102
	v_and_b32_e32 v98, 0xff, v102
	v_lshl_add_u32 v98, v98, 2, v250
	ds_read_b96 v[98:100], v98
	v_lshlrev_b64 v[102:103], 11, v[102:103]
	v_lshl_add_u64 v[102:103], v[130:131], 0, v[102:103]
	s_waitcnt lgkmcnt(0)
	v_mul_f32_e32 v80, v80, v98
	v_mul_f32_e32 v64, v64, v98
	v_cvt_pk_bf16_f32 v80, v80, s0
	v_cvt_pk_bf16_f32 v64, v64, s0
	global_store_short v[102:103], v80, off
	global_store_short v[102:103], v64, off offset:64
	v_or_b32_e32 v102, v96, v182
	v_ashrrev_i32_e32 v103, 31, v102
	v_lshlrev_b64 v[102:103], 11, v[102:103]
	v_mul_f32_e32 v64, v81, v99
	v_lshl_add_u64 v[102:103], v[130:131], 0, v[102:103]
	v_cvt_pk_bf16_f32 v64, v64, s0
	global_store_short v[102:103], v64, off
	v_mul_f32_e32 v64, v65, v99
	v_cvt_pk_bf16_f32 v64, v64, s0
	global_store_short v[102:103], v64, off offset:64
	v_or_b32_e32 v64, v96, v183
	v_ashrrev_i32_e32 v65, 31, v64
	v_lshlrev_b64 v[64:65], 11, v[64:65]
	v_mul_f32_e32 v80, v82, v100
	v_mul_f32_e32 v66, v66, v100
	v_lshl_add_u64 v[64:65], v[130:131], 0, v[64:65]
	v_cvt_pk_bf16_f32 v80, v80, s0
	v_cvt_pk_bf16_f32 v66, v66, s0
	global_store_short v[64:65], v80, off
	global_store_short v[64:65], v66, off offset:64
	v_or_b32_e32 v64, v96, v184
	v_ashrrev_i32_e32 v65, 31, v64
	v_and_b32_e32 v80, 0xff, v64
	v_lshl_add_u32 v80, v80, 2, v250
	ds_read_b32 v66, v80
	v_lshlrev_b64 v[64:65], 11, v[64:65]
	v_lshl_add_u64 v[64:65], v[130:131], 0, v[64:65]
	s_waitcnt lgkmcnt(0)
	v_mul_f32_e32 v80, v83, v66
	v_cvt_pk_bf16_f32 v80, v80, s0
	global_store_short v[64:65], v80, off
	v_mul_f32_e32 v66, v67, v66
	v_or_b32_e32 v80, v96, v185
	v_cvt_pk_bf16_f32 v66, v66, s0
	v_ashrrev_i32_e32 v81, 31, v80
	global_store_short v[64:65], v66, off offset:64
	v_and_b32_e32 v64, 0xff, v80
	v_lshl_add_u32 v64, v64, 2, v250
	ds_read_b96 v[64:66], v64
	v_lshlrev_b64 v[80:81], 11, v[80:81]
	v_lshl_add_u64 v[80:81], v[130:131], 0, v[80:81]
	s_waitcnt lgkmcnt(0)
	v_mul_f32_e32 v67, v84, v64
	v_mul_f32_e32 v64, v68, v64
	v_cvt_pk_bf16_f32 v67, v67, s0
	v_cvt_pk_bf16_f32 v64, v64, s0
	global_store_short v[80:81], v67, off
	global_store_short v[80:81], v64, off offset:64
	v_or_b32_e32 v80, v96, v186
	v_ashrrev_i32_e32 v81, 31, v80
	v_lshlrev_b64 v[80:81], 11, v[80:81]
	v_mul_f32_e32 v64, v85, v65
	v_lshl_add_u64 v[80:81], v[130:131], 0, v[80:81]
	v_cvt_pk_bf16_f32 v64, v64, s0
	global_store_short v[80:81], v64, off
	v_mul_f32_e32 v64, v69, v65
	v_cvt_pk_bf16_f32 v64, v64, s0
	global_store_short v[80:81], v64, off offset:64
	v_or_b32_e32 v64, v96, v187
	v_ashrrev_i32_e32 v65, 31, v64
	v_lshlrev_b64 v[64:65], 11, v[64:65]
	v_mul_f32_e32 v67, v86, v66
	v_mul_f32_e32 v66, v70, v66
	v_lshl_add_u64 v[64:65], v[130:131], 0, v[64:65]
	v_cvt_pk_bf16_f32 v67, v67, s0
	v_cvt_pk_bf16_f32 v66, v66, s0
	global_store_short v[64:65], v67, off
	global_store_short v[64:65], v66, off offset:64
	v_or_b32_e32 v64, v96, v188
	v_ashrrev_i32_e32 v65, 31, v64
	v_and_b32_e32 v66, 0xff, v64
	v_lshl_add_u32 v66, v66, 2, v250
	ds_read_b32 v66, v66
	v_lshlrev_b64 v[64:65], 11, v[64:65]
	v_or_b32_e32 v68, v96, v189
	v_lshl_add_u64 v[64:65], v[130:131], 0, v[64:65]
	v_ashrrev_i32_e32 v69, 31, v68
	s_waitcnt lgkmcnt(0)
	v_mul_f32_e32 v67, v87, v66
	v_mul_f32_e32 v66, v71, v66
	v_cvt_pk_bf16_f32 v67, v67, s0
	v_cvt_pk_bf16_f32 v66, v66, s0
	global_store_short v[64:65], v67, off
	global_store_short v[64:65], v66, off offset:64
	v_and_b32_e32 v64, 0xff, v68
	v_lshl_add_u32 v64, v64, 2, v250
	ds_read_b96 v[64:66], v64
	v_lshlrev_b64 v[68:69], 11, v[68:69]
	v_lshl_add_u64 v[68:69], v[130:131], 0, v[68:69]
	s_waitcnt lgkmcnt(0)
	v_mul_f32_e32 v67, v88, v64
	v_mul_f32_e32 v64, v72, v64
	v_cvt_pk_bf16_f32 v67, v67, s0
	v_cvt_pk_bf16_f32 v64, v64, s0
	global_store_short v[68:69], v67, off
	global_store_short v[68:69], v64, off offset:64
	v_or_b32_e32 v68, v96, v190
	v_ashrrev_i32_e32 v69, 31, v68
	v_lshlrev_b64 v[68:69], 11, v[68:69]
	v_mul_f32_e32 v64, v89, v65
	v_lshl_add_u64 v[68:69], v[130:131], 0, v[68:69]
	v_cvt_pk_bf16_f32 v64, v64, s0
	global_store_short v[68:69], v64, off
	v_mul_f32_e32 v64, v73, v65
	v_cvt_pk_bf16_f32 v64, v64, s0
	global_store_short v[68:69], v64, off offset:64
	v_or_b32_e32 v64, v96, v191
	v_ashrrev_i32_e32 v65, 31, v64
	v_lshlrev_b64 v[64:65], 11, v[64:65]
	v_mul_f32_e32 v67, v90, v66
	v_mul_f32_e32 v66, v74, v66
	v_lshl_add_u64 v[64:65], v[130:131], 0, v[64:65]
	v_cvt_pk_bf16_f32 v67, v67, s0
	v_cvt_pk_bf16_f32 v66, v66, s0
	global_store_short v[64:65], v67, off
	global_store_short v[64:65], v66, off offset:64
	v_or_b32_e32 v64, v96, v192
	v_ashrrev_i32_e32 v65, 31, v64
	v_and_b32_e32 v66, 0xff, v64
	v_lshl_add_u32 v66, v66, 2, v250
	ds_read_b32 v66, v66
	v_lshlrev_b64 v[64:65], 11, v[64:65]
	v_or_b32_e32 v68, v96, v193
	v_lshl_add_u64 v[64:65], v[130:131], 0, v[64:65]
	v_ashrrev_i32_e32 v69, 31, v68
	s_waitcnt lgkmcnt(0)
	v_mul_f32_e32 v67, v91, v66
	v_mul_f32_e32 v66, v75, v66
	v_cvt_pk_bf16_f32 v67, v67, s0
	v_cvt_pk_bf16_f32 v66, v66, s0
	global_store_short v[64:65], v67, off
	global_store_short v[64:65], v66, off offset:64
	v_and_b32_e32 v64, 0xff, v68
	v_lshl_add_u32 v64, v64, 2, v250
	ds_read_b96 v[64:66], v64
	v_lshlrev_b64 v[68:69], 11, v[68:69]
	v_lshl_add_u64 v[68:69], v[130:131], 0, v[68:69]
	s_waitcnt lgkmcnt(0)
	v_mul_f32_e32 v67, v92, v64
	v_mul_f32_e32 v64, v76, v64
	v_cvt_pk_bf16_f32 v67, v67, s0
	v_cvt_pk_bf16_f32 v64, v64, s0
	global_store_short v[68:69], v67, off
	global_store_short v[68:69], v64, off offset:64
	v_or_b32_e32 v68, v96, v194
	v_ashrrev_i32_e32 v69, 31, v68
	v_lshlrev_b64 v[68:69], 11, v[68:69]
	v_mul_f32_e32 v64, v93, v65
	v_lshl_add_u64 v[68:69], v[130:131], 0, v[68:69]
	v_cvt_pk_bf16_f32 v64, v64, s0
	global_store_short v[68:69], v64, off
	v_mul_f32_e32 v64, v77, v65
	v_cvt_pk_bf16_f32 v64, v64, s0
	global_store_short v[68:69], v64, off offset:64
	v_or_b32_e32 v64, v96, v195
	v_ashrrev_i32_e32 v65, 31, v64
	v_lshlrev_b64 v[64:65], 11, v[64:65]
	v_mul_f32_e32 v67, v94, v66
	v_mul_f32_e32 v66, v78, v66
	v_lshl_add_u64 v[64:65], v[130:131], 0, v[64:65]
	v_cvt_pk_bf16_f32 v67, v67, s0
	v_cvt_pk_bf16_f32 v66, v66, s0
	global_store_short v[64:65], v67, off
	global_store_short v[64:65], v66, off offset:64
	v_or_b32_e32 v64, v96, v196
	v_ashrrev_i32_e32 v65, 31, v64
	v_and_b32_e32 v66, 0xff, v64
	v_lshl_add_u32 v66, v66, 2, v250
	ds_read_b32 v66, v66
	v_lshlrev_b64 v[64:65], 11, v[64:65]
	v_lshl_add_u64 v[64:65], v[130:131], 0, v[64:65]
	s_waitcnt lgkmcnt(0)
	v_mul_f32_e32 v67, v95, v66
	v_mul_f32_e32 v66, v79, v66
	v_cvt_pk_bf16_f32 v67, v67, s0
	v_cvt_pk_bf16_f32 v66, v66, s0
	global_store_short v[64:65], v67, off
	global_store_short v[64:65], v66, off offset:64
	v_or_b32_e32 v64, 64, v132
	v_or_b32_e32 v70, v64, v181
	v_ashrrev_i32_e32 v71, 31, v70
	v_and_b32_e32 v66, 0xff, v70
	v_lshl_add_u32 v66, v66, 2, v250
	ds_read_b96 v[66:68], v66
	v_lshlrev_b64 v[70:71], 11, v[70:71]
	v_lshl_add_u64 v[70:71], v[130:131], 0, v[70:71]
	s_waitcnt lgkmcnt(0)
	v_mul_f32_e32 v48, v48, v66
	v_mul_f32_e32 v32, v32, v66
	v_cvt_pk_bf16_f32 v48, v48, s0
	v_cvt_pk_bf16_f32 v32, v32, s0
	global_store_short v[70:71], v48, off
	global_store_short v[70:71], v32, off offset:64
	v_or_b32_e32 v70, v64, v182
	v_ashrrev_i32_e32 v71, 31, v70
	v_lshlrev_b64 v[70:71], 11, v[70:71]
	v_mul_f32_e32 v32, v49, v67
	v_lshl_add_u64 v[70:71], v[130:131], 0, v[70:71]
	v_cvt_pk_bf16_f32 v32, v32, s0
	global_store_short v[70:71], v32, off
	v_mul_f32_e32 v32, v33, v67
	v_cvt_pk_bf16_f32 v32, v32, s0
	global_store_short v[70:71], v32, off offset:64
	v_or_b32_e32 v32, v64, v183
	v_ashrrev_i32_e32 v33, 31, v32
	v_lshlrev_b64 v[32:33], 11, v[32:33]
	v_mul_f32_e32 v48, v50, v68
	v_mul_f32_e32 v34, v34, v68
	v_lshl_add_u64 v[32:33], v[130:131], 0, v[32:33]
	v_cvt_pk_bf16_f32 v48, v48, s0
	v_cvt_pk_bf16_f32 v34, v34, s0
	global_store_short v[32:33], v48, off
	global_store_short v[32:33], v34, off offset:64
	v_or_b32_e32 v32, v64, v184
	v_ashrrev_i32_e32 v33, 31, v32
	v_and_b32_e32 v48, 0xff, v32
	v_lshl_add_u32 v48, v48, 2, v250
	ds_read_b32 v34, v48
	v_lshlrev_b64 v[32:33], 11, v[32:33]
	v_lshl_add_u64 v[32:33], v[130:131], 0, v[32:33]
	s_waitcnt lgkmcnt(0)
	v_mul_f32_e32 v48, v51, v34
	v_cvt_pk_bf16_f32 v48, v48, s0
	global_store_short v[32:33], v48, off
	v_mul_f32_e32 v34, v35, v34
	v_or_b32_e32 v48, v64, v185
	v_cvt_pk_bf16_f32 v34, v34, s0
	v_ashrrev_i32_e32 v49, 31, v48
	global_store_short v[32:33], v34, off offset:64
	v_and_b32_e32 v32, 0xff, v48
	v_lshl_add_u32 v32, v32, 2, v250
	ds_read_b96 v[32:34], v32
	v_lshlrev_b64 v[48:49], 11, v[48:49]
	v_lshl_add_u64 v[48:49], v[130:131], 0, v[48:49]
	s_waitcnt lgkmcnt(0)
	v_mul_f32_e32 v35, v52, v32
	v_mul_f32_e32 v32, v36, v32
	v_cvt_pk_bf16_f32 v35, v35, s0
	v_cvt_pk_bf16_f32 v32, v32, s0
	global_store_short v[48:49], v35, off
	global_store_short v[48:49], v32, off offset:64
	v_or_b32_e32 v48, v64, v186
	v_ashrrev_i32_e32 v49, 31, v48
	v_lshlrev_b64 v[48:49], 11, v[48:49]
	v_mul_f32_e32 v32, v53, v33
	v_lshl_add_u64 v[48:49], v[130:131], 0, v[48:49]
	v_cvt_pk_bf16_f32 v32, v32, s0
	global_store_short v[48:49], v32, off
	v_mul_f32_e32 v32, v37, v33
	v_cvt_pk_bf16_f32 v32, v32, s0
	global_store_short v[48:49], v32, off offset:64
	v_or_b32_e32 v32, v64, v187
	v_ashrrev_i32_e32 v33, 31, v32
	v_lshlrev_b64 v[32:33], 11, v[32:33]
	v_mul_f32_e32 v35, v54, v34
	v_mul_f32_e32 v34, v38, v34
	v_lshl_add_u64 v[32:33], v[130:131], 0, v[32:33]
	v_cvt_pk_bf16_f32 v35, v35, s0
	v_cvt_pk_bf16_f32 v34, v34, s0
	global_store_short v[32:33], v35, off
	global_store_short v[32:33], v34, off offset:64
	v_or_b32_e32 v32, v64, v188
	v_ashrrev_i32_e32 v33, 31, v32
	v_and_b32_e32 v34, 0xff, v32
	v_lshl_add_u32 v34, v34, 2, v250
	ds_read_b32 v34, v34
	v_lshlrev_b64 v[32:33], 11, v[32:33]
	v_or_b32_e32 v36, v64, v189
	v_lshl_add_u64 v[32:33], v[130:131], 0, v[32:33]
	v_ashrrev_i32_e32 v37, 31, v36
	s_waitcnt lgkmcnt(0)
	v_mul_f32_e32 v35, v55, v34
	v_mul_f32_e32 v34, v39, v34
	v_cvt_pk_bf16_f32 v35, v35, s0
	v_cvt_pk_bf16_f32 v34, v34, s0
	global_store_short v[32:33], v35, off
	global_store_short v[32:33], v34, off offset:64
	v_and_b32_e32 v32, 0xff, v36
	v_lshl_add_u32 v32, v32, 2, v250
	ds_read_b96 v[32:34], v32
	v_lshlrev_b64 v[36:37], 11, v[36:37]
	v_lshl_add_u64 v[36:37], v[130:131], 0, v[36:37]
	s_waitcnt lgkmcnt(0)
	v_mul_f32_e32 v35, v56, v32
	v_mul_f32_e32 v32, v40, v32
	v_cvt_pk_bf16_f32 v35, v35, s0
	v_cvt_pk_bf16_f32 v32, v32, s0
	global_store_short v[36:37], v35, off
	global_store_short v[36:37], v32, off offset:64
	v_or_b32_e32 v36, v64, v190
	v_ashrrev_i32_e32 v37, 31, v36
	v_lshlrev_b64 v[36:37], 11, v[36:37]
	v_mul_f32_e32 v32, v57, v33
	v_lshl_add_u64 v[36:37], v[130:131], 0, v[36:37]
	v_cvt_pk_bf16_f32 v32, v32, s0
	global_store_short v[36:37], v32, off
	v_mul_f32_e32 v32, v41, v33
	v_cvt_pk_bf16_f32 v32, v32, s0
	global_store_short v[36:37], v32, off offset:64
	v_or_b32_e32 v32, v64, v191
	v_ashrrev_i32_e32 v33, 31, v32
	v_lshlrev_b64 v[32:33], 11, v[32:33]
	v_mul_f32_e32 v35, v58, v34
	v_mul_f32_e32 v34, v42, v34
	v_lshl_add_u64 v[32:33], v[130:131], 0, v[32:33]
	v_cvt_pk_bf16_f32 v35, v35, s0
	v_cvt_pk_bf16_f32 v34, v34, s0
	global_store_short v[32:33], v35, off
	global_store_short v[32:33], v34, off offset:64
	v_or_b32_e32 v32, v64, v192
	v_ashrrev_i32_e32 v33, 31, v32
	v_and_b32_e32 v34, 0xff, v32
	v_lshl_add_u32 v34, v34, 2, v250
	ds_read_b32 v34, v34
	v_lshlrev_b64 v[32:33], 11, v[32:33]
	v_or_b32_e32 v36, v64, v193
	v_lshl_add_u64 v[32:33], v[130:131], 0, v[32:33]
	v_ashrrev_i32_e32 v37, 31, v36
	s_waitcnt lgkmcnt(0)
	v_mul_f32_e32 v35, v59, v34
	v_mul_f32_e32 v34, v43, v34
	v_cvt_pk_bf16_f32 v35, v35, s0
	v_cvt_pk_bf16_f32 v34, v34, s0
	global_store_short v[32:33], v35, off
	global_store_short v[32:33], v34, off offset:64
	v_and_b32_e32 v32, 0xff, v36
	v_lshl_add_u32 v32, v32, 2, v250
	ds_read_b96 v[32:34], v32
	v_lshlrev_b64 v[36:37], 11, v[36:37]
	v_lshl_add_u64 v[36:37], v[130:131], 0, v[36:37]
	s_waitcnt lgkmcnt(0)
	v_mul_f32_e32 v35, v60, v32
	v_mul_f32_e32 v32, v44, v32
	v_cvt_pk_bf16_f32 v35, v35, s0
	v_cvt_pk_bf16_f32 v32, v32, s0
	global_store_short v[36:37], v35, off
	global_store_short v[36:37], v32, off offset:64
	v_or_b32_e32 v36, v64, v194
	v_ashrrev_i32_e32 v37, 31, v36
	v_lshlrev_b64 v[36:37], 11, v[36:37]
	v_mul_f32_e32 v32, v61, v33
	v_lshl_add_u64 v[36:37], v[130:131], 0, v[36:37]
	v_cvt_pk_bf16_f32 v32, v32, s0
	global_store_short v[36:37], v32, off
	v_mul_f32_e32 v32, v45, v33
	v_cvt_pk_bf16_f32 v32, v32, s0
	global_store_short v[36:37], v32, off offset:64
	v_or_b32_e32 v32, v64, v195
	v_ashrrev_i32_e32 v33, 31, v32
	v_lshlrev_b64 v[32:33], 11, v[32:33]
	v_mul_f32_e32 v35, v62, v34
	v_mul_f32_e32 v34, v46, v34
	v_lshl_add_u64 v[32:33], v[130:131], 0, v[32:33]
	v_cvt_pk_bf16_f32 v35, v35, s0
	v_cvt_pk_bf16_f32 v34, v34, s0
	global_store_short v[32:33], v35, off
	global_store_short v[32:33], v34, off offset:64
	v_or_b32_e32 v32, v64, v196
	v_ashrrev_i32_e32 v33, 31, v32
	v_and_b32_e32 v34, 0xff, v32
	v_lshl_add_u32 v34, v34, 2, v250
	ds_read_b32 v34, v34
	v_lshlrev_b64 v[32:33], 11, v[32:33]
	v_lshl_add_u64 v[32:33], v[130:131], 0, v[32:33]
	s_waitcnt lgkmcnt(0)
	v_mul_f32_e32 v35, v63, v34
	v_mul_f32_e32 v34, v47, v34
	v_cvt_pk_bf16_f32 v35, v35, s0
	v_cvt_pk_bf16_f32 v34, v34, s0
	global_store_short v[32:33], v35, off
	global_store_short v[32:33], v34, off offset:64
	v_or_b32_e32 v32, 0x60, v132
	v_or_b32_e32 v38, v32, v181
	v_ashrrev_i32_e32 v39, 31, v38
	v_and_b32_e32 v34, 0xff, v38
	v_lshl_add_u32 v34, v34, 2, v250
	ds_read_b96 v[34:36], v34
	v_lshlrev_b64 v[38:39], 11, v[38:39]
	v_lshl_add_u64 v[38:39], v[130:131], 0, v[38:39]
	s_waitcnt lgkmcnt(0)
	v_mul_f32_e32 v16, v16, v34
	v_mul_f32_e32 v0, v0, v34
	v_cvt_pk_bf16_f32 v16, v16, s0
	v_cvt_pk_bf16_f32 v0, v0, s0
	global_store_short v[38:39], v16, off
	global_store_short v[38:39], v0, off offset:64
	v_or_b32_e32 v38, v32, v182
	v_ashrrev_i32_e32 v39, 31, v38
	v_lshlrev_b64 v[38:39], 11, v[38:39]
	v_mul_f32_e32 v0, v17, v35
	v_lshl_add_u64 v[38:39], v[130:131], 0, v[38:39]
	v_cvt_pk_bf16_f32 v0, v0, s0
	global_store_short v[38:39], v0, off
	v_mul_f32_e32 v0, v1, v35
	v_cvt_pk_bf16_f32 v0, v0, s0
	global_store_short v[38:39], v0, off offset:64
	v_or_b32_e32 v0, v32, v183
	v_ashrrev_i32_e32 v1, 31, v0
	v_lshlrev_b64 v[0:1], 11, v[0:1]
	v_mul_f32_e32 v16, v18, v36
	v_mul_f32_e32 v2, v2, v36
	v_lshl_add_u64 v[0:1], v[130:131], 0, v[0:1]
	v_cvt_pk_bf16_f32 v16, v16, s0
	v_cvt_pk_bf16_f32 v2, v2, s0
	global_store_short v[0:1], v16, off
	global_store_short v[0:1], v2, off offset:64
	v_or_b32_e32 v0, v32, v184
	v_ashrrev_i32_e32 v1, 31, v0
	v_and_b32_e32 v16, 0xff, v0
	v_lshl_add_u32 v16, v16, 2, v250
	ds_read_b32 v2, v16
	v_lshlrev_b64 v[0:1], 11, v[0:1]
	v_lshl_add_u64 v[0:1], v[130:131], 0, v[0:1]
	s_waitcnt lgkmcnt(0)
	v_mul_f32_e32 v16, v19, v2
	v_cvt_pk_bf16_f32 v16, v16, s0
	global_store_short v[0:1], v16, off
	v_mul_f32_e32 v2, v3, v2
	v_or_b32_e32 v16, v32, v185
	v_cvt_pk_bf16_f32 v2, v2, s0
	v_ashrrev_i32_e32 v17, 31, v16
	global_store_short v[0:1], v2, off offset:64
	v_and_b32_e32 v0, 0xff, v16
	v_lshl_add_u32 v0, v0, 2, v250
	ds_read_b96 v[0:2], v0
	v_lshlrev_b64 v[16:17], 11, v[16:17]
	v_lshl_add_u64 v[16:17], v[130:131], 0, v[16:17]
	s_waitcnt lgkmcnt(0)
	v_mul_f32_e32 v3, v20, v0
	v_mul_f32_e32 v0, v4, v0
	v_cvt_pk_bf16_f32 v3, v3, s0
	v_cvt_pk_bf16_f32 v0, v0, s0
	global_store_short v[16:17], v3, off
	global_store_short v[16:17], v0, off offset:64
	v_or_b32_e32 v16, v32, v186
	v_ashrrev_i32_e32 v17, 31, v16
	v_lshlrev_b64 v[16:17], 11, v[16:17]
	v_mul_f32_e32 v0, v21, v1
	v_lshl_add_u64 v[16:17], v[130:131], 0, v[16:17]
	v_cvt_pk_bf16_f32 v0, v0, s0
	global_store_short v[16:17], v0, off
	v_mul_f32_e32 v0, v5, v1
	v_cvt_pk_bf16_f32 v0, v0, s0
	global_store_short v[16:17], v0, off offset:64
	v_or_b32_e32 v0, v32, v187
	v_ashrrev_i32_e32 v1, 31, v0
	v_lshlrev_b64 v[0:1], 11, v[0:1]
	v_mul_f32_e32 v3, v22, v2
	v_mul_f32_e32 v2, v6, v2
	v_lshl_add_u64 v[0:1], v[130:131], 0, v[0:1]
	v_cvt_pk_bf16_f32 v3, v3, s0
	v_cvt_pk_bf16_f32 v2, v2, s0
	global_store_short v[0:1], v3, off
	global_store_short v[0:1], v2, off offset:64
	v_or_b32_e32 v0, v32, v188
	v_ashrrev_i32_e32 v1, 31, v0
	v_and_b32_e32 v2, 0xff, v0
	v_lshl_add_u32 v2, v2, 2, v250
	ds_read_b32 v2, v2
	v_lshlrev_b64 v[0:1], 11, v[0:1]
	v_or_b32_e32 v4, v32, v189
	v_lshl_add_u64 v[0:1], v[130:131], 0, v[0:1]
	v_ashrrev_i32_e32 v5, 31, v4
	s_waitcnt lgkmcnt(0)
	v_mul_f32_e32 v3, v23, v2
	v_mul_f32_e32 v2, v7, v2
	v_cvt_pk_bf16_f32 v3, v3, s0
	v_cvt_pk_bf16_f32 v2, v2, s0
	global_store_short v[0:1], v3, off
	global_store_short v[0:1], v2, off offset:64
	v_and_b32_e32 v0, 0xff, v4
	v_lshl_add_u32 v0, v0, 2, v250
	ds_read_b96 v[0:2], v0
	v_lshlrev_b64 v[4:5], 11, v[4:5]
	v_lshl_add_u64 v[4:5], v[130:131], 0, v[4:5]
	s_waitcnt lgkmcnt(0)
	v_mul_f32_e32 v3, v24, v0
	v_mul_f32_e32 v0, v8, v0
	v_cvt_pk_bf16_f32 v3, v3, s0
	v_cvt_pk_bf16_f32 v0, v0, s0
	global_store_short v[4:5], v3, off
	global_store_short v[4:5], v0, off offset:64
	v_or_b32_e32 v4, v32, v190
	v_ashrrev_i32_e32 v5, 31, v4
	v_lshlrev_b64 v[4:5], 11, v[4:5]
	v_mul_f32_e32 v0, v25, v1
	v_lshl_add_u64 v[4:5], v[130:131], 0, v[4:5]
	v_cvt_pk_bf16_f32 v0, v0, s0
	global_store_short v[4:5], v0, off
	v_mul_f32_e32 v0, v9, v1
	v_cvt_pk_bf16_f32 v0, v0, s0
	global_store_short v[4:5], v0, off offset:64
	v_or_b32_e32 v0, v32, v191
	v_ashrrev_i32_e32 v1, 31, v0
	v_lshlrev_b64 v[0:1], 11, v[0:1]
	v_mul_f32_e32 v3, v26, v2
	v_mul_f32_e32 v2, v10, v2
	v_lshl_add_u64 v[0:1], v[130:131], 0, v[0:1]
	v_cvt_pk_bf16_f32 v3, v3, s0
	v_cvt_pk_bf16_f32 v2, v2, s0
	global_store_short v[0:1], v3, off
	global_store_short v[0:1], v2, off offset:64
	v_or_b32_e32 v0, v32, v192
	v_ashrrev_i32_e32 v1, 31, v0
	v_and_b32_e32 v2, 0xff, v0
	v_lshl_add_u32 v2, v2, 2, v250
	ds_read_b32 v2, v2
	v_lshlrev_b64 v[0:1], 11, v[0:1]
	v_or_b32_e32 v4, v32, v193
	v_lshl_add_u64 v[0:1], v[130:131], 0, v[0:1]
	v_ashrrev_i32_e32 v5, 31, v4
	s_waitcnt lgkmcnt(0)
	v_mul_f32_e32 v3, v27, v2
	v_mul_f32_e32 v2, v11, v2
	v_cvt_pk_bf16_f32 v3, v3, s0
	v_cvt_pk_bf16_f32 v2, v2, s0
	global_store_short v[0:1], v3, off
	global_store_short v[0:1], v2, off offset:64
	v_and_b32_e32 v0, 0xff, v4
	v_lshl_add_u32 v0, v0, 2, v250
	ds_read_b96 v[0:2], v0
	v_lshlrev_b64 v[4:5], 11, v[4:5]
	v_lshl_add_u64 v[4:5], v[130:131], 0, v[4:5]
	s_waitcnt lgkmcnt(0)
	v_mul_f32_e32 v3, v28, v0
	v_mul_f32_e32 v0, v12, v0
	v_cvt_pk_bf16_f32 v3, v3, s0
	v_cvt_pk_bf16_f32 v0, v0, s0
	global_store_short v[4:5], v3, off
	global_store_short v[4:5], v0, off offset:64
	v_or_b32_e32 v4, v32, v194
	v_ashrrev_i32_e32 v5, 31, v4
	v_lshlrev_b64 v[4:5], 11, v[4:5]
	v_mul_f32_e32 v0, v29, v1
	v_lshl_add_u64 v[4:5], v[130:131], 0, v[4:5]
	v_cvt_pk_bf16_f32 v0, v0, s0
	global_store_short v[4:5], v0, off
	v_mul_f32_e32 v0, v13, v1
	v_cvt_pk_bf16_f32 v0, v0, s0
	global_store_short v[4:5], v0, off offset:64
	v_or_b32_e32 v0, v32, v195
	v_ashrrev_i32_e32 v1, 31, v0
	v_lshlrev_b64 v[0:1], 11, v[0:1]
	v_mul_f32_e32 v3, v30, v2
	v_mul_f32_e32 v2, v14, v2
	v_lshl_add_u64 v[0:1], v[130:131], 0, v[0:1]
	v_cvt_pk_bf16_f32 v3, v3, s0
	v_cvt_pk_bf16_f32 v2, v2, s0
	global_store_short v[0:1], v3, off
	global_store_short v[0:1], v2, off offset:64
	v_or_b32_e32 v0, v32, v196
	v_ashrrev_i32_e32 v1, 31, v0
	v_and_b32_e32 v2, 0xff, v0
	v_lshl_add_u32 v2, v2, 2, v250
	ds_read_b32 v2, v2
	v_lshlrev_b64 v[0:1], 11, v[0:1]
	v_lshl_add_u64 v[0:1], v[130:131], 0, v[0:1]
	s_waitcnt lgkmcnt(0)
	v_mul_f32_e32 v3, v31, v2
	v_mul_f32_e32 v2, v15, v2
	v_cvt_pk_bf16_f32 v3, v3, s0
	v_cvt_pk_bf16_f32 v2, v2, s0
	global_store_short v[0:1], v3, off
	global_store_short v[0:1], v2, off offset:64
	s_cbranch_scc0 .LBB0_2225
